# peephole: every wave-sum tail (v_mov 0 + v_mov_b32_dpp row_bcast + v_add) folded into one v_add_f32_dpp row_bcast with row_mask; DPP/readlane wait states re-derived
# baseline (speedup 1.0000x reference)
; __device__ __forceinline__ unsigned cvt_pk_bf16(float lo, float hi) { unsigned r; asm volatile("s_nop 0\n\tv_cvt_pk_bf16_f32 %0, %1, %2" : "=v"(r) : "v"(lo), "v"(hi)); return r; }
; __device__ __forceinline__ void phase_norm0_sw(KP P, unsigned char* shm) {
;     ...
;             for (int rr = 0; rr < 2; ++rr) { const int row = rowb + rr * nw; if (row < NTOK) {
;                 const float* scp = modall + (size_t)(row >> 11) * 9216 + 1024;
;                 float ss = 0.f;
; #pragma unroll
;                 for (int i = 0; i < 4; ++i) ss += v[rr][i][0] * v[rr][i][0] + v[rr][i][1] * v[rr][i][1] + v[rr][i][2] * v[rr][i][2] + v[rr][i][3] * v[rr][i][3];
;                 ss = wave_sum(ss);
;                 if (lane == 0) ss0[row] = ss;
; #pragma unroll
;                 for (int i = 0; i < 4; ++i) { const int c = 4 * (lane + 64 * i);
;                     const f32x4 y = v[rr][i] * wv[i] * (*(const f32x4*)(scp + c) + 1.f);
;                     uint2 st; st.x = cvt_pk_bf16(y[0], y[1]); st.y = cvt_pk_bf16(y[2], y[3]);
;                     *(uint2*)(U + (size_t)row * DM + c) = st; } } }
.LBB0_1828:
	s_or_b64 exec, exec, s[6:7]
	s_waitcnt vmcnt(3)
	v_mul_f32_e32 v51, v45, v45
	s_waitcnt vmcnt(2)
	v_mul_f32_e32 v53, v41, v41
	v_fmac_f32_e32 v51, v44, v44
	v_fmac_f32_e32 v53, v40, v40
	v_fmac_f32_e32 v51, v46, v46
	v_fmac_f32_e32 v53, v42, v42
	v_fmac_f32_e32 v51, v47, v47
	v_fmac_f32_e32 v53, v43, v43
	v_add_f32_e32 v51, v51, v53
	s_waitcnt vmcnt(1)
	v_mul_f32_e32 v53, v37, v37
	v_fmac_f32_e32 v53, v36, v36
	v_fmac_f32_e32 v53, v38, v38
	v_fmac_f32_e32 v53, v39, v39
	v_add_f32_e32 v51, v51, v53
	s_waitcnt vmcnt(0)
	v_mul_f32_e32 v53, v33, v33
	v_fmac_f32_e32 v53, v32, v32
	v_fmac_f32_e32 v53, v34, v34
	v_fmac_f32_e32 v53, v35, v35
	v_add_f32_e32 v51, v51, v53
	s_nop 0
	s_nop 0
	v_add_f32_dpp v51, v51, v51 quad_perm:[1,0,3,2] row_mask:0xf bank_mask:0xf bound_ctrl:1
	s_nop 1
	v_add_f32_dpp v51, v51, v51 quad_perm:[2,3,0,1] row_mask:0xf bank_mask:0xf bound_ctrl:1
	s_nop 1
	v_add_f32_dpp v51, v51, v51 row_half_mirror row_mask:0xf bank_mask:0xf bound_ctrl:1
	s_nop 1
	v_add_f32_dpp v51, v51, v51 row_mirror row_mask:0xf bank_mask:0xf bound_ctrl:1
	s_nop 1
	v_add_f32_dpp v51, v51, v51 row_bcast:15 row_mask:0xa bank_mask:0xf
	s_nop 1
	v_add_f32_dpp v51, v51, v51 row_bcast:31 row_mask:0xc bank_mask:0xf
	s_nop 0
	v_readlane_b32 s28, v51, 63
	s_and_saveexec_b64 s[6:7], vcc
	s_cbranch_execz .LBB0_1830
	v_lshl_add_u64 v[80:81], s[8:9], 0, v[68:69]
	v_mov_b32_e32 v51, s28
	global_store_dword v[80:81], v51, off
.LBB0_1830:
	s_or_b64 exec, exec, s[6:7]
	v_ashrrev_i32_e32 v51, 11, v54
	v_mul_hi_i32_i24_e32 v81, 0x9000, v51
	v_mul_i32_i24_e32 v80, 0x9000, v51
	v_lshl_add_u64 v[80:81], s[18:19], 0, v[80:81]
	v_lshl_add_u64 v[84:85], v[80:81], 0, s[26:27]
	v_lshlrev_b32_e32 v56, 2, v58
	v_lshl_add_u64 v[80:81], v[84:85], 0, v[56:57]
	global_load_dwordx4 v[80:83], v[80:81], off
	v_lshl_add_u64 v[86:87], s[8:9], 0, v[70:71]
	v_pk_mul_f32 v[44:45], v[0:1], v[44:45]
	v_add_co_u32_e64 v86, s[6:7], s3, v86
	v_pk_mul_f32 v[46:47], v[2:3], v[46:47]
	v_mov_b32_e32 v75, v57
	v_addc_co_u32_e64 v87, s[6:7], 0, v87, s[6:7]
	v_lshl_add_u64 v[88:89], v[84:85], 0, v[74:75]
	v_pk_mul_f32 v[40:41], v[4:5], v[40:41]
	v_pk_mul_f32 v[42:43], v[6:7], v[42:43]
	v_mov_b32_e32 v77, v57
	v_pk_mul_f32 v[36:37], v[8:9], v[36:37]
	v_pk_mul_f32 v[38:39], v[10:11], v[38:39]
	v_mov_b32_e32 v79, v57
	v_pk_mul_f32 v[32:33], v[12:13], v[32:33]
	v_pk_mul_f32 v[34:35], v[14:15], v[34:35]
	s_waitcnt vmcnt(0)
	v_pk_add_f32 v[80:81], v[80:81], 1.0 op_sel_hi:[1,0]
	v_pk_add_f32 v[82:83], v[82:83], 1.0 op_sel_hi:[1,0]
	v_pk_mul_f32 v[44:45], v[44:45], v[80:81]
	v_pk_mul_f32 v[46:47], v[46:47], v[82:83]
	s_nop 0
	v_cvt_pk_bf16_f32 v44, v44, v45
	v_lshl_add_u64 v[80:81], v[84:85], 0, v[76:77]
	s_nop 0
	v_cvt_pk_bf16_f32 v45, v46, v47
	global_store_dwordx2 v[86:87], v[44:45], off
	global_load_dwordx4 v[44:47], v[88:89], off
	s_waitcnt vmcnt(0)
	v_pk_add_f32 v[44:45], v[44:45], 1.0 op_sel_hi:[1,0]
	v_pk_add_f32 v[46:47], v[46:47], 1.0 op_sel_hi:[1,0]
	v_pk_mul_f32 v[40:41], v[40:41], v[44:45]
	v_pk_mul_f32 v[42:43], v[42:43], v[46:47]
	s_nop 0
	v_cvt_pk_bf16_f32 v40, v40, v41
	v_lshl_add_u64 v[44:45], v[84:85], 0, v[78:79]
	s_nop 0
	v_cvt_pk_bf16_f32 v41, v42, v43
	global_store_dwordx2 v[86:87], v[40:41], off offset:512
	global_load_dwordx4 v[40:43], v[80:81], off
	s_waitcnt vmcnt(0)
	v_pk_add_f32 v[40:41], v[40:41], 1.0 op_sel_hi:[1,0]
	v_pk_add_f32 v[42:43], v[42:43], 1.0 op_sel_hi:[1,0]
	v_pk_mul_f32 v[36:37], v[36:37], v[40:41]
	v_pk_mul_f32 v[38:39], v[38:39], v[42:43]
	s_nop 0
	v_cvt_pk_bf16_f32 v36, v36, v37
	s_nop 0
	s_nop 0
	v_cvt_pk_bf16_f32 v37, v38, v39
	global_store_dwordx2 v[86:87], v[36:37], off offset:1024
	global_load_dwordx4 v[36:39], v[44:45], off
	s_waitcnt vmcnt(0)
	v_pk_add_f32 v[36:37], v[36:37], 1.0 op_sel_hi:[1,0]
	v_pk_add_f32 v[38:39], v[38:39], 1.0 op_sel_hi:[1,0]
	v_pk_mul_f32 v[32:33], v[32:33], v[36:37]
	v_pk_mul_f32 v[34:35], v[34:35], v[38:39]
	s_nop 0
	v_cvt_pk_bf16_f32 v32, v32, v33
	s_nop 0
	s_nop 0
	v_cvt_pk_bf16_f32 v33, v34, v35
	global_store_dwordx2 v[86:87], v[32:33], off offset:1536
	s_and_saveexec_b64 s[6:7], s[4:5]
	s_cbranch_execz .LBB0_1825
	v_mul_f32_e32 v32, v17, v17
	v_mul_f32_e32 v33, v21, v21
	v_fmac_f32_e32 v32, v16, v16
	v_fmac_f32_e32 v33, v20, v20
	v_fmac_f32_e32 v32, v18, v18
	v_fmac_f32_e32 v33, v22, v22
	v_fmac_f32_e32 v32, v19, v19
	v_fmac_f32_e32 v33, v23, v23
	v_add_f32_e32 v32, v32, v33
	v_mul_f32_e32 v33, v25, v25
	v_fmac_f32_e32 v33, v24, v24
	v_fmac_f32_e32 v33, v26, v26
	v_fmac_f32_e32 v33, v27, v27
	v_add_f32_e32 v32, v32, v33
	v_mul_f32_e32 v33, v29, v29
	v_fmac_f32_e32 v33, v28, v28
	v_fmac_f32_e32 v33, v30, v30
	v_fmac_f32_e32 v33, v31, v31
	v_add_f32_e32 v32, v32, v33
	v_mov_b32_e32 v33, v57
	s_nop 0
	v_add_f32_dpp v32, v32, v32 quad_perm:[1,0,3,2] row_mask:0xf bank_mask:0xf bound_ctrl:1
	s_nop 1
	v_add_f32_dpp v32, v32, v32 quad_perm:[2,3,0,1] row_mask:0xf bank_mask:0xf bound_ctrl:1
	s_nop 1
	v_add_f32_dpp v32, v32, v32 row_half_mirror row_mask:0xf bank_mask:0xf bound_ctrl:1
	s_nop 1
	v_add_f32_dpp v32, v32, v32 row_mirror row_mask:0xf bank_mask:0xf bound_ctrl:1
	s_nop 1
	v_add_f32_dpp v32, v32, v32 row_bcast:15 row_mask:0xa bank_mask:0xf
	v_mov_b32_e32 v33, v57
	s_nop 1
	v_add_f32_dpp v32, v32, v32 row_bcast:31 row_mask:0xc bank_mask:0xf
	s_nop 0
	v_readlane_b32 s28, v32, 63
	s_and_saveexec_b64 s[4:5], vcc
	s_cbranch_execz .LBB0_1824
	v_lshl_add_u64 v[32:33], s[8:9], 0, v[62:63]
	v_mov_b32_e32 v34, s28
	global_store_dword v[32:33], v34, off
	s_branch .LBB0_1824

.LBB0_2147:
	s_or_b64 exec, exec, s[20:21]
	s_waitcnt vmcnt(19)
	v_lshlrev_b32_e32 v26, 16, v8
	s_waitcnt vmcnt(18)
	v_lshlrev_b32_e32 v28, 16, v7
	v_mul_f32_e32 v25, 0xbfb8aa3b, v26
	v_mul_f32_e32 v29, 0xbfb8aa3b, v28
	v_exp_f32_e32 v25, v25
	v_exp_f32_e32 v29, v29
	v_sub_f32_e32 v119, 1.0, v117
	v_sub_f32_e32 v120, 1.0, v118
	v_add_f32_e32 v25, 1.0, v25
	v_add_f32_e32 v29, 1.0, v29
	v_rcp_f32_e32 v27, v25
	v_rcp_f32_e32 v29, v29
	v_mul_f32_e32 v25, v27, v26
	v_mul_f32_e32 v28, v29, v28
	ds_write2st64_b32 v91, v25, v28 offset0:64 offset1:65
	s_waitcnt vmcnt(17)
	v_lshlrev_b32_e32 v25, 16, v6
	s_waitcnt vmcnt(16)
	v_lshlrev_b32_e32 v29, 16, v4
	v_mul_f32_e32 v25, 0xbfb8aa3b, v25
	v_mul_f32_e32 v29, 0xbfb8aa3b, v29
	v_exp_f32_e32 v25, v25
	v_exp_f32_e32 v29, v29
	v_fmac_f32_e32 v28, v27, v26
	v_add_f32_e32 v25, 1.0, v25
	s_nop 0
	v_add_f32_dpp v26, v28, v28 quad_perm:[1,0,3,2] row_mask:0xf bank_mask:0xf bound_ctrl:1
	v_add_f32_e32 v29, 1.0, v29
	v_rcp_f32_e32 v25, v25
	v_add_f32_dpp v26, v26, v26 quad_perm:[2,3,0,1] row_mask:0xf bank_mask:0xf bound_ctrl:1
	v_rcp_f32_e32 v29, v29
	v_fma_f32 v25, v119, v25, v117
	v_add_f32_dpp v26, v26, v26 row_half_mirror row_mask:0xf bank_mask:0xf bound_ctrl:1
	v_fma_f32 v29, v120, v29, v118
	ds_write2st64_b32 v91, v25, v29 offset1:1
	v_add_f32_dpp v26, v26, v26 row_mirror row_mask:0xf bank_mask:0xf bound_ctrl:1
	s_waitcnt vmcnt(10)
	v_lshlrev_b32_e32 v25, 16, v18
	v_lshlrev_b32_e32 v29, 16, v10
	v_add_f32_dpp v26, v26, v26 row_bcast:15 row_mask:0xa bank_mask:0xf
	v_sub_f32_e32 v29, v29, v25
	ds_write2st64_b32 v93, v29, v25 offset0:128 offset1:160
	v_add_f32_dpp v26, v26, v26 row_bcast:31 row_mask:0xc bank_mask:0xf
	s_nop 0
	v_readlane_b32 s17, v26, 63
	s_and_saveexec_b64 s[20:21], s[6:7]
	s_nop 0
	v_mov_b32_e32 v26, s17
	ds_write_b32 v94, v26
	s_or_b64 exec, exec, s[20:21]
	v_lshlrev_b32_e32 v27, 16, v9
	v_lshlrev_b32_e32 v29, 16, v13
	v_mul_f32_e32 v26, 0xbfb8aa3b, v27
	v_mul_f32_e32 v30, 0xbfb8aa3b, v29
	v_exp_f32_e32 v26, v26
	v_exp_f32_e32 v30, v30
	v_add_f32_e32 v26, 1.0, v26
	v_add_f32_e32 v30, 1.0, v30
	v_rcp_f32_e32 v28, v26
	v_rcp_f32_e32 v30, v30
	v_mul_f32_e32 v26, v28, v27
	v_mul_f32_e32 v29, v30, v29
	ds_write2st64_b32 v95, v26, v29 offset0:64 offset1:65
	v_lshlrev_b32_e32 v26, 16, v12
	v_lshlrev_b32_e32 v30, 16, v11
	v_mul_f32_e32 v26, 0xbfb8aa3b, v26
	v_mul_f32_e32 v30, 0xbfb8aa3b, v30
	v_exp_f32_e32 v26, v26
	v_exp_f32_e32 v30, v30
	v_fmac_f32_e32 v29, v28, v27
	v_add_f32_e32 v26, 1.0, v26
	v_add_f32_e32 v30, 1.0, v30
	v_rcp_f32_e32 v26, v26
	v_rcp_f32_e32 v30, v30
	v_fma_f32 v26, v119, v26, v117
	v_fma_f32 v30, v120, v30, v118
	ds_write2st64_b32 v95, v26, v30 offset1:1
	s_waitcnt vmcnt(5)
	v_lshlrev_b32_e32 v26, 16, v19
	v_sub_f32_e32 v25, v25, v26
	ds_write2st64_b32 v97, v25, v26 offset0:128 offset1:160
	s_nop 0
	v_add_f32_dpp v25, v29, v29 quad_perm:[1,0,3,2] row_mask:0xf bank_mask:0xf bound_ctrl:1
	s_nop 1
	v_add_f32_dpp v25, v25, v25 quad_perm:[2,3,0,1] row_mask:0xf bank_mask:0xf bound_ctrl:1
	s_nop 1
	v_add_f32_dpp v25, v25, v25 row_half_mirror row_mask:0xf bank_mask:0xf bound_ctrl:1
	s_nop 1
	v_add_f32_dpp v25, v25, v25 row_mirror row_mask:0xf bank_mask:0xf bound_ctrl:1
	s_nop 1
	v_add_f32_dpp v25, v25, v25 row_bcast:15 row_mask:0xa bank_mask:0xf
	s_nop 1
	v_add_f32_dpp v25, v25, v25 row_bcast:31 row_mask:0xc bank_mask:0xf
	s_nop 0
	v_readlane_b32 s17, v25, 63
	s_and_saveexec_b64 s[20:21], s[6:7]
	s_nop 0
	v_mov_b32_e32 v25, s17
	ds_write_b32 v98, v25
	s_or_b64 exec, exec, s[20:21]
	v_lshlrev_b32_e32 v27, 16, v17
	v_lshlrev_b32_e32 v29, 16, v16
	v_mul_f32_e32 v25, 0xbfb8aa3b, v27
	v_mul_f32_e32 v30, 0xbfb8aa3b, v29
	v_exp_f32_e32 v25, v25
	v_exp_f32_e32 v30, v30
	v_add_f32_e32 v25, 1.0, v25
	v_add_f32_e32 v30, 1.0, v30
	v_rcp_f32_e32 v28, v25
	v_rcp_f32_e32 v30, v30
	v_mul_f32_e32 v25, v28, v27
	v_mul_f32_e32 v29, v30, v29
	ds_write2st64_b32 v99, v25, v29 offset0:64 offset1:65
	v_lshlrev_b32_e32 v25, 16, v15
	v_lshlrev_b32_e32 v30, 16, v14
	v_mul_f32_e32 v25, 0xbfb8aa3b, v25
	v_mul_f32_e32 v30, 0xbfb8aa3b, v30
	v_exp_f32_e32 v25, v25
	v_exp_f32_e32 v30, v30
	v_fmac_f32_e32 v29, v28, v27
	v_add_f32_e32 v25, 1.0, v25
	v_add_f32_e32 v30, 1.0, v30
	v_rcp_f32_e32 v25, v25
	v_rcp_f32_e32 v30, v30
	v_fma_f32 v25, v119, v25, v117
	v_fma_f32 v30, v120, v30, v118
	ds_write2st64_b32 v99, v25, v30 offset1:1
	s_waitcnt vmcnt(0)
; __device__ __forceinline__ float bf2f(u16 h) { return __uint_as_float((unsigned)h << 16); }
; __device__ __forceinline__ void phase_hgrn(KP P, int l_, unsigned char* shm) {
;     ...
;         const float v0a = bf2f(pC[((size_t)b * SEQ) * 2048 + h * 128 + 1024 + half * 64 + cp]), v0b = bf2f(pC[((size_t)b * SEQ) * 2048 + h * 128 + 1024 + half * 64 + cp + 32]);
;         f32x2 ea[4], eb[4];
; #pragma unroll
;         for (int jj = 0; jj < 4; ++jj) { ea[jj] = (f32x2){-v0a, -v0a}; eb[jj] = (f32x2){-v0b, -v0b}; }
;         unsigned short gq0[4], gq1[4], gf0[4], gf1[4], gvv[5];
;     ...
;         HG_LOAD(0); HG_PREP();
;         __syncthreads();
	v_lshlrev_b32_e32 v25, 16, v24
	v_sub_f32_e32 v26, v26, v25
	ds_write2st64_b32 v101, v26, v25 offset0:128 offset1:160
	s_nop 0
	v_add_f32_dpp v26, v29, v29 quad_perm:[1,0,3,2] row_mask:0xf bank_mask:0xf bound_ctrl:1
	s_nop 1
	v_add_f32_dpp v26, v26, v26 quad_perm:[2,3,0,1] row_mask:0xf bank_mask:0xf bound_ctrl:1
	s_nop 1
	v_add_f32_dpp v26, v26, v26 row_half_mirror row_mask:0xf bank_mask:0xf bound_ctrl:1
	s_nop 1
	v_add_f32_dpp v26, v26, v26 row_mirror row_mask:0xf bank_mask:0xf bound_ctrl:1
	s_nop 1
	v_add_f32_dpp v26, v26, v26 row_bcast:15 row_mask:0xa bank_mask:0xf
	s_nop 1
	v_add_f32_dpp v26, v26, v26 row_bcast:31 row_mask:0xc bank_mask:0xf
	s_nop 0
	v_readlane_b32 s17, v26, 63
	s_and_saveexec_b64 s[20:21], s[6:7]
	s_nop 0
	v_mov_b32_e32 v26, s17
	ds_write_b32 v102, v26
	s_or_b64 exec, exec, s[20:21]
	v_lshlrev_b32_e32 v26, 16, v23
	v_lshlrev_b32_e32 v29, 16, v22
	v_mul_f32_e32 v27, 0xbfb8aa3b, v26
	v_mul_f32_e32 v30, 0xbfb8aa3b, v29
	v_exp_f32_e32 v27, v27
	v_exp_f32_e32 v30, v30
	v_add_f32_e32 v27, 1.0, v27
	v_add_f32_e32 v30, 1.0, v30
	v_rcp_f32_e32 v27, v27
	v_rcp_f32_e32 v30, v30
	v_mul_f32_e32 v28, v27, v26
	v_mul_f32_e32 v29, v30, v29
	ds_write2st64_b32 v103, v28, v29 offset0:64 offset1:65
	v_lshlrev_b32_e32 v28, 16, v21
	v_lshlrev_b32_e32 v30, 16, v20
	v_mul_f32_e32 v28, 0xbfb8aa3b, v28
	v_mul_f32_e32 v30, 0xbfb8aa3b, v30
	v_exp_f32_e32 v28, v28
	v_exp_f32_e32 v30, v30
	v_fmac_f32_e32 v29, v27, v26
	v_add_f32_e32 v28, 1.0, v28
	v_add_f32_e32 v30, 1.0, v30
	v_rcp_f32_e32 v28, v28
	v_rcp_f32_e32 v30, v30
	v_fma_f32 v28, v119, v28, v117
	v_fma_f32 v30, v120, v30, v118
	ds_write2st64_b32 v103, v28, v30 offset1:1
	v_lshlrev_b32_e32 v28, 16, v2
	v_sub_f32_e32 v25, v25, v28
	ds_write2st64_b32 v105, v25, v28 offset0:128 offset1:160
	s_nop 0
	v_add_f32_dpp v25, v29, v29 quad_perm:[1,0,3,2] row_mask:0xf bank_mask:0xf bound_ctrl:1
	s_nop 1
	v_add_f32_dpp v25, v25, v25 quad_perm:[2,3,0,1] row_mask:0xf bank_mask:0xf bound_ctrl:1
	s_nop 1
	v_add_f32_dpp v25, v25, v25 row_half_mirror row_mask:0xf bank_mask:0xf bound_ctrl:1
	s_nop 1
	v_add_f32_dpp v25, v25, v25 row_mirror row_mask:0xf bank_mask:0xf bound_ctrl:1
	s_nop 1
	v_add_f32_dpp v25, v25, v25 row_bcast:15 row_mask:0xa bank_mask:0xf
	s_nop 1
	v_add_f32_dpp v25, v25, v25 row_bcast:31 row_mask:0xc bank_mask:0xf
	s_nop 0
	v_readlane_b32 s17, v25, 63
	s_and_saveexec_b64 s[20:21], s[6:7]
	s_nop 0
	v_mov_b32_e32 v25, s17
	ds_write_b32 v106, v25
	s_or_b64 exec, exec, s[20:21]
	v_lshlrev_b32_e32 v0, 16, v0
	v_lshlrev_b32_e32 v1, 16, v1
	v_xor_b32_e32 v64, 0x80000000, v0
	v_xor_b32_e32 v62, 0x80000000, v1
	v_perm_b32 v1, v24, v19, s82
	v_perm_b32 v0, v18, v10, s82
	v_lshl_add_u64 v[18:19], s[52:53], 1, v[46:47]
	s_mov_b32 s17, s53
	v_lshl_add_u64 v[58:59], v[18:19], 0, s[16:17]
	v_lshl_add_u64 v[60:61], v[56:57], 0, s[16:17]
	v_perm_b32 v121, v9, v8, s82
	v_perm_b32 v125, v23, v17, s82
	v_perm_b32 v122, v13, v7, s82
	v_perm_b32 v126, v22, v16, s82
	v_perm_b32 v123, v12, v6, s82
	v_perm_b32 v127, v21, v15, s82
	v_perm_b32 v124, v11, v4, s82
	v_perm_b32 v128, v20, v14, s82
	s_mov_b32 s26, 0
	v_mov_b32_e32 v65, v64
	v_mov_b32_e32 v70, v64
	v_mov_b32_e32 v71, v64
	v_mov_b32_e32 v68, v64
	v_mov_b32_e32 v69, v64
	v_mov_b32_e32 v66, v64
	v_mov_b32_e32 v67, v64
	v_mov_b32_e32 v63, v62
	v_mov_b32_e32 v76, v62
	v_mov_b32_e32 v77, v62
	v_mov_b32_e32 v74, v62
	v_mov_b32_e32 v75, v62
	v_mov_b32_e32 v72, v62
	v_mov_b32_e32 v73, v62
	s_waitcnt lgkmcnt(0)
	s_barrier
	s_branch .LBB0_2158

; __device__ __forceinline__ u16 f2bf(float f) { return (u16)(cvt_pk_bf16(f, 0.f) & 0xffffu); }
; __device__ __forceinline__ void phase_hgrn(KP P, int l_, unsigned char* shm) {
;     ...
;             __syncthreads();
; #pragma unroll
;             for (int i = 0; i < 4; ++i) { const int tl = wave * 4 + i; const size_t tok = (size_t)b * SEQ + c * T + tl;
;                 const f32x4 oa = *(const f32x4*)(sO + tl * 256 + lane * 4);
;                 const float o = ((oa[0] + oa[1]) + (oa[2] + oa[3])) + sVN[tl * 64 + lane] * sQS[tl];
;                 OC[tok * 512 + h * 128 + half * 64 + lane] = f2bf(o); }
;             if (c + 1 < SEQ / T) HG_PREP();
.LBB0_2172:
	s_waitcnt lgkmcnt(0)
	s_barrier
	s_waitcnt vmcnt(0)
	v_perm_b32 v1, v246, v227, s82
	v_perm_b32 v0, v222, v217, s82
	v_perm_b32 v124, v221, v216, s82
	v_perm_b32 v128, v245, v226, s82
	v_perm_b32 v123, v220, v215, s82
	v_perm_b32 v127, v244, v225, s82
	v_perm_b32 v122, v219, v214, s82
	v_perm_b32 v126, v243, v224, s82
	v_perm_b32 v121, v218, v213, s82
	v_perm_b32 v125, v242, v223, s82
	v_mov_b32_e32 v2, v247
	ds_read_b128 v[158:161], v112 offset:49152
	ds_read_b128 v[162:165], v113 offset:49152
	ds_read_b128 v[166:169], v114 offset:49152
	ds_read_b128 v[170:173], v115 offset:49152
	v_add_u32_e32 v6, v90, v92
	v_add_u32_e32 v7, v90, v96
	v_add_u32_e32 v8, v90, v100
	v_add_u32_e32 v9, v90, v104
	ds_read_b32 v174, v6 offset:40960
	ds_read_b32 v175, v94
	ds_read_b32 v176, v7 offset:40960
	ds_read_b32 v186, v98
	ds_read_b32 v187, v8 offset:40960
	ds_read_b32 v235, v102
	ds_read_b32 v239, v9 offset:40960
	ds_read_b32 v240, v106
	s_lshl_b32 s0, s26, 5
	s_add_u32 s22, s18, s0
	s_addc_u32 s23, s19, 0
	s_and_b64 vcc, exec, s[20:21]
	v_lshl_add_u64 v[10:11], s[22:23], 0, v[40:41]
	s_waitcnt lgkmcnt(0)
	v_add_f32_e32 v4, v158, v159
	v_add_f32_e32 v6, v160, v161
	v_add_f32_e32 v4, v4, v6
	v_fmac_f32_e32 v4, v174, v175
	v_lshlrev_b64 v[6:7], 10, v[10:11]
	v_lshl_add_u64 v[6:7], v[58:59], 0, v[6:7]
	s_nop 0
	v_cvt_pk_bf16_f32 v4, v4, v5
	global_store_short v[6:7], v4, off
	v_lshl_add_u64 v[10:11], s[22:23], 0, v[48:49]
	v_add_f32_e32 v8, v162, v163
	v_add_f32_e32 v9, v164, v165
	v_add_f32_e32 v8, v8, v9
	v_fmac_f32_e32 v8, v176, v186
	v_lshlrev_b64 v[6:7], 10, v[10:11]
	v_lshl_add_u64 v[6:7], v[58:59], 0, v[6:7]
	s_nop 0
	v_cvt_pk_bf16_f32 v8, v8, v5
	global_store_short v[6:7], v8, off
	v_lshl_add_u64 v[10:11], s[22:23], 0, v[50:51]
	v_add_f32_e32 v4, v166, v167
	v_add_f32_e32 v9, v168, v169
	v_add_f32_e32 v4, v4, v9
	v_fmac_f32_e32 v4, v187, v235
	v_lshlrev_b64 v[6:7], 10, v[10:11]
	v_lshl_add_u64 v[6:7], v[58:59], 0, v[6:7]
	s_nop 0
	v_cvt_pk_bf16_f32 v4, v4, v5
	global_store_short v[6:7], v4, off
	v_lshl_add_u64 v[10:11], s[22:23], 0, v[52:53]
	v_add_f32_e32 v8, v170, v171
	v_add_f32_e32 v9, v172, v173
	v_add_f32_e32 v8, v8, v9
	v_fmac_f32_e32 v8, v239, v240
	v_lshlrev_b64 v[6:7], 10, v[10:11]
	v_lshl_add_u64 v[6:7], v[58:59], 0, v[6:7]
	s_nop 0
	v_cvt_pk_bf16_f32 v8, v8, v5
	global_store_short v[6:7], v8, off
	s_cbranch_vccz .LBB0_2157
	v_lshlrev_b32_e32 v4, 16, v121
	v_mul_f32_e32 v6, 0xbfb8aa3b, v4
	v_exp_f32_e32 v6, v6
	v_lshlrev_b32_e32 v7, 16, v122
	v_mul_f32_e32 v8, 0xbfb8aa3b, v7
	v_exp_f32_e32 v8, v8
	v_add_f32_e32 v6, 1.0, v6
	v_rcp_f32_e32 v6, v6
	v_lshlrev_b32_e32 v9, 16, v123
	v_add_f32_e32 v8, 1.0, v8
	v_mul_f32_e32 v9, 0xbfb8aa3b, v9
	v_rcp_f32_e32 v8, v8
	v_mul_f32_e32 v6, v6, v4
	v_exp_f32_e32 v4, v9
	v_lshlrev_b32_e32 v9, 16, v124
	v_mul_f32_e32 v9, 0xbfb8aa3b, v9
	v_exp_f32_e32 v9, v9
	v_mul_f32_e32 v10, v8, v7
	ds_write2st64_b32 v91, v6, v10 offset0:64 offset1:65
	v_fmac_f32_e32 v6, v8, v7
	v_add_f32_e32 v4, 1.0, v4
	v_add_f32_e32 v9, 1.0, v9
	v_add_f32_dpp v6, v6, v6 quad_perm:[1,0,3,2] row_mask:0xf bank_mask:0xf bound_ctrl:1
	v_rcp_f32_e32 v4, v4
	v_rcp_f32_e32 v9, v9
	v_add_f32_dpp v6, v6, v6 quad_perm:[2,3,0,1] row_mask:0xf bank_mask:0xf bound_ctrl:1
	v_fma_f32 v4, v119, v4, v117
	s_nop 0
	v_add_f32_dpp v6, v6, v6 row_half_mirror row_mask:0xf bank_mask:0xf bound_ctrl:1
	v_fma_f32 v9, v120, v9, v118
	ds_write2st64_b32 v91, v4, v9 offset1:1
	v_add_f32_dpp v6, v6, v6 row_mirror row_mask:0xf bank_mask:0xf bound_ctrl:1
	v_and_b32_e32 v4, 0xffff0000, v0
	v_lshlrev_b32_e32 v9, 16, v0
	v_add_f32_dpp v6, v6, v6 row_bcast:15 row_mask:0xa bank_mask:0xf
	v_sub_f32_e32 v9, v9, v4
	ds_write2st64_b32 v93, v9, v4 offset0:128 offset1:160
	v_add_f32_dpp v6, v6, v6 row_bcast:31 row_mask:0xc bank_mask:0xf
	s_nop 0
	v_readlane_b32 s17, v6, 63
	s_and_saveexec_b64 s[20:21], s[6:7]
	s_nop 0
	v_mov_b32_e32 v6, s17
	ds_write_b32 v94, v6
	s_or_b64 exec, exec, s[20:21]
	v_and_b32_e32 v6, 0xffff0000, v121
	v_mul_f32_e32 v7, 0xbfb8aa3b, v6
	v_exp_f32_e32 v7, v7
	v_and_b32_e32 v10, 0xffff0000, v123
	v_mul_f32_e32 v10, 0xbfb8aa3b, v10
	v_and_b32_e32 v8, 0xffff0000, v122
	v_add_f32_e32 v7, 1.0, v7
	v_rcp_f32_e32 v7, v7
	v_mul_f32_e32 v9, 0xbfb8aa3b, v8
	v_exp_f32_e32 v9, v9
	v_mul_f32_e32 v7, v7, v6
	v_exp_f32_e32 v6, v10
	v_and_b32_e32 v10, 0xffff0000, v124
	v_mul_f32_e32 v10, 0xbfb8aa3b, v10
	v_exp_f32_e32 v10, v10
	v_add_f32_e32 v6, 1.0, v6
	v_add_f32_e32 v9, 1.0, v9
	v_rcp_f32_e32 v6, v6
	v_add_f32_e32 v10, 1.0, v10
	v_rcp_f32_e32 v10, v10
	v_rcp_f32_e32 v9, v9
	v_fma_f32 v6, v119, v6, v117
	v_fma_f32 v10, v120, v10, v118
	v_mul_f32_e32 v11, v9, v8
	ds_write2st64_b32 v95, v6, v10 offset1:1
	v_lshlrev_b32_e32 v6, 16, v1
	ds_write2st64_b32 v95, v7, v11 offset0:64 offset1:65
	v_sub_f32_e32 v4, v4, v6
	v_fmac_f32_e32 v7, v9, v8
	ds_write2st64_b32 v97, v4, v6 offset0:128 offset1:160
	s_nop 0
	v_add_f32_dpp v4, v7, v7 quad_perm:[1,0,3,2] row_mask:0xf bank_mask:0xf bound_ctrl:1
	s_nop 0
	s_nop 0
	v_add_f32_dpp v4, v4, v4 quad_perm:[2,3,0,1] row_mask:0xf bank_mask:0xf bound_ctrl:1
	s_nop 1
	v_add_f32_dpp v4, v4, v4 row_half_mirror row_mask:0xf bank_mask:0xf bound_ctrl:1
	s_nop 1
	v_add_f32_dpp v4, v4, v4 row_mirror row_mask:0xf bank_mask:0xf bound_ctrl:1
	s_nop 1
	v_add_f32_dpp v4, v4, v4 row_bcast:15 row_mask:0xa bank_mask:0xf
	s_nop 1
	v_add_f32_dpp v4, v4, v4 row_bcast:31 row_mask:0xc bank_mask:0xf
	s_nop 0
	v_readlane_b32 s17, v4, 63
	s_and_saveexec_b64 s[20:21], s[6:7]
	s_nop 0
	v_mov_b32_e32 v4, s17
	ds_write_b32 v98, v4
	s_or_b64 exec, exec, s[20:21]
	v_lshlrev_b32_e32 v4, 16, v125
	v_mul_f32_e32 v7, 0xbfb8aa3b, v4
	v_exp_f32_e32 v7, v7
	v_lshlrev_b32_e32 v10, 16, v127
	v_mul_f32_e32 v10, 0xbfb8aa3b, v10
	v_lshlrev_b32_e32 v8, 16, v126
	v_add_f32_e32 v7, 1.0, v7
	v_rcp_f32_e32 v7, v7
	v_mul_f32_e32 v9, 0xbfb8aa3b, v8
	v_exp_f32_e32 v9, v9
	v_mul_f32_e32 v7, v7, v4
	v_exp_f32_e32 v4, v10
	v_lshlrev_b32_e32 v10, 16, v128
	v_mul_f32_e32 v10, 0xbfb8aa3b, v10
	v_exp_f32_e32 v10, v10
	v_add_f32_e32 v4, 1.0, v4
	v_add_f32_e32 v9, 1.0, v9
	v_rcp_f32_e32 v4, v4
	v_add_f32_e32 v10, 1.0, v10
	v_rcp_f32_e32 v10, v10
	v_rcp_f32_e32 v9, v9
	v_fma_f32 v4, v119, v4, v117
	v_fma_f32 v10, v120, v10, v118
	v_mul_f32_e32 v11, v9, v8
	ds_write2st64_b32 v99, v4, v10 offset1:1
	v_and_b32_e32 v4, 0xffff0000, v1
	ds_write2st64_b32 v99, v7, v11 offset0:64 offset1:65
	v_sub_f32_e32 v6, v6, v4
	v_fmac_f32_e32 v7, v9, v8
	ds_write2st64_b32 v101, v6, v4 offset0:128 offset1:160
	s_nop 0
	v_add_f32_dpp v6, v7, v7 quad_perm:[1,0,3,2] row_mask:0xf bank_mask:0xf bound_ctrl:1
	s_nop 0
	s_nop 0
	v_add_f32_dpp v6, v6, v6 quad_perm:[2,3,0,1] row_mask:0xf bank_mask:0xf bound_ctrl:1
	s_nop 1
	v_add_f32_dpp v6, v6, v6 row_half_mirror row_mask:0xf bank_mask:0xf bound_ctrl:1
	s_nop 1
	v_add_f32_dpp v6, v6, v6 row_mirror row_mask:0xf bank_mask:0xf bound_ctrl:1
	s_nop 1
	v_add_f32_dpp v6, v6, v6 row_bcast:15 row_mask:0xa bank_mask:0xf
	s_nop 1
	v_add_f32_dpp v6, v6, v6 row_bcast:31 row_mask:0xc bank_mask:0xf
	s_nop 0
	v_readlane_b32 s17, v6, 63
	s_and_saveexec_b64 s[20:21], s[6:7]
	s_nop 0
	v_mov_b32_e32 v6, s17
	ds_write_b32 v102, v6
	s_or_b64 exec, exec, s[20:21]
	v_and_b32_e32 v6, 0xffff0000, v125
	v_mul_f32_e32 v7, 0xbfb8aa3b, v6
	v_exp_f32_e32 v7, v7
	v_and_b32_e32 v10, 0xffff0000, v127
	v_mul_f32_e32 v10, 0xbfb8aa3b, v10
	v_and_b32_e32 v8, 0xffff0000, v126
	v_add_f32_e32 v7, 1.0, v7
	v_rcp_f32_e32 v7, v7
	v_mul_f32_e32 v9, 0xbfb8aa3b, v8
	v_exp_f32_e32 v9, v9
	v_mul_f32_e32 v6, v7, v6
	v_exp_f32_e32 v7, v10
	v_and_b32_e32 v10, 0xffff0000, v128
	v_mul_f32_e32 v10, 0xbfb8aa3b, v10
	v_exp_f32_e32 v10, v10
	v_add_f32_e32 v7, 1.0, v7
	v_add_f32_e32 v9, 1.0, v9
	v_rcp_f32_e32 v7, v7
	v_add_f32_e32 v10, 1.0, v10
	v_rcp_f32_e32 v10, v10
	v_rcp_f32_e32 v9, v9
	v_fma_f32 v7, v119, v7, v117
	v_fma_f32 v10, v120, v10, v118
	v_mul_f32_e32 v11, v9, v8
	ds_write2st64_b32 v103, v7, v10 offset1:1
	v_lshlrev_b32_e32 v7, 16, v2
	ds_write2st64_b32 v103, v6, v11 offset0:64 offset1:65
	v_sub_f32_e32 v4, v4, v7
	v_fmac_f32_e32 v6, v9, v8
	ds_write2st64_b32 v105, v4, v7 offset0:128 offset1:160
	s_nop 0
	v_add_f32_dpp v4, v6, v6 quad_perm:[1,0,3,2] row_mask:0xf bank_mask:0xf bound_ctrl:1
	s_nop 0
	s_nop 0
	v_add_f32_dpp v4, v4, v4 quad_perm:[2,3,0,1] row_mask:0xf bank_mask:0xf bound_ctrl:1
	s_nop 1
	v_add_f32_dpp v4, v4, v4 row_half_mirror row_mask:0xf bank_mask:0xf bound_ctrl:1
	s_nop 1
	v_add_f32_dpp v4, v4, v4 row_mirror row_mask:0xf bank_mask:0xf bound_ctrl:1
	s_nop 1
	v_add_f32_dpp v4, v4, v4 row_bcast:15 row_mask:0xa bank_mask:0xf
	s_nop 1
	v_add_f32_dpp v4, v4, v4 row_bcast:31 row_mask:0xc bank_mask:0xf
	s_nop 0
	v_readlane_b32 s17, v4, 63
	s_and_saveexec_b64 s[20:21], s[6:7]
	s_cbranch_execz .LBB0_2156
	v_mov_b32_e32 v4, s17
	ds_write_b32 v106, v4
	s_branch .LBB0_2156

.LBB0_2469:
	v_readlane_b32 s0, v255, 16
	v_readlane_b32 s1, v255, 17
	s_lshl_b64 s[84:85], s[70:71], 11
	v_lshlrev_b32_e32 v0, 16, v0
	v_lshl_add_u64 v[6:7], v[6:7], 0, s[0:1]
	v_add_co_u32_e32 v8, vcc, 0x1000, v6
	s_movk_i32 s0, 0x6000
	s_nop 0
	v_addc_co_u32_e32 v9, vcc, 0, v7, vcc
	global_load_ushort v33, v[8:9], off
	global_load_ushort v34, v[8:9], off offset:1024
	global_load_ushort v35, v[8:9], off offset:2048
	v_add_co_u32_e32 v8, vcc, 0x2000, v6
	s_nop 0
	v_addc_co_u32_e32 v9, vcc, 0, v7, vcc
	global_load_ushort v27, v[8:9], off
	global_load_ushort v28, v[8:9], off offset:1024
	global_load_ushort v29, v[8:9], off offset:2048
	v_add_co_u32_e32 v8, vcc, 0x3000, v6
	v_lshlrev_b32_e32 v2, 16, v2
	s_nop 0
	v_addc_co_u32_e32 v9, vcc, 0, v7, vcc
	global_load_ushort v22, v[8:9], off
	global_load_ushort v23, v[8:9], off offset:1024
	global_load_ushort v24, v[8:9], off offset:2048
	v_add_co_u32_e32 v8, vcc, 0x4000, v6
	s_nop 1
	v_addc_co_u32_e32 v9, vcc, 0, v7, vcc
	global_load_ushort v13, v[8:9], off
	global_load_ushort v14, v[8:9], off offset:1024
	global_load_ushort v15, v[8:9], off offset:2048
	v_add_co_u32_e32 v8, vcc, 0x5000, v6
	s_nop 1
	v_addc_co_u32_e32 v9, vcc, 0, v7, vcc
	global_load_ushort v1, v[8:9], off
	global_load_ushort v3, v[8:9], off offset:1024
	global_load_ushort v12, v[8:9], off offset:2048
	v_add_co_u32_e32 v16, vcc, s0, v6
	s_or_b32 s0, s84, s38
	v_lshl_add_u64 v[8:9], s[26:27], 0, v[4:5]
	v_mad_u64_u32 v[10:11], s[42:43], s0, v236, v[8:9]
	global_load_ushort v51, v[6:7], off
	global_load_ushort v54, v[6:7], off offset:1024
	global_load_ushort v55, v[6:7], off offset:2048
	s_mul_i32 s42, s85, 0xc00
	v_add_u32_e32 v11, s42, v11
	global_load_ushort v56, v[10:11], off
	v_addc_co_u32_e32 v17, vcc, 0, v7, vcc
	global_load_ushort v19, v[16:17], off
	global_load_ushort v20, v[16:17], off offset:1024
	global_load_ushort v21, v[16:17], off offset:2048
	global_load_ushort v57, v[10:11], off offset:1024
	v_add_co_u32_e32 v30, vcc, 0x7000, v6
	s_movk_i32 s0, 0x3000
	s_nop 0
	v_addc_co_u32_e32 v31, vcc, 0, v7, vcc
	global_load_ushort v16, v[30:31], off
	global_load_ushort v17, v[30:31], off offset:1024
	global_load_ushort v18, v[30:31], off offset:2048
	global_load_ushort v50, v[10:11], off offset:3072
	v_add_co_u32_e32 v30, vcc, s66, v10
	s_nop 1
	v_addc_co_u32_e32 v31, vcc, 0, v11, vcc
	v_add_co_u32_e32 v36, vcc, s67, v10
	s_nop 1
	v_addc_co_u32_e32 v37, vcc, 0, v11, vcc
	global_load_ushort v49, v[36:37], off offset:-4096
	global_load_ushort v48, v[30:31], off offset:1024
	global_load_ushort v47, v[30:31], off offset:2048
	global_load_ushort v46, v[30:31], off offset:3072
	global_load_ushort v45, v[36:37], off
	global_load_ushort v44, v[36:37], off offset:1024
	global_load_ushort v43, v[36:37], off offset:2048
	global_load_ushort v40, v[36:37], off offset:3072
	v_add_co_u32_e32 v30, vcc, s0, v10
	s_movk_i32 s0, 0x4000
	s_nop 0
	v_addc_co_u32_e32 v31, vcc, 0, v11, vcc
	v_add_co_u32_e32 v52, vcc, s0, v10
	s_nop 1
	v_addc_co_u32_e32 v53, vcc, 0, v11, vcc
	global_load_ushort v42, v[52:53], off offset:-4096
	global_load_ushort v41, v[30:31], off offset:1024
	global_load_ushort v38, v[30:31], off offset:2048
	global_load_ushort v37, v[30:31], off offset:3072
	global_load_ushort v36, v[52:53], off
	global_load_ushort v32, v[52:53], off offset:1024
	s_nop 0
	global_load_ushort v31, v[52:53], off offset:2048
	global_load_ushort v30, v[52:53], off offset:3072
	v_add_co_u32_e32 v52, vcc, s68, v10
	s_nop 1
	v_addc_co_u32_e32 v53, vcc, 0, v11, vcc
	global_load_ushort v26, v[52:53], off
	global_load_ushort v25, v[52:53], off offset:1024
	global_load_ushort v58, v[10:11], off offset:2048
	s_nop 0
	global_load_ushort v11, v[52:53], off offset:2048
	global_load_ushort v10, v[52:53], off offset:3072
	s_waitcnt vmcnt(32)
	v_lshlrev_b32_e32 v53, 16, v51
	s_waitcnt vmcnt(31)
	v_lshlrev_b32_e32 v52, 16, v54
	v_sub_f32_e32 v0, v0, v52
	v_fma_f32 v0, v245, v0, v52
	s_waitcnt vmcnt(30)
	v_lshlrev_b32_e32 v51, 16, v55
	s_waitcnt vmcnt(29)
	v_lshlrev_b32_e32 v54, 16, v56
	v_mul_f32_e32 v56, v247, v0
	v_add_f32_e32 v54, v250, v54
	v_mul_f32_e32 v54, 0xbfb8aa3b, v54
	s_waitcnt vmcnt(25)
	v_lshlrev_b32_e32 v55, 16, v57
	v_mul_f32_e32 v57, v56, v56
	v_add_f32_e32 v55, v251, v55
	v_mul_f32_e32 v55, 0xbfb8aa3b, v55
	v_mov_b32_dpp v57, v57 quad_perm:[1,0,3,2] row_mask:0xf bank_mask:0xf bound_ctrl:1
	v_fmac_f32_e32 v57, v56, v56
	v_exp_f32_e32 v55, v55
	v_exp_f32_e32 v54, v54
	v_add_f32_dpp v57, v57, v57 quad_perm:[2,3,0,1] row_mask:0xf bank_mask:0xf bound_ctrl:1
	v_sub_f32_e32 v2, v2, v53
	v_add_f32_e32 v55, 1.0, v55
	v_add_f32_dpp v57, v57, v57 row_half_mirror row_mask:0xf bank_mask:0xf bound_ctrl:1
	v_rcp_f32_e32 v55, v55
	v_fma_f32 v2, v244, v2, v53
	v_add_f32_dpp v57, v57, v57 row_mirror row_mask:0xf bank_mask:0xf bound_ctrl:1
	v_add_f32_e32 v54, 1.0, v54
	v_rcp_f32_e32 v54, v54
	v_add_f32_dpp v57, v57, v57 row_bcast:15 row_mask:0xa bank_mask:0xf
	v_mul_f32_e32 v54, 0xbf1b4598, v54
	v_mul_f32_e32 v54, 0x3fb8aa3b, v54
	v_add_f32_dpp v57, v57, v57 row_bcast:31 row_mask:0xc bank_mask:0xf
	v_exp_f32_e32 v54, v54
	v_readlane_b32 s0, v57, 63
	v_sub_f32_e32 v39, v39, v51
	v_fma_f32 v39, v246, v39, v51
	v_max_f32_e64 v57, s0, s0
	v_max_f32_e32 v57, 0x179abe15, v57
	v_rsq_f32_e32 v57, v57
	s_nop 0
	v_mul_f32_e32 v56, v56, v57
	v_add_f32_e32 v57, -1.0, v55
	v_fma_f32 v57, v248, v57, 1.0
	v_mul_f32_e32 v0, v0, v57
	v_mul_f32_e32 v57, v2, v0
	v_mul_f32_e32 v59, v249, v57
	ds_write2st64_b32 v125, v54, v56 offset1:32
	v_mul_f32_e32 v54, v55, v56
	v_mov_b32_dpp v59, v59 quad_perm:[1,0,3,2] row_mask:0xf bank_mask:0xf bound_ctrl:1
	v_fmac_f32_e32 v59, v249, v57
	ds_write2st64_b32 v125, v54, v0 offset0:64 offset1:96
	ds_write_b32 v125, v2 offset:32768
	ds_write_b32 v126, v39
	v_add_f32_dpp v57, v59, v59 quad_perm:[2,3,0,1] row_mask:0xf bank_mask:0xf bound_ctrl:1
	s_waitcnt vmcnt(2)
	v_lshlrev_b32_e32 v0, 16, v58
	v_add_f32_dpp v57, v57, v57 row_half_mirror row_mask:0xf bank_mask:0xf bound_ctrl:1
	ds_write_b32 v127, v0
	s_nop 0
	v_add_f32_dpp v57, v57, v57 row_mirror row_mask:0xf bank_mask:0xf bound_ctrl:1
	s_nop 1
	v_add_f32_dpp v57, v57, v57 row_bcast:15 row_mask:0xa bank_mask:0xf
	s_nop 1
	v_add_f32_dpp v57, v57, v57 row_bcast:31 row_mask:0xc bank_mask:0xf
	s_nop 0
	v_readlane_b32 s43, v57, 63
	s_and_saveexec_b64 s[72:73], s[4:5]
	v_mov_b32_e32 v0, s41
	v_mov_b32_e32 v2, s43
	ds_write_b32 v0, v2
	s_or_b64 exec, exec, s[72:73]
	v_lshlrev_b32_e32 v39, 16, v33
	v_lshlrev_b32_e32 v33, 16, v34
	v_lshlrev_b32_e32 v0, 16, v35
	v_sub_f32_e32 v35, v52, v33
	v_fma_f32 v35, v245, v35, v33
	v_lshlrev_b32_e32 v34, 16, v50
	v_sub_f32_e32 v50, v51, v0
	v_mul_f32_e32 v51, v247, v35
	v_mul_f32_e32 v52, v51, v51
	v_sub_f32_e32 v2, v53, v39
	v_lshlrev_b32_e32 v49, 16, v49
	v_mov_b32_dpp v52, v52 quad_perm:[1,0,3,2] row_mask:0xf bank_mask:0xf bound_ctrl:1
	v_fmac_f32_e32 v52, v51, v51
	v_add_f32_e32 v49, v251, v49
	s_nop 0
	v_add_f32_dpp v52, v52, v52 quad_perm:[2,3,0,1] row_mask:0xf bank_mask:0xf bound_ctrl:1
	v_mul_f32_e32 v49, 0xbfb8aa3b, v49
	v_exp_f32_e32 v49, v49
	v_add_f32_dpp v52, v52, v52 row_half_mirror row_mask:0xf bank_mask:0xf bound_ctrl:1
	v_add_f32_e32 v34, v250, v34
	v_mul_f32_e32 v34, 0xbfb8aa3b, v34
	v_add_f32_dpp v52, v52, v52 row_mirror row_mask:0xf bank_mask:0xf bound_ctrl:1
	v_add_f32_e32 v49, 1.0, v49
	v_rcp_f32_e32 v49, v49
	v_add_f32_dpp v52, v52, v52 row_bcast:15 row_mask:0xa bank_mask:0xf
	v_exp_f32_e32 v34, v34
	v_fma_f32 v2, v244, v2, v39
	v_add_f32_dpp v52, v52, v52 row_bcast:31 row_mask:0xc bank_mask:0xf
	v_add_f32_e32 v34, 1.0, v34
	v_readlane_b32 s0, v52, 63
	v_rcp_f32_e32 v34, v34
	v_fma_f32 v50, v246, v50, v0
	v_max_f32_e64 v52, s0, s0
	v_max_f32_e32 v52, 0x179abe15, v52
	v_rsq_f32_e32 v52, v52
	v_mul_f32_e32 v34, 0xbf1b4598, v34
	v_mul_f32_e32 v34, 0x3fb8aa3b, v34
	v_exp_f32_e32 v34, v34
	v_mul_f32_e32 v51, v51, v52
	v_add_f32_e32 v52, -1.0, v49
	v_fma_f32 v52, v248, v52, 1.0
	v_mul_f32_e32 v35, v35, v52
	v_mul_f32_e32 v52, v2, v35
	v_mul_f32_e32 v53, v249, v52
	ds_write2st64_b32 v129, v34, v51 offset1:32
	v_mul_f32_e32 v34, v49, v51
	v_mov_b32_dpp v53, v53 quad_perm:[1,0,3,2] row_mask:0xf bank_mask:0xf bound_ctrl:1
	v_fmac_f32_e32 v53, v249, v52
	ds_write2st64_b32 v129, v34, v35 offset0:64 offset1:96
	ds_write_b32 v129, v2 offset:32768
	ds_write_b32 v130, v50
	v_add_f32_dpp v52, v53, v53 quad_perm:[2,3,0,1] row_mask:0xf bank_mask:0xf bound_ctrl:1
	v_lshlrev_b32_e32 v2, 16, v48
	s_nop 0
	v_add_f32_dpp v52, v52, v52 row_half_mirror row_mask:0xf bank_mask:0xf bound_ctrl:1
	ds_write_b32 v131, v2
	s_nop 0
	v_add_f32_dpp v52, v52, v52 row_mirror row_mask:0xf bank_mask:0xf bound_ctrl:1
	s_nop 1
	v_add_f32_dpp v52, v52, v52 row_bcast:15 row_mask:0xa bank_mask:0xf
	s_nop 1
	v_add_f32_dpp v52, v52, v52 row_bcast:31 row_mask:0xc bank_mask:0xf
	s_nop 0
	v_readlane_b32 s43, v52, 63
	s_and_saveexec_b64 s[72:73], s[4:5]
	v_mov_b32_e32 v2, s62
	v_mov_b32_e32 v34, s43
	ds_write_b32 v2, v34
	s_or_b64 exec, exec, s[72:73]
	v_lshlrev_b32_e32 v34, 16, v27
	v_lshlrev_b32_e32 v27, 16, v28
	v_sub_f32_e32 v33, v33, v27
	v_fma_f32 v33, v245, v33, v27
	v_sub_f32_e32 v28, v39, v34
	v_mul_f32_e32 v39, v247, v33
	v_lshlrev_b32_e32 v35, 16, v46
	v_mul_f32_e32 v46, v39, v39
	v_lshlrev_b32_e32 v2, 16, v29
	v_lshlrev_b32_e32 v29, 16, v47
	v_mov_b32_dpp v46, v46 quad_perm:[1,0,3,2] row_mask:0xf bank_mask:0xf bound_ctrl:1
	v_fmac_f32_e32 v46, v39, v39
	v_add_f32_e32 v35, v251, v35
	s_nop 0
	v_add_f32_dpp v46, v46, v46 quad_perm:[2,3,0,1] row_mask:0xf bank_mask:0xf bound_ctrl:1
	v_mul_f32_e32 v35, 0xbfb8aa3b, v35
	v_exp_f32_e32 v35, v35
	v_add_f32_dpp v46, v46, v46 row_half_mirror row_mask:0xf bank_mask:0xf bound_ctrl:1
	v_add_f32_e32 v29, v250, v29
	v_mul_f32_e32 v29, 0xbfb8aa3b, v29
	v_add_f32_dpp v46, v46, v46 row_mirror row_mask:0xf bank_mask:0xf bound_ctrl:1
	v_add_f32_e32 v35, 1.0, v35
	v_rcp_f32_e32 v35, v35
	v_add_f32_dpp v46, v46, v46 row_bcast:15 row_mask:0xa bank_mask:0xf
	v_exp_f32_e32 v29, v29
	v_fma_f32 v28, v244, v28, v34
	v_add_f32_dpp v46, v46, v46 row_bcast:31 row_mask:0xc bank_mask:0xf
	v_add_f32_e32 v29, 1.0, v29
	v_readlane_b32 s0, v46, 63
	v_rcp_f32_e32 v29, v29
	v_sub_f32_e32 v0, v0, v2
	v_max_f32_e64 v46, s0, s0
	v_max_f32_e32 v46, 0x179abe15, v46
	v_rsq_f32_e32 v46, v46
	v_mul_f32_e32 v29, 0xbf1b4598, v29
	v_mul_f32_e32 v29, 0x3fb8aa3b, v29
	v_exp_f32_e32 v29, v29
	v_mul_f32_e32 v39, v39, v46
	v_add_f32_e32 v46, -1.0, v35
	v_fma_f32 v46, v248, v46, 1.0
	v_mul_f32_e32 v33, v33, v46
	v_mul_f32_e32 v46, v28, v33
	v_mul_f32_e32 v47, v249, v46
	v_fma_f32 v0, v246, v0, v2
	ds_write2st64_b32 v133, v29, v39 offset1:32
	v_mov_b32_dpp v47, v47 quad_perm:[1,0,3,2] row_mask:0xf bank_mask:0xf bound_ctrl:1
	v_fmac_f32_e32 v47, v249, v46
	v_mul_f32_e32 v29, v35, v39
	ds_write2st64_b32 v133, v29, v33 offset0:64 offset1:96
	ds_write_b32 v133, v28 offset:32768
	ds_write_b32 v134, v0
	v_add_f32_dpp v46, v47, v47 quad_perm:[2,3,0,1] row_mask:0xf bank_mask:0xf bound_ctrl:1
	v_lshlrev_b32_e32 v0, 16, v45
	s_nop 0
	v_add_f32_dpp v46, v46, v46 row_half_mirror row_mask:0xf bank_mask:0xf bound_ctrl:1
	ds_write_b32 v135, v0
	s_nop 0
	v_add_f32_dpp v46, v46, v46 row_mirror row_mask:0xf bank_mask:0xf bound_ctrl:1
	s_nop 1
	v_add_f32_dpp v46, v46, v46 row_bcast:15 row_mask:0xa bank_mask:0xf
	s_nop 1
	v_add_f32_dpp v46, v46, v46 row_bcast:31 row_mask:0xc bank_mask:0xf
	s_nop 0
	v_readlane_b32 s43, v46, 63
	s_and_saveexec_b64 s[72:73], s[4:5]
	v_mov_b32_e32 v0, s63
	v_mov_b32_e32 v28, s43
	ds_write_b32 v0, v28
	s_or_b64 exec, exec, s[72:73]
	v_lshlrev_b32_e32 v28, 16, v22
	v_lshlrev_b32_e32 v22, 16, v23
	v_sub_f32_e32 v27, v27, v22
	v_fma_f32 v27, v245, v27, v22
	v_mul_f32_e32 v33, v247, v27
	v_sub_f32_e32 v23, v34, v28
	v_mul_f32_e32 v34, v33, v33
	v_lshlrev_b32_e32 v29, 16, v43
	s_nop 0
	v_mov_b32_dpp v34, v34 quad_perm:[1,0,3,2] row_mask:0xf bank_mask:0xf bound_ctrl:1
	v_fmac_f32_e32 v34, v33, v33
	v_add_f32_e32 v29, v251, v29
	v_mul_f32_e32 v29, 0xbfb8aa3b, v29
	v_add_f32_dpp v34, v34, v34 quad_perm:[2,3,0,1] row_mask:0xf bank_mask:0xf bound_ctrl:1
	v_exp_f32_e32 v29, v29
	v_lshlrev_b32_e32 v0, 16, v24
	v_add_f32_dpp v34, v34, v34 row_half_mirror row_mask:0xf bank_mask:0xf bound_ctrl:1
	v_lshlrev_b32_e32 v24, 16, v44
	v_add_f32_e32 v29, 1.0, v29
	v_add_f32_dpp v34, v34, v34 row_mirror row_mask:0xf bank_mask:0xf bound_ctrl:1
	v_add_f32_e32 v24, v250, v24
	v_rcp_f32_e32 v29, v29
	v_add_f32_dpp v34, v34, v34 row_bcast:15 row_mask:0xa bank_mask:0xf
	v_mul_f32_e32 v24, 0xbfb8aa3b, v24
	v_exp_f32_e32 v24, v24
	v_add_f32_dpp v34, v34, v34 row_bcast:31 row_mask:0xc bank_mask:0xf
	v_fma_f32 v23, v244, v23, v28
	v_readlane_b32 s0, v34, 63
	v_add_f32_e32 v24, 1.0, v24
	v_rcp_f32_e32 v24, v24
	v_max_f32_e64 v34, s0, s0
	v_max_f32_e32 v34, 0x179abe15, v34
	v_rsq_f32_e32 v34, v34
	v_mul_f32_e32 v24, 0xbf1b4598, v24
	v_mul_f32_e32 v24, 0x3fb8aa3b, v24
	v_exp_f32_e32 v24, v24
	v_mul_f32_e32 v33, v33, v34
	v_add_f32_e32 v34, -1.0, v29
	v_fma_f32 v34, v248, v34, 1.0
	v_mul_f32_e32 v27, v27, v34
	v_mul_f32_e32 v34, v23, v27
	v_mul_f32_e32 v35, v249, v34
	v_sub_f32_e32 v2, v2, v0
	v_fma_f32 v2, v246, v2, v0
	v_mov_b32_dpp v35, v35 quad_perm:[1,0,3,2] row_mask:0xf bank_mask:0xf bound_ctrl:1
	v_fmac_f32_e32 v35, v249, v34
	ds_write2st64_b32 v137, v24, v33 offset1:32
	v_mul_f32_e32 v24, v29, v33
	v_add_f32_dpp v34, v35, v35 quad_perm:[2,3,0,1] row_mask:0xf bank_mask:0xf bound_ctrl:1
	ds_write2st64_b32 v137, v24, v27 offset0:64 offset1:96
	ds_write_b32 v137, v23 offset:32768
	ds_write_b32 v138, v2
	v_add_f32_dpp v34, v34, v34 row_half_mirror row_mask:0xf bank_mask:0xf bound_ctrl:1
	v_lshlrev_b32_e32 v2, 16, v40
	ds_write_b32 v139, v2
	v_add_f32_dpp v34, v34, v34 row_mirror row_mask:0xf bank_mask:0xf bound_ctrl:1
	s_nop 1
	v_add_f32_dpp v34, v34, v34 row_bcast:15 row_mask:0xa bank_mask:0xf
	s_nop 1
	v_add_f32_dpp v34, v34, v34 row_bcast:31 row_mask:0xc bank_mask:0xf
	s_nop 0
	v_readlane_b32 s43, v34, 63
	s_and_saveexec_b64 s[72:73], s[4:5]
	v_mov_b32_e32 v2, s64
	v_mov_b32_e32 v23, s43
	ds_write_b32 v2, v23
	s_or_b64 exec, exec, s[72:73]
	v_lshlrev_b32_e32 v23, 16, v13
	v_lshlrev_b32_e32 v13, 16, v14
	v_sub_f32_e32 v22, v22, v13
	v_fma_f32 v22, v245, v22, v13
	v_mul_f32_e32 v27, v247, v22
	v_sub_f32_e32 v14, v28, v23
	v_mul_f32_e32 v28, v27, v27
	v_lshlrev_b32_e32 v24, 16, v41
	s_nop 0
	v_mov_b32_dpp v28, v28 quad_perm:[1,0,3,2] row_mask:0xf bank_mask:0xf bound_ctrl:1
	v_fmac_f32_e32 v28, v27, v27
	v_add_f32_e32 v24, v251, v24
	v_mul_f32_e32 v24, 0xbfb8aa3b, v24
	v_add_f32_dpp v28, v28, v28 quad_perm:[2,3,0,1] row_mask:0xf bank_mask:0xf bound_ctrl:1
	v_exp_f32_e32 v24, v24
	v_lshlrev_b32_e32 v2, 16, v15
	v_add_f32_dpp v28, v28, v28 row_half_mirror row_mask:0xf bank_mask:0xf bound_ctrl:1
	v_lshlrev_b32_e32 v15, 16, v42
	v_add_f32_e32 v24, 1.0, v24
	v_add_f32_dpp v28, v28, v28 row_mirror row_mask:0xf bank_mask:0xf bound_ctrl:1
	v_add_f32_e32 v15, v250, v15
	v_rcp_f32_e32 v24, v24
	v_add_f32_dpp v28, v28, v28 row_bcast:15 row_mask:0xa bank_mask:0xf
	v_mul_f32_e32 v15, 0xbfb8aa3b, v15
	v_exp_f32_e32 v15, v15
	v_add_f32_dpp v28, v28, v28 row_bcast:31 row_mask:0xc bank_mask:0xf
	v_fma_f32 v14, v244, v14, v23
	v_readlane_b32 s0, v28, 63
	v_add_f32_e32 v15, 1.0, v15
	v_rcp_f32_e32 v15, v15
	v_max_f32_e64 v28, s0, s0
	v_max_f32_e32 v28, 0x179abe15, v28
	v_rsq_f32_e32 v28, v28
	v_mul_f32_e32 v15, 0xbf1b4598, v15
	v_mul_f32_e32 v15, 0x3fb8aa3b, v15
	v_exp_f32_e32 v15, v15
	v_mul_f32_e32 v27, v27, v28
	v_add_f32_e32 v28, -1.0, v24
	v_fma_f32 v28, v248, v28, 1.0
	v_mul_f32_e32 v22, v22, v28
	v_mul_f32_e32 v28, v14, v22
	v_mul_f32_e32 v29, v249, v28
	v_sub_f32_e32 v0, v0, v2
	v_fma_f32 v0, v246, v0, v2
	v_mov_b32_dpp v29, v29 quad_perm:[1,0,3,2] row_mask:0xf bank_mask:0xf bound_ctrl:1
	v_fmac_f32_e32 v29, v249, v28
	ds_write2st64_b32 v141, v15, v27 offset1:32
	v_mul_f32_e32 v15, v24, v27
	v_add_f32_dpp v28, v29, v29 quad_perm:[2,3,0,1] row_mask:0xf bank_mask:0xf bound_ctrl:1
	ds_write2st64_b32 v141, v15, v22 offset0:64 offset1:96
	ds_write_b32 v141, v14 offset:32768
	ds_write_b32 v142, v0
	v_add_f32_dpp v28, v28, v28 row_half_mirror row_mask:0xf bank_mask:0xf bound_ctrl:1
	v_lshlrev_b32_e32 v0, 16, v38
	ds_write_b32 v143, v0
	v_add_f32_dpp v28, v28, v28 row_mirror row_mask:0xf bank_mask:0xf bound_ctrl:1
	s_nop 1
	v_add_f32_dpp v28, v28, v28 row_bcast:15 row_mask:0xa bank_mask:0xf
	s_nop 1
	v_add_f32_dpp v28, v28, v28 row_bcast:31 row_mask:0xc bank_mask:0xf
	s_nop 0
	v_readlane_b32 s43, v28, 63
	s_and_saveexec_b64 s[72:73], s[4:5]
	v_mov_b32_e32 v0, s65
	v_mov_b32_e32 v14, s43
	ds_write_b32 v0, v14
	s_or_b64 exec, exec, s[72:73]
	v_lshlrev_b32_e32 v3, 16, v3
	v_sub_f32_e32 v13, v13, v3
	v_fma_f32 v13, v245, v13, v3
	v_lshlrev_b32_e32 v14, 16, v1
	v_mul_f32_e32 v22, v247, v13
	v_sub_f32_e32 v0, v23, v14
	v_mul_f32_e32 v23, v22, v22
	v_lshlrev_b32_e32 v15, 16, v36
	s_nop 0
	v_mov_b32_dpp v23, v23 quad_perm:[1,0,3,2] row_mask:0xf bank_mask:0xf bound_ctrl:1
	v_fmac_f32_e32 v23, v22, v22
	v_add_f32_e32 v15, v251, v15
	v_mul_f32_e32 v15, 0xbfb8aa3b, v15
	v_add_f32_dpp v23, v23, v23 quad_perm:[2,3,0,1] row_mask:0xf bank_mask:0xf bound_ctrl:1
	v_exp_f32_e32 v15, v15
	v_lshlrev_b32_e32 v1, 16, v12
	v_add_f32_dpp v23, v23, v23 row_half_mirror row_mask:0xf bank_mask:0xf bound_ctrl:1
	v_lshlrev_b32_e32 v12, 16, v37
	v_add_f32_e32 v15, 1.0, v15
	v_add_f32_dpp v23, v23, v23 row_mirror row_mask:0xf bank_mask:0xf bound_ctrl:1
	v_add_f32_e32 v12, v250, v12
	v_rcp_f32_e32 v15, v15
	v_add_f32_dpp v23, v23, v23 row_bcast:15 row_mask:0xa bank_mask:0xf
	v_mul_f32_e32 v12, 0xbfb8aa3b, v12
	v_exp_f32_e32 v12, v12
	v_add_f32_dpp v23, v23, v23 row_bcast:31 row_mask:0xc bank_mask:0xf
	v_fma_f32 v0, v244, v0, v14
	v_readlane_b32 s0, v23, 63
	v_add_f32_e32 v12, 1.0, v12
	v_rcp_f32_e32 v12, v12
	v_max_f32_e64 v23, s0, s0
	v_max_f32_e32 v23, 0x179abe15, v23
	v_rsq_f32_e32 v23, v23
	v_mul_f32_e32 v12, 0xbf1b4598, v12
	v_mul_f32_e32 v12, 0x3fb8aa3b, v12
	v_exp_f32_e32 v12, v12
	v_mul_f32_e32 v22, v22, v23
	v_add_f32_e32 v23, -1.0, v15
	v_fma_f32 v23, v248, v23, 1.0
	v_mul_f32_e32 v13, v13, v23
	v_mul_f32_e32 v23, v0, v13
	v_mul_f32_e32 v24, v249, v23
	v_sub_f32_e32 v2, v2, v1
	ds_write2st64_b32 v145, v12, v22 offset1:32
	v_mov_b32_dpp v24, v24 quad_perm:[1,0,3,2] row_mask:0xf bank_mask:0xf bound_ctrl:1
	v_fmac_f32_e32 v24, v249, v23
	v_mul_f32_e32 v12, v15, v22
	v_fma_f32 v2, v246, v2, v1
	v_add_f32_dpp v23, v24, v24 quad_perm:[2,3,0,1] row_mask:0xf bank_mask:0xf bound_ctrl:1
	ds_write2st64_b32 v145, v12, v13 offset0:64 offset1:96
	ds_write_b32 v145, v0 offset:32768
	ds_write_b32 v146, v2
	v_add_f32_dpp v23, v23, v23 row_half_mirror row_mask:0xf bank_mask:0xf bound_ctrl:1
	v_lshlrev_b32_e32 v0, 16, v32
	ds_write_b32 v147, v0
	v_add_f32_dpp v23, v23, v23 row_mirror row_mask:0xf bank_mask:0xf bound_ctrl:1
	s_nop 1
	v_add_f32_dpp v23, v23, v23 row_bcast:15 row_mask:0xa bank_mask:0xf
	s_nop 1
	v_add_f32_dpp v23, v23, v23 row_bcast:31 row_mask:0xc bank_mask:0xf
	s_nop 0
	v_readlane_b32 s43, v23, 63
	s_and_saveexec_b64 s[72:73], s[4:5]
	v_mov_b32_e32 v0, s58
	v_mov_b32_e32 v2, s43
	ds_write_b32 v0, v2
	s_or_b64 exec, exec, s[72:73]
	v_lshlrev_b32_e32 v2, 16, v20
	v_sub_f32_e32 v3, v3, v2
	v_fma_f32 v3, v245, v3, v2
	v_lshlrev_b32_e32 v12, 16, v19
	v_mul_f32_e32 v19, v247, v3
	v_mul_f32_e32 v20, v19, v19
	v_lshlrev_b32_e32 v0, 16, v21
	v_lshlrev_b32_e32 v15, 16, v30
	v_mov_b32_dpp v20, v20 quad_perm:[1,0,3,2] row_mask:0xf bank_mask:0xf bound_ctrl:1
	v_fmac_f32_e32 v20, v19, v19
	v_add_f32_e32 v15, v251, v15
	s_nop 0
	v_add_f32_dpp v20, v20, v20 quad_perm:[2,3,0,1] row_mask:0xf bank_mask:0xf bound_ctrl:1
	v_mul_f32_e32 v15, 0xbfb8aa3b, v15
	v_exp_f32_e32 v15, v15
	v_add_f32_dpp v20, v20, v20 row_half_mirror row_mask:0xf bank_mask:0xf bound_ctrl:1
	v_sub_f32_e32 v13, v14, v12
	v_lshlrev_b32_e32 v14, 16, v31
	v_add_f32_dpp v20, v20, v20 row_mirror row_mask:0xf bank_mask:0xf bound_ctrl:1
	v_add_f32_e32 v15, 1.0, v15
	v_add_f32_e32 v14, v250, v14
	v_add_f32_dpp v20, v20, v20 row_bcast:15 row_mask:0xa bank_mask:0xf
	v_rcp_f32_e32 v15, v15
	v_mul_f32_e32 v14, 0xbfb8aa3b, v14
	v_add_f32_dpp v20, v20, v20 row_bcast:31 row_mask:0xc bank_mask:0xf
	v_exp_f32_e32 v14, v14
	v_readlane_b32 s0, v20, 63
	v_fma_f32 v13, v244, v13, v12
	v_sub_f32_e32 v1, v1, v0
	v_max_f32_e64 v20, s0, s0
	v_max_f32_e32 v20, 0x179abe15, v20
	v_rsq_f32_e32 v20, v20
	v_add_f32_e32 v14, 1.0, v14
	v_rcp_f32_e32 v14, v14
	v_fma_f32 v1, v246, v1, v0
	v_mul_f32_e32 v19, v19, v20
	v_add_f32_e32 v20, -1.0, v15
	v_fma_f32 v20, v248, v20, 1.0
	v_mul_f32_e32 v3, v3, v20
	v_mul_f32_e32 v20, v13, v3
	v_mul_f32_e32 v21, v249, v20
	v_mul_f32_e32 v14, 0xbf1b4598, v14
	v_mul_f32_e32 v14, 0x3fb8aa3b, v14
	v_mov_b32_dpp v21, v21 quad_perm:[1,0,3,2] row_mask:0xf bank_mask:0xf bound_ctrl:1
	v_fmac_f32_e32 v21, v249, v20
	v_exp_f32_e32 v14, v14
	ds_write2st64_b32 v149, v14, v19 offset1:32
	v_add_f32_dpp v20, v21, v21 quad_perm:[2,3,0,1] row_mask:0xf bank_mask:0xf bound_ctrl:1
	v_mul_f32_e32 v14, v15, v19
	s_nop 0
	v_add_f32_dpp v20, v20, v20 row_half_mirror row_mask:0xf bank_mask:0xf bound_ctrl:1
	ds_write2st64_b32 v149, v14, v3 offset0:64 offset1:96
	ds_write_b32 v149, v13 offset:32768
	ds_write_b32 v150, v1
	v_add_f32_dpp v20, v20, v20 row_mirror row_mask:0xf bank_mask:0xf bound_ctrl:1
	v_lshlrev_b32_e32 v1, 16, v26
	ds_write_b32 v151, v1
	v_add_f32_dpp v20, v20, v20 row_bcast:15 row_mask:0xa bank_mask:0xf
	s_nop 1
	v_add_f32_dpp v20, v20, v20 row_bcast:31 row_mask:0xc bank_mask:0xf
	s_nop 0
	v_readlane_b32 s43, v20, 63
	s_and_saveexec_b64 s[72:73], s[4:5]
	v_mov_b32_e32 v1, s59
	v_mov_b32_e32 v3, s43
	ds_write_b32 v1, v3
	s_or_b64 exec, exec, s[72:73]
	v_lshlrev_b32_e32 v14, 16, v25
	v_add_f32_e32 v14, v250, v14
	v_mul_f32_e32 v14, 0xbfb8aa3b, v14
	v_exp_f32_e32 v14, v14
	v_lshlrev_b32_e32 v3, 16, v17
	s_waitcnt vmcnt(1)
	v_lshlrev_b32_e32 v11, 16, v11
	v_sub_f32_e32 v2, v2, v3
	v_add_f32_e32 v11, v251, v11
	v_fmac_f32_e32 v3, v245, v2
	v_add_f32_e32 v2, 1.0, v14
	v_mul_f32_e32 v11, 0xbfb8aa3b, v11
	v_rcp_f32_e32 v2, v2
	v_exp_f32_e32 v11, v11
	v_lshlrev_b32_e32 v13, 16, v18
	v_lshlrev_b32_e32 v1, 16, v16
	v_sub_f32_e32 v0, v0, v13
	v_sub_f32_e32 v12, v12, v1
	v_fmac_f32_e32 v13, v246, v0
	v_mul_f32_e32 v0, 0xbf1b4598, v2
	v_add_f32_e32 v2, 1.0, v11
	v_mul_f32_e32 v11, v247, v3
	v_fmac_f32_e32 v1, v244, v12
	v_mul_f32_e32 v12, v11, v11
	v_rcp_f32_e32 v2, v2
	s_nop 0
	v_mov_b32_dpp v12, v12 quad_perm:[1,0,3,2] row_mask:0xf bank_mask:0xf bound_ctrl:1
	v_fmac_f32_e32 v12, v11, v11
	v_mul_f32_e32 v0, 0x3fb8aa3b, v0
	v_exp_f32_e32 v0, v0
	v_add_f32_dpp v12, v12, v12 quad_perm:[2,3,0,1] row_mask:0xf bank_mask:0xf bound_ctrl:1
	s_nop 1
	v_add_f32_dpp v12, v12, v12 row_half_mirror row_mask:0xf bank_mask:0xf bound_ctrl:1
	s_nop 1
	v_add_f32_dpp v12, v12, v12 row_mirror row_mask:0xf bank_mask:0xf bound_ctrl:1
	s_nop 1
	v_add_f32_dpp v12, v12, v12 row_bcast:15 row_mask:0xa bank_mask:0xf
	s_nop 1
	v_add_f32_dpp v12, v12, v12 row_bcast:31 row_mask:0xc bank_mask:0xf
	s_nop 0
	v_readlane_b32 s0, v12, 63
	s_nop 1
	v_max_f32_e64 v12, s0, s0
	v_max_f32_e32 v12, 0x179abe15, v12
	v_rsq_f32_e32 v12, v12
	s_nop 0
	v_mul_f32_e32 v11, v11, v12
	v_add_f32_e32 v12, -1.0, v2
	v_fma_f32 v12, v248, v12, 1.0
	v_mul_f32_e32 v3, v3, v12
	v_mul_f32_e32 v12, v1, v3
	v_mul_f32_e32 v14, v249, v12
	ds_write2st64_b32 v153, v0, v11 offset1:32
	v_mul_f32_e32 v0, v2, v11
	v_mov_b32_dpp v14, v14 quad_perm:[1,0,3,2] row_mask:0xf bank_mask:0xf bound_ctrl:1
	v_fmac_f32_e32 v14, v249, v12
	ds_write2st64_b32 v153, v0, v3 offset0:64 offset1:96
	ds_write_b32 v153, v1 offset:32768
	ds_write_b32 v154, v13
	v_add_f32_dpp v12, v14, v14 quad_perm:[2,3,0,1] row_mask:0xf bank_mask:0xf bound_ctrl:1
	s_waitcnt vmcnt(0)
	v_lshlrev_b32_e32 v0, 16, v10
	v_add_f32_dpp v12, v12, v12 row_half_mirror row_mask:0xf bank_mask:0xf bound_ctrl:1
	ds_write_b32 v155, v0
	s_nop 0
	v_add_f32_dpp v12, v12, v12 row_mirror row_mask:0xf bank_mask:0xf bound_ctrl:1
	s_nop 1
	v_add_f32_dpp v12, v12, v12 row_bcast:15 row_mask:0xa bank_mask:0xf
	s_nop 1
	v_add_f32_dpp v12, v12, v12 row_bcast:31 row_mask:0xc bank_mask:0xf
	s_nop 0
	v_readlane_b32 s43, v12, 63
	s_and_saveexec_b64 s[72:73], s[4:5]
	v_mov_b32_e32 v0, s56
	v_mov_b32_e32 v1, s43
	ds_write_b32 v0, v1
	s_or_b64 exec, exec, s[72:73]
	v_add_co_u32_e32 v0, vcc, 0x1f000, v6
	s_mov_b32 s0, 0x22000
	s_nop 0
	v_addc_co_u32_e32 v1, vcc, 0, v7, vcc
	global_load_ushort v33, v[0:1], off
	global_load_ushort v34, v[0:1], off offset:1024
	global_load_ushort v24, v[0:1], off offset:2048
	v_add_co_u32_e32 v0, vcc, 0x20000, v6
	s_nop 1
	v_addc_co_u32_e32 v1, vcc, 0, v7, vcc
	global_load_ushort v35, v[0:1], off
	global_load_ushort v36, v[0:1], off offset:1024
	global_load_ushort v37, v[0:1], off offset:2048
	v_add_co_u32_e32 v0, vcc, 0x21000, v6
	s_waitcnt vmcnt(2)
	v_perm_b32 v221, v35, v33, s82
	v_addc_co_u32_e32 v1, vcc, 0, v7, vcc
	global_load_ushort v38, v[0:1], off
	global_load_ushort v39, v[0:1], off offset:1024
	global_load_ushort v40, v[0:1], off offset:2048
	v_add_co_u32_e32 v0, vcc, s0, v6
	s_mov_b32 s0, 0x24000
	s_nop 0
	v_addc_co_u32_e32 v1, vcc, 0, v7, vcc
	global_load_ushort v41, v[0:1], off
	global_load_ushort v42, v[0:1], off offset:1024
	global_load_ushort v43, v[0:1], off offset:2048
	v_add_co_u32_e32 v0, vcc, 0x23000, v6
	s_waitcnt vmcnt(7)
	v_perm_b32 v222, v36, v34, s82
	v_addc_co_u32_e32 v1, vcc, 0, v7, vcc
	global_load_ushort v44, v[0:1], off
	global_load_ushort v45, v[0:1], off offset:1024
	global_load_ushort v46, v[0:1], off offset:2048
	v_add_co_u32_e32 v0, vcc, s0, v6
	v_readlane_b32 s0, v255, 13
	s_nop 0
	v_addc_co_u32_e32 v1, vcc, 0, v7, vcc
	global_load_ushort v47, v[0:1], off
	global_load_ushort v48, v[0:1], off offset:1024
	global_load_ushort v49, v[0:1], off offset:2048
	v_add_co_u32_e32 v0, vcc, 0x25000, v6
	s_or_b32 s0, s84, s0
	s_nop 0
	v_addc_co_u32_e32 v1, vcc, 0, v7, vcc
	global_load_ushort v50, v[0:1], off
	global_load_ushort v51, v[0:1], off offset:1024
	global_load_ushort v52, v[0:1], off offset:2048
	v_add_co_u32_e32 v0, vcc, 0x26000, v6
	v_mad_u64_u32 v[22:23], s[50:51], s0, v236, v[8:9]
	s_nop 0
	v_addc_co_u32_e32 v1, vcc, 0, v7, vcc
	v_add_co_u32_e32 v6, vcc, 0x27000, v6
	v_add_u32_e32 v23, s42, v23
	s_nop 0
	v_addc_co_u32_e32 v7, vcc, 0, v7, vcc
	v_add_co_u32_e32 v12, vcc, s66, v22
	s_movk_i32 s0, 0x3000
	s_nop 0
	v_addc_co_u32_e32 v13, vcc, 0, v23, vcc
	v_add_co_u32_e32 v18, vcc, s67, v22
	global_load_ushort v53, v[0:1], off
	global_load_ushort v54, v[0:1], off offset:1024
	global_load_ushort v55, v[0:1], off offset:2048
	v_addc_co_u32_e32 v19, vcc, 0, v23, vcc
	v_add_co_u32_e32 v20, vcc, s0, v22
	s_movk_i32 s0, 0x4000
	s_nop 0
	v_addc_co_u32_e32 v21, vcc, 0, v23, vcc
	v_add_co_u32_e32 v30, vcc, s0, v22
	global_load_ushort v2, v[6:7], off
	global_load_ushort v1, v[6:7], off offset:1024
	global_load_ushort v0, v[6:7], off offset:2048
	v_addc_co_u32_e32 v31, vcc, 0, v23, vcc
	global_load_ushort v7, v[22:23], off
	global_load_ushort v6, v[22:23], off offset:1024
	global_load_ushort v3, v[22:23], off offset:2048
	global_load_ushort v8, v[22:23], off offset:3072
	global_load_ushort v11, v[18:19], off offset:-4096
	global_load_ushort v9, v[12:13], off offset:1024
	global_load_ushort v15, v[12:13], off offset:2048
	s_nop 0
	global_load_ushort v13, v[12:13], off offset:3072
	s_nop 0
	global_load_ushort v10, v[18:19], off
	global_load_ushort v16, v[18:19], off offset:1024
	global_load_ushort v14, v[18:19], off offset:2048
	global_load_ushort v12, v[18:19], off offset:3072
	global_load_ushort v17, v[30:31], off offset:-4096
	s_nop 0
	global_load_ushort v19, v[20:21], off offset:1024
	global_load_ushort v18, v[20:21], off offset:2048
	s_nop 0
	global_load_ushort v20, v[20:21], off offset:3072
	s_nop 0
	global_load_ushort v26, v[30:31], off
	global_load_ushort v25, v[30:31], off offset:1024
	global_load_ushort v28, v[30:31], off offset:2048
	global_load_ushort v27, v[30:31], off offset:3072
	v_add_co_u32_e32 v22, vcc, s68, v22
	s_waitcnt vmcnt(41)
	v_perm_b32 v21, v37, v24, s82
	v_addc_co_u32_e32 v23, vcc, 0, v23, vcc
	global_load_ushort v29, v[22:23], off
	global_load_ushort v32, v[22:23], off offset:1024
	global_load_ushort v31, v[22:23], off offset:2048
	global_load_ushort v30, v[22:23], off offset:3072
	s_waitcnt vmcnt(41)
	v_perm_b32 v223, v41, v38, s82
	s_waitcnt vmcnt(40)
	v_perm_b32 v226, v42, v39, s82
	s_waitcnt vmcnt(39)
	v_perm_b32 v22, v43, v40, s82
	s_waitcnt vmcnt(35)
	v_perm_b32 v224, v47, v44, s82
	s_waitcnt vmcnt(34)
	v_perm_b32 v227, v48, v45, s82
	s_waitcnt vmcnt(33)
	v_perm_b32 v23, v49, v46, s82
	s_waitcnt vmcnt(29)
	v_perm_b32 v225, v53, v50, s82
	s_waitcnt vmcnt(28)
	v_perm_b32 v242, v54, v51, s82
	s_waitcnt vmcnt(27)
	v_perm_b32 v24, v55, v52, s82
	s_branch .LBB0_2487

.LBB0_2490:
	s_mov_b64 s[72:73], -1
	s_and_b64 vcc, exec, s[20:21]
	s_cbranch_vccz .LBB0_2514
	s_cmp_eq_u32 s42, 0
	s_cselect_b64 s[72:73], -1, 0
	s_and_b64 vcc, exec, s[72:73]
	s_cbranch_vccnz .LBB0_2493
	s_add_i32 s0, s42, -1
	s_lshl_b32 s50, s0, 13
	s_and_b32 s50, s50, 0x2000
	s_add_i32 s72, s50, 0
	s_add_i32 s52, s72, 0x1a000
	s_add_i32 s72, s72, 0x1e000
	v_add_u32_e32 v0, s72, v124
	ds_read_b32 v1, v0
	s_and_b32 s1, s0, 0xff
	s_mulk_i32 s1, 0xab
	s_lshr_b32 s1, s1, 9
	s_mul_i32 s1, s1, 3
	s_sub_i32 s1, s0, s1
	s_waitcnt lgkmcnt(0)
	v_add_f32_dpp v6, v1, v1 quad_perm:[1,0,3,2] row_mask:0xf bank_mask:0xf bound_ctrl:1
	s_and_b32 s1, s1, 0xff
	s_lshl_b32 s43, s1, 13
	v_add_f32_dpp v6, v6, v6 quad_perm:[2,3,0,1] row_mask:0xf bank_mask:0xf bound_ctrl:1
	s_add_i32 s43, s43, 0
	s_nop 0
	v_add_f32_dpp v6, v6, v6 row_half_mirror row_mask:0xf bank_mask:0xf bound_ctrl:1
	s_add_i32 s43, s43, 0x14000
	s_lshl_b32 s0, s0, 5
	v_add_f32_dpp v6, v6, v6 row_mirror row_mask:0xf bank_mask:0xf bound_ctrl:1
	s_add_u32 vcc_lo, s84, s0
	s_addc_u32 vcc_hi, s85, 0
	v_add_f32_dpp v6, v6, v6 row_bcast:15 row_mask:0xa bank_mask:0xf
	s_lshl_b32 s0, s1, 7
	s_add_i32 s0, s41, s0
	v_add_f32_dpp v6, v6, v6 row_bcast:31 row_mask:0xc bank_mask:0xf
	v_mov_b32_e32 v0, s0
	v_readlane_b32 s0, v6, 63
	v_add_u32_e32 v2, s43, v124
	v_fmac_f32_e32 v1, s0, v237
	v_mul_f32_e32 v6, v1, v1
	v_add_u32_e32 v3, s52, v124
	ds_read_b32 v4, v0
	ds_read_b32 v2, v2
	ds_read_b32 v3, v3
	v_mov_b32_dpp v6, v6 quad_perm:[1,0,3,2] row_mask:0xf bank_mask:0xf bound_ctrl:1
	v_fmac_f32_e32 v6, v1, v1
	s_or_b64 s[50:51], vcc, s[38:39]
	s_lshl_b64 s[50:51], s[50:51], 10
	v_add_f32_dpp v6, v6, v6 quad_perm:[2,3,0,1] row_mask:0xf bank_mask:0xf bound_ctrl:1
	v_mov_b32_e32 v16, v225
	v_mov_b32_e32 v17, v224
	v_add_f32_dpp v6, v6, v6 row_half_mirror row_mask:0xf bank_mask:0xf bound_ctrl:1
	v_mov_b32_e32 v18, v223
	v_mov_b32_e32 v19, v221
	v_add_f32_dpp v6, v6, v6 row_mirror row_mask:0xf bank_mask:0xf bound_ctrl:1
	v_mov_b32_e32 v20, v242
	v_mov_b32_e32 v22, v227
	v_add_f32_dpp v6, v6, v6 row_bcast:15 row_mask:0xa bank_mask:0xf
	v_mov_b32_e32 v23, v226
	v_mov_b32_e32 v24, v222
	v_add_f32_dpp v6, v6, v6 row_bcast:31 row_mask:0xc bank_mask:0xf
	v_mov_b32_e32 v25, v218
	v_readlane_b32 s0, v6, 63
	v_mov_b32_e32 v26, v217
	v_mov_b32_e32 v27, v216
	v_fma_f32 v6, s0, v238, v234
	v_rsq_f32_e32 v6, v6
	v_mov_b32_e32 v29, v215
	v_mul_f32_e32 v1, v1, v6
	v_fma_f32 v1, v220, v1, v213
	s_waitcnt lgkmcnt(1)
	v_fmac_f32_e32 v1, v4, v2
	s_waitcnt lgkmcnt(0)
	v_mul_f32_e32 v1, v3, v1
	v_add_u32_e32 v2, s72, v128
	s_nop 0
	v_cvt_pk_bf16_f32 v1, v1, v5
	ds_read_b32 v4, v2
	v_add_u32_e32 v2, s43, v128
	v_add_u32_e32 v3, s52, v128
	ds_read_b32 v6, v2
	ds_read_b32 v7, v3
	ds_read_b32 v8, v0 offset:4
	s_waitcnt lgkmcnt(3)
	v_add_f32_dpp v2, v4, v4 quad_perm:[1,0,3,2] row_mask:0xf bank_mask:0xf bound_ctrl:1
	s_nop 1
	v_add_f32_dpp v2, v2, v2 quad_perm:[2,3,0,1] row_mask:0xf bank_mask:0xf bound_ctrl:1
	s_nop 1
	v_add_f32_dpp v2, v2, v2 row_half_mirror row_mask:0xf bank_mask:0xf bound_ctrl:1
	s_nop 1
	v_add_f32_dpp v2, v2, v2 row_mirror row_mask:0xf bank_mask:0xf bound_ctrl:1
	s_nop 1
	v_add_f32_dpp v2, v2, v2 row_bcast:15 row_mask:0xa bank_mask:0xf
	s_nop 1
	v_add_f32_dpp v2, v2, v2 row_bcast:31 row_mask:0xc bank_mask:0xf
	s_nop 0
	v_readlane_b32 s0, v2, 63
	s_nop 1
	v_fmac_f32_e32 v4, s0, v237
	v_mul_f32_e32 v2, v4, v4
	s_nop 1
	v_mov_b32_dpp v2, v2 quad_perm:[1,0,3,2] row_mask:0xf bank_mask:0xf bound_ctrl:1
	v_fmac_f32_e32 v2, v4, v4
	s_nop 1
	v_add_f32_dpp v2, v2, v2 quad_perm:[2,3,0,1] row_mask:0xf bank_mask:0xf bound_ctrl:1
	s_nop 1
	v_add_f32_dpp v2, v2, v2 row_half_mirror row_mask:0xf bank_mask:0xf bound_ctrl:1
	s_nop 1
	v_add_f32_dpp v2, v2, v2 row_mirror row_mask:0xf bank_mask:0xf bound_ctrl:1
	s_nop 1
	v_add_f32_dpp v2, v2, v2 row_bcast:15 row_mask:0xa bank_mask:0xf
	s_nop 1
	v_add_f32_dpp v2, v2, v2 row_bcast:31 row_mask:0xc bank_mask:0xf
	s_nop 0
	v_readlane_b32 s0, v2, 63
	s_nop 1
	v_fma_f32 v2, s0, v238, v234
	v_rsq_f32_e32 v9, v2
	v_lshl_add_u64 v[2:3], v[84:85], 0, s[50:51]
	global_store_short v[2:3], v1, off
	v_add_u32_e32 v2, s72, v132
	v_mul_f32_e32 v1, v4, v9
	v_fma_f32 v1, v220, v1, v213
	s_waitcnt lgkmcnt(0)
	v_fmac_f32_e32 v1, v8, v6
	v_mul_f32_e32 v1, v7, v1
	s_nop 0
	v_cvt_pk_bf16_f32 v1, v1, v5
	ds_read_b32 v4, v2
	v_add_u32_e32 v2, s43, v132
	v_add_u32_e32 v3, s52, v132
	ds_read_b32 v6, v2
	ds_read_b32 v7, v3
	ds_read_b32 v8, v0 offset:8
	s_waitcnt lgkmcnt(3)
	v_add_f32_dpp v2, v4, v4 quad_perm:[1,0,3,2] row_mask:0xf bank_mask:0xf bound_ctrl:1
	s_or_b64 s[50:51], vcc, s[96:97]
	s_lshl_b64 s[50:51], s[50:51], 10
	v_add_f32_dpp v2, v2, v2 quad_perm:[2,3,0,1] row_mask:0xf bank_mask:0xf bound_ctrl:1
	s_nop 1
	v_add_f32_dpp v2, v2, v2 row_half_mirror row_mask:0xf bank_mask:0xf bound_ctrl:1
	s_nop 1
	v_add_f32_dpp v2, v2, v2 row_mirror row_mask:0xf bank_mask:0xf bound_ctrl:1
	s_nop 1
	v_add_f32_dpp v2, v2, v2 row_bcast:15 row_mask:0xa bank_mask:0xf
	s_nop 1
	v_add_f32_dpp v2, v2, v2 row_bcast:31 row_mask:0xc bank_mask:0xf
	s_nop 0
	v_readlane_b32 s0, v2, 63
	s_nop 1
	v_fmac_f32_e32 v4, s0, v237
	v_mul_f32_e32 v2, v4, v4
	s_nop 1
	v_mov_b32_dpp v2, v2 quad_perm:[1,0,3,2] row_mask:0xf bank_mask:0xf bound_ctrl:1
	v_fmac_f32_e32 v2, v4, v4
	s_nop 1
	v_add_f32_dpp v2, v2, v2 quad_perm:[2,3,0,1] row_mask:0xf bank_mask:0xf bound_ctrl:1
	s_nop 1
	v_add_f32_dpp v2, v2, v2 row_half_mirror row_mask:0xf bank_mask:0xf bound_ctrl:1
	s_nop 1
	v_add_f32_dpp v2, v2, v2 row_mirror row_mask:0xf bank_mask:0xf bound_ctrl:1
	s_nop 1
	v_add_f32_dpp v2, v2, v2 row_bcast:15 row_mask:0xa bank_mask:0xf
	s_nop 1
	v_add_f32_dpp v2, v2, v2 row_bcast:31 row_mask:0xc bank_mask:0xf
	s_nop 0
	v_readlane_b32 s0, v2, 63
	s_nop 1
	v_fma_f32 v2, s0, v238, v234
	v_rsq_f32_e32 v9, v2
	v_lshl_add_u64 v[2:3], v[84:85], 0, s[50:51]
	global_store_short v[2:3], v1, off
	v_add_u32_e32 v2, s72, v136
	v_mul_f32_e32 v1, v4, v9
	v_fma_f32 v1, v220, v1, v213
	s_waitcnt lgkmcnt(0)
	v_fmac_f32_e32 v1, v8, v6
	v_mul_f32_e32 v1, v7, v1
	s_nop 0
	v_cvt_pk_bf16_f32 v1, v1, v5
	ds_read_b32 v4, v2
	v_add_u32_e32 v2, s43, v136
	v_add_u32_e32 v3, s52, v136
	ds_read_b32 v6, v2
	ds_read_b32 v7, v3
	ds_read_b32 v8, v0 offset:12
	s_waitcnt lgkmcnt(3)
	v_add_f32_dpp v2, v4, v4 quad_perm:[1,0,3,2] row_mask:0xf bank_mask:0xf bound_ctrl:1
	s_or_b64 s[50:51], vcc, s[48:49]
	s_lshl_b64 s[50:51], s[50:51], 10
	v_add_f32_dpp v2, v2, v2 quad_perm:[2,3,0,1] row_mask:0xf bank_mask:0xf bound_ctrl:1
	s_nop 1
	v_add_f32_dpp v2, v2, v2 row_half_mirror row_mask:0xf bank_mask:0xf bound_ctrl:1
	s_nop 1
	v_add_f32_dpp v2, v2, v2 row_mirror row_mask:0xf bank_mask:0xf bound_ctrl:1
	s_nop 1
	v_add_f32_dpp v2, v2, v2 row_bcast:15 row_mask:0xa bank_mask:0xf
	s_nop 1
	v_add_f32_dpp v2, v2, v2 row_bcast:31 row_mask:0xc bank_mask:0xf
	s_nop 0
	v_readlane_b32 s0, v2, 63
	s_nop 1
	v_fmac_f32_e32 v4, s0, v237
	v_mul_f32_e32 v2, v4, v4
	s_nop 1
	v_mov_b32_dpp v2, v2 quad_perm:[1,0,3,2] row_mask:0xf bank_mask:0xf bound_ctrl:1
	v_fmac_f32_e32 v2, v4, v4
	s_nop 1
	v_add_f32_dpp v2, v2, v2 quad_perm:[2,3,0,1] row_mask:0xf bank_mask:0xf bound_ctrl:1
	s_nop 1
	v_add_f32_dpp v2, v2, v2 row_half_mirror row_mask:0xf bank_mask:0xf bound_ctrl:1
	s_nop 1
	v_add_f32_dpp v2, v2, v2 row_mirror row_mask:0xf bank_mask:0xf bound_ctrl:1
	s_nop 1
	v_add_f32_dpp v2, v2, v2 row_bcast:15 row_mask:0xa bank_mask:0xf
	s_nop 1
	v_add_f32_dpp v2, v2, v2 row_bcast:31 row_mask:0xc bank_mask:0xf
	s_nop 0
	v_readlane_b32 s0, v2, 63
	s_nop 1
	v_fma_f32 v2, s0, v238, v234
	v_rsq_f32_e32 v9, v2
	v_lshl_add_u64 v[2:3], v[84:85], 0, s[50:51]
	global_store_short v[2:3], v1, off
	v_add_u32_e32 v2, s72, v140
	v_mul_f32_e32 v1, v4, v9
	v_fma_f32 v1, v220, v1, v213
	s_waitcnt lgkmcnt(0)
	v_fmac_f32_e32 v1, v8, v6
	v_mul_f32_e32 v1, v7, v1
	s_nop 0
	v_cvt_pk_bf16_f32 v1, v1, v5
	ds_read_b32 v4, v2
	v_add_u32_e32 v2, s43, v140
	v_add_u32_e32 v3, s52, v140
	ds_read_b32 v6, v2
	ds_read_b32 v7, v3
	ds_read_b32 v8, v0 offset:16
	s_waitcnt lgkmcnt(3)
	v_add_f32_dpp v2, v4, v4 quad_perm:[1,0,3,2] row_mask:0xf bank_mask:0xf bound_ctrl:1
	s_or_b64 s[50:51], vcc, s[60:61]
	s_lshl_b64 s[50:51], s[50:51], 10
	v_add_f32_dpp v2, v2, v2 quad_perm:[2,3,0,1] row_mask:0xf bank_mask:0xf bound_ctrl:1
	s_nop 1
	v_add_f32_dpp v2, v2, v2 row_half_mirror row_mask:0xf bank_mask:0xf bound_ctrl:1
	s_nop 1
	v_add_f32_dpp v2, v2, v2 row_mirror row_mask:0xf bank_mask:0xf bound_ctrl:1
	s_nop 1
	v_add_f32_dpp v2, v2, v2 row_bcast:15 row_mask:0xa bank_mask:0xf
	s_nop 1
	v_add_f32_dpp v2, v2, v2 row_bcast:31 row_mask:0xc bank_mask:0xf
	s_nop 0
	v_readlane_b32 s0, v2, 63
	s_nop 1
	v_fmac_f32_e32 v4, s0, v237
	v_mul_f32_e32 v2, v4, v4
	s_nop 1
	v_mov_b32_dpp v2, v2 quad_perm:[1,0,3,2] row_mask:0xf bank_mask:0xf bound_ctrl:1
	v_fmac_f32_e32 v2, v4, v4
	s_nop 1
	v_add_f32_dpp v2, v2, v2 quad_perm:[2,3,0,1] row_mask:0xf bank_mask:0xf bound_ctrl:1
	s_nop 1
	v_add_f32_dpp v2, v2, v2 row_half_mirror row_mask:0xf bank_mask:0xf bound_ctrl:1
	s_nop 1
	v_add_f32_dpp v2, v2, v2 row_mirror row_mask:0xf bank_mask:0xf bound_ctrl:1
	s_nop 1
	v_add_f32_dpp v2, v2, v2 row_bcast:15 row_mask:0xa bank_mask:0xf
	s_nop 1
	v_add_f32_dpp v2, v2, v2 row_bcast:31 row_mask:0xc bank_mask:0xf
	s_nop 0
	v_readlane_b32 s0, v2, 63
	s_nop 1
	v_fma_f32 v2, s0, v238, v234
	v_rsq_f32_e32 v9, v2
	v_lshl_add_u64 v[2:3], v[84:85], 0, s[50:51]
	global_store_short v[2:3], v1, off
	v_add_u32_e32 v2, s72, v144
	v_mul_f32_e32 v1, v4, v9
	v_fma_f32 v1, v220, v1, v213
	s_waitcnt lgkmcnt(0)
	v_fmac_f32_e32 v1, v8, v6
	v_mul_f32_e32 v1, v7, v1
	s_nop 0
	v_cvt_pk_bf16_f32 v1, v1, v5
	ds_read_b32 v4, v2
	v_add_u32_e32 v2, s43, v144
	v_add_u32_e32 v3, s52, v144
	ds_read_b32 v6, v2
	ds_read_b32 v7, v3
	ds_read_b32 v8, v0 offset:20
	s_waitcnt lgkmcnt(3)
	v_add_f32_dpp v2, v4, v4 quad_perm:[1,0,3,2] row_mask:0xf bank_mask:0xf bound_ctrl:1
	s_or_b64 s[50:51], vcc, s[54:55]
	s_lshl_b64 s[50:51], s[50:51], 10
	v_add_f32_dpp v2, v2, v2 quad_perm:[2,3,0,1] row_mask:0xf bank_mask:0xf bound_ctrl:1
	s_nop 1
	v_add_f32_dpp v2, v2, v2 row_half_mirror row_mask:0xf bank_mask:0xf bound_ctrl:1
	s_nop 1
	v_add_f32_dpp v2, v2, v2 row_mirror row_mask:0xf bank_mask:0xf bound_ctrl:1
	s_nop 1
	v_add_f32_dpp v2, v2, v2 row_bcast:15 row_mask:0xa bank_mask:0xf
	s_nop 1
	v_add_f32_dpp v2, v2, v2 row_bcast:31 row_mask:0xc bank_mask:0xf
	s_nop 0
	v_readlane_b32 s0, v2, 63
	s_nop 1
	v_fmac_f32_e32 v4, s0, v237
	v_mul_f32_e32 v2, v4, v4
	s_nop 1
	v_mov_b32_dpp v2, v2 quad_perm:[1,0,3,2] row_mask:0xf bank_mask:0xf bound_ctrl:1
	v_fmac_f32_e32 v2, v4, v4
	s_nop 1
	v_add_f32_dpp v2, v2, v2 quad_perm:[2,3,0,1] row_mask:0xf bank_mask:0xf bound_ctrl:1
	s_nop 1
	v_add_f32_dpp v2, v2, v2 row_half_mirror row_mask:0xf bank_mask:0xf bound_ctrl:1
	s_nop 1
	v_add_f32_dpp v2, v2, v2 row_mirror row_mask:0xf bank_mask:0xf bound_ctrl:1
	s_nop 1
	v_add_f32_dpp v2, v2, v2 row_bcast:15 row_mask:0xa bank_mask:0xf
	s_nop 1
	v_add_f32_dpp v2, v2, v2 row_bcast:31 row_mask:0xc bank_mask:0xf
	s_nop 0
	v_readlane_b32 s0, v2, 63
	s_nop 1
	v_fma_f32 v2, s0, v238, v234
	v_rsq_f32_e32 v9, v2
	v_lshl_add_u64 v[2:3], v[84:85], 0, s[50:51]
	global_store_short v[2:3], v1, off
	v_add_u32_e32 v2, s72, v148
	v_mul_f32_e32 v1, v4, v9
	v_fma_f32 v1, v220, v1, v213
	s_waitcnt lgkmcnt(0)
; __device__ __forceinline__ void phase_rwkv(KP P, int l_, unsigned char* shm) {
;     ...
;                 if (c >= 1) RW_POST(c - 1);
	v_fmac_f32_e32 v1, v8, v6
	v_mul_f32_e32 v1, v7, v1
	s_nop 0
	v_cvt_pk_bf16_f32 v1, v1, v5
	ds_read_b32 v4, v2
	v_add_u32_e32 v2, s43, v148
	v_add_u32_e32 v3, s52, v148
	ds_read_b32 v6, v2
	ds_read_b32 v7, v3
	ds_read_b32 v8, v0 offset:24
	s_waitcnt lgkmcnt(3)
	v_add_f32_dpp v2, v4, v4 quad_perm:[1,0,3,2] row_mask:0xf bank_mask:0xf bound_ctrl:1
	s_or_b64 s[50:51], vcc, s[74:75]
	s_lshl_b64 s[50:51], s[50:51], 10
	v_add_f32_dpp v2, v2, v2 quad_perm:[2,3,0,1] row_mask:0xf bank_mask:0xf bound_ctrl:1
	s_nop 1
	v_add_f32_dpp v2, v2, v2 row_half_mirror row_mask:0xf bank_mask:0xf bound_ctrl:1
	s_nop 1
	v_add_f32_dpp v2, v2, v2 row_mirror row_mask:0xf bank_mask:0xf bound_ctrl:1
	s_nop 1
	v_add_f32_dpp v2, v2, v2 row_bcast:15 row_mask:0xa bank_mask:0xf
	s_nop 1
	v_add_f32_dpp v2, v2, v2 row_bcast:31 row_mask:0xc bank_mask:0xf
	s_nop 0
	v_readlane_b32 s0, v2, 63
	s_nop 1
	v_fmac_f32_e32 v4, s0, v237
	v_mul_f32_e32 v2, v4, v4
	s_nop 1
	v_mov_b32_dpp v2, v2 quad_perm:[1,0,3,2] row_mask:0xf bank_mask:0xf bound_ctrl:1
	v_fmac_f32_e32 v2, v4, v4
	s_nop 1
	v_add_f32_dpp v2, v2, v2 quad_perm:[2,3,0,1] row_mask:0xf bank_mask:0xf bound_ctrl:1
	s_nop 1
	v_add_f32_dpp v2, v2, v2 row_half_mirror row_mask:0xf bank_mask:0xf bound_ctrl:1
	s_nop 1
	v_add_f32_dpp v2, v2, v2 row_mirror row_mask:0xf bank_mask:0xf bound_ctrl:1
	s_nop 1
	v_add_f32_dpp v2, v2, v2 row_bcast:15 row_mask:0xa bank_mask:0xf
	s_nop 1
	v_add_f32_dpp v2, v2, v2 row_bcast:31 row_mask:0xc bank_mask:0xf
	s_nop 0
	v_readlane_b32 s0, v2, 63
	s_nop 1
	v_fma_f32 v2, s0, v238, v234
	v_rsq_f32_e32 v9, v2
	v_lshl_add_u64 v[2:3], v[84:85], 0, s[50:51]
	global_store_short v[2:3], v1, off
	s_or_b64 s[50:51], vcc, s[76:77]
	v_mul_f32_e32 v1, v4, v9
	v_fma_f32 v1, v220, v1, v213
	s_waitcnt lgkmcnt(0)
	v_fmac_f32_e32 v1, v8, v6
	v_mul_f32_e32 v1, v7, v1
	s_nop 0
	v_cvt_pk_bf16_f32 v2, v1, v5
	v_add_u32_e32 v1, s72, v152
	ds_read_b32 v3, v1
	v_add_u32_e32 v1, s43, v152
	v_add_u32_e32 v4, s52, v152
	ds_read_b32 v6, v1
	ds_read_b32 v4, v4
	ds_read_b32 v7, v0 offset:28
	s_waitcnt lgkmcnt(3)
	v_add_f32_dpp v0, v3, v3 quad_perm:[1,0,3,2] row_mask:0xf bank_mask:0xf bound_ctrl:1
	s_lshl_b64 s[50:51], s[50:51], 10
	s_nop 0
	v_add_f32_dpp v0, v0, v0 quad_perm:[2,3,0,1] row_mask:0xf bank_mask:0xf bound_ctrl:1
	s_nop 1
	v_add_f32_dpp v0, v0, v0 row_half_mirror row_mask:0xf bank_mask:0xf bound_ctrl:1
	s_nop 1
	v_add_f32_dpp v0, v0, v0 row_mirror row_mask:0xf bank_mask:0xf bound_ctrl:1
	s_nop 1
	v_add_f32_dpp v0, v0, v0 row_bcast:15 row_mask:0xa bank_mask:0xf
	s_nop 1
	v_add_f32_dpp v0, v0, v0 row_bcast:31 row_mask:0xc bank_mask:0xf
	s_nop 0
	v_readlane_b32 s0, v0, 63
	s_nop 1
	v_fmac_f32_e32 v3, s0, v237
	v_mul_f32_e32 v0, v3, v3
	s_nop 1
	v_mov_b32_dpp v0, v0 quad_perm:[1,0,3,2] row_mask:0xf bank_mask:0xf bound_ctrl:1
	v_fmac_f32_e32 v0, v3, v3
	s_nop 1
	v_add_f32_dpp v0, v0, v0 quad_perm:[2,3,0,1] row_mask:0xf bank_mask:0xf bound_ctrl:1
	s_nop 1
	v_add_f32_dpp v0, v0, v0 row_half_mirror row_mask:0xf bank_mask:0xf bound_ctrl:1
	s_nop 1
	v_add_f32_dpp v0, v0, v0 row_mirror row_mask:0xf bank_mask:0xf bound_ctrl:1
	s_nop 1
	v_add_f32_dpp v0, v0, v0 row_bcast:15 row_mask:0xa bank_mask:0xf
	s_nop 1
	v_add_f32_dpp v0, v0, v0 row_bcast:31 row_mask:0xc bank_mask:0xf
	s_nop 0
	v_readlane_b32 s0, v0, 63
	s_nop 1
	v_fma_f32 v0, s0, v238, v234
	v_rsq_f32_e32 v8, v0
	v_lshl_add_u64 v[0:1], v[84:85], 0, s[50:51]
	global_store_short v[0:1], v2, off
	s_or_b64 s[50:51], vcc, s[80:81]
	v_mul_f32_e32 v0, v3, v8
	v_fma_f32 v0, v220, v0, v213
	s_waitcnt lgkmcnt(0)
	v_fmac_f32_e32 v0, v7, v6
	s_lshl_b64 s[50:51], s[50:51], 10
	v_mul_f32_e32 v0, v4, v0
	s_cmp_lg_u32 s42, 63
	s_nop 0
	v_cvt_pk_bf16_f32 v2, v0, v5
	v_lshl_add_u64 v[0:1], v[84:85], 0, s[50:51]
	s_cselect_b64 s[72:73], -1, 0
	global_store_short v[0:1], v2, off
	s_branch .LBB0_2494

.Lrw_nopack:
	s_andn2_b64 vcc, exec, s[72:73]
	v_mov_b32_e32 v0, v176
	v_mov_b32_e32 v1, v214
	v_mov_b32_e32 v2, v219
	v_mov_b32_e32 v3, v177
	v_mov_b32_e32 v9, v190
	v_mov_b32_e32 v10, v191
	v_mov_b32_e32 v11, v192
	v_mov_b32_e32 v21, v193
	v_mov_b32_e32 v28, v194
	v_mov_b32_e32 v35, v195
	v_mov_b32_e32 v38, v196
	v_mov_b32_e32 v4, v197
	v_mov_b32_e32 v8, v198
	v_mov_b32_e32 v12, v199
	v_mov_b32_e32 v13, v200
	v_mov_b32_e32 v30, v201
	v_mov_b32_e32 v31, v202
	v_mov_b32_e32 v33, v203
	v_mov_b32_e32 v37, v204
	v_mov_b32_e32 v6, v205
	v_mov_b32_e32 v7, v206
	v_mov_b32_e32 v14, v207
	v_mov_b32_e32 v15, v208
	v_mov_b32_e32 v32, v209
	v_mov_b32_e32 v34, v210
	v_mov_b32_e32 v36, v211
	v_mov_b32_e32 v39, v212
	s_cbranch_vccnz .LBB0_2513
	v_and_b32_e32 v2, 0xffff0000, v222
	v_lshlrev_b32_e32 v3, 16, v222
	v_sub_f32_e32 v3, v3, v2
	v_fma_f32 v3, v245, v3, v2
	v_mul_f32_e32 v9, v247, v3
	v_mul_f32_e32 v10, v9, v9
	s_add_i32 s0, s42, 1
	s_and_b32 s1, s0, 1
	v_mov_b32_dpp v10, v10 quad_perm:[1,0,3,2] row_mask:0xf bank_mask:0xf bound_ctrl:1
	v_fmac_f32_e32 v10, v9, v9
	s_mul_i32 s43, s1, 0xa000
	s_add_i32 s52, s43, 0
	v_add_f32_dpp v10, v10, v10 quad_perm:[2,3,0,1] row_mask:0xf bank_mask:0xf bound_ctrl:1
	s_mul_hi_u32 s43, s0, 0xaaaaaaab
	v_lshlrev_b32_e32 v8, 16, v197
	v_add_f32_dpp v10, v10, v10 row_half_mirror row_mask:0xf bank_mask:0xf bound_ctrl:1
	s_lshr_b32 s43, s43, 1
	s_nop 0
	v_add_f32_dpp v10, v10, v10 row_mirror row_mask:0xf bank_mask:0xf bound_ctrl:1
	v_add_f32_e32 v8, v251, v8
	s_mul_i32 s43, s43, 3
	v_add_f32_dpp v10, v10, v10 row_bcast:15 row_mask:0xa bank_mask:0xf
	v_mul_f32_e32 v8, 0xbfb8aa3b, v8
	s_sub_i32 s0, s0, s43
	v_exp_f32_e32 v8, v8
	v_add_f32_dpp v10, v10, v10 row_bcast:31 row_mask:0xc bank_mask:0xf
	s_lshl_b32 s43, s0, 13
	s_lshl_b32 s0, s0, 7
	s_add_i32 vcc_lo, s43, 0
	s_add_i32 s43, s0, 0
	v_readlane_b32 s0, v10, 63
	v_add_f32_e32 v8, 1.0, v8
	v_rcp_f32_e32 v8, v8
	v_max_f32_e64 v10, s0, s0
	v_max_f32_e32 v10, 0x179abe15, v10
	v_rsq_f32_e32 v10, v10
	v_lshlrev_b32_e32 v6, 16, v205
	v_add_f32_e32 v6, v250, v6
	v_mul_f32_e32 v6, 0xbfb8aa3b, v6
	v_and_b32_e32 v4, 0xffff0000, v221
	v_lshlrev_b32_e32 v1, 16, v221
	v_exp_f32_e32 v6, v6
	v_mul_f32_e32 v9, v9, v10
	v_add_f32_e32 v10, -1.0, v8
	v_sub_f32_e32 v1, v1, v4
	v_fma_f32 v10, v248, v10, 1.0
	v_fma_f32 v1, v244, v1, v4
	v_mul_f32_e32 v3, v10, v3
	v_mul_f32_e32 v10, v1, v3
	v_add_f32_e32 v6, 1.0, v6
	v_mul_f32_e32 v11, v249, v10
	v_rcp_f32_e32 v6, v6
	s_lshl_b32 s1, s1, 13
	v_mov_b32_dpp v11, v11 quad_perm:[1,0,3,2] row_mask:0xf bank_mask:0xf bound_ctrl:1
	v_fmac_f32_e32 v11, v249, v10
	v_mul_f32_e32 v6, 0xbf1b4598, v6
	v_mul_f32_e32 v6, 0x3fb8aa3b, v6
	v_add_f32_dpp v10, v11, v11 quad_perm:[2,3,0,1] row_mask:0xf bank_mask:0xf bound_ctrl:1
	v_exp_f32_e32 v6, v6
	s_nop 0
	v_add_f32_dpp v10, v10, v10 row_half_mirror row_mask:0xf bank_mask:0xf bound_ctrl:1
	v_and_b32_e32 v0, 0xffff0000, v215
	v_lshlrev_b32_e32 v7, 16, v215
	v_add_f32_dpp v10, v10, v10 row_mirror row_mask:0xf bank_mask:0xf bound_ctrl:1
	s_add_i32 vcc_lo, vcc_lo, 0x14000
	s_add_i32 vcc_hi, s1, 0
	v_add_f32_dpp v10, v10, v10 row_bcast:15 row_mask:0xa bank_mask:0xf
	v_sub_f32_e32 v7, v7, v0
	s_add_i32 vcc_hi, vcc_hi, 0x1a000
	v_add_f32_dpp v10, v10, v10 row_bcast:31 row_mask:0xc bank_mask:0xf
	v_fma_f32 v7, v246, v7, v0
	v_readlane_b32 s50, v10, 63
	v_add_u32_e32 v10, s52, v124
	ds_write2st64_b32 v10, v6, v9 offset1:32
	v_mul_f32_e32 v6, v8, v9
	ds_write2st64_b32 v10, v6, v3 offset0:64 offset1:96
	ds_write_b32 v10, v1 offset:32768
	v_add_u32_e32 v1, vcc_lo, v124
	s_add_i32 s43, s43, 0x22000
	ds_write_b32 v1, v7
	v_lshlrev_b32_e32 v1, 16, v177
	v_add_u32_e32 v3, vcc_hi, v124
	ds_write_b32 v3, v1
	s_and_saveexec_b64 s[72:73], s[4:5]
	s_lshl_b32 s0, s38, 2
	s_add_i32 s0, s43, s0
	v_mov_b32_e32 v1, s0
	v_mov_b32_e32 v3, s50
	ds_write_b32 v1, v3
	s_or_b64 exec, exec, s[72:73]
	v_lshlrev_b32_e32 v3, 16, v226
	v_sub_f32_e32 v2, v2, v3
	v_fma_f32 v2, v245, v2, v3
	v_mul_f32_e32 v9, v247, v2
	v_mul_f32_e32 v10, v9, v9
	v_lshlrev_b32_e32 v8, 16, v198
	s_nop 0
	v_mov_b32_dpp v10, v10 quad_perm:[1,0,3,2] row_mask:0xf bank_mask:0xf bound_ctrl:1
	v_fmac_f32_e32 v10, v9, v9
	v_add_f32_e32 v8, v251, v8
	v_mul_f32_e32 v8, 0xbfb8aa3b, v8
	v_add_f32_dpp v10, v10, v10 quad_perm:[2,3,0,1] row_mask:0xf bank_mask:0xf bound_ctrl:1
	v_exp_f32_e32 v8, v8
	v_lshlrev_b32_e32 v7, 16, v206
	v_add_f32_dpp v10, v10, v10 row_half_mirror row_mask:0xf bank_mask:0xf bound_ctrl:1
	v_add_f32_e32 v7, v250, v7
	v_add_f32_e32 v8, 1.0, v8
	v_add_f32_dpp v10, v10, v10 row_mirror row_mask:0xf bank_mask:0xf bound_ctrl:1
	v_rcp_f32_e32 v8, v8
	v_mul_f32_e32 v7, 0xbfb8aa3b, v7
	v_add_f32_dpp v10, v10, v10 row_bcast:15 row_mask:0xa bank_mask:0xf
	v_lshlrev_b32_e32 v6, 16, v223
	v_exp_f32_e32 v7, v7
	v_add_f32_dpp v10, v10, v10 row_bcast:31 row_mask:0xc bank_mask:0xf
	v_sub_f32_e32 v4, v4, v6
	v_readlane_b32 s0, v10, 63
	v_fma_f32 v4, v244, v4, v6
	v_add_f32_e32 v7, 1.0, v7
	v_max_f32_e64 v10, s0, s0
	v_max_f32_e32 v10, 0x179abe15, v10
	v_rsq_f32_e32 v10, v10
	v_rcp_f32_e32 v7, v7
	v_lshlrev_b32_e32 v1, 16, v216
	v_sub_f32_e32 v0, v0, v1
	v_mul_f32_e32 v9, v9, v10
	v_add_f32_e32 v10, -1.0, v8
	v_fma_f32 v10, v248, v10, 1.0
	v_mul_f32_e32 v2, v10, v2
	v_mul_f32_e32 v10, v4, v2
	v_mul_f32_e32 v11, v249, v10
	v_mul_f32_e32 v7, 0xbf1b4598, v7
	v_mul_f32_e32 v7, 0x3fb8aa3b, v7
	v_mov_b32_dpp v11, v11 quad_perm:[1,0,3,2] row_mask:0xf bank_mask:0xf bound_ctrl:1
	v_fmac_f32_e32 v11, v249, v10
	v_exp_f32_e32 v7, v7
	v_fma_f32 v0, v246, v0, v1
	v_add_f32_dpp v10, v11, v11 quad_perm:[2,3,0,1] row_mask:0xf bank_mask:0xf bound_ctrl:1
	s_nop 0
	s_nop 0
	v_add_f32_dpp v10, v10, v10 row_half_mirror row_mask:0xf bank_mask:0xf bound_ctrl:1
	s_nop 1
	v_add_f32_dpp v10, v10, v10 row_mirror row_mask:0xf bank_mask:0xf bound_ctrl:1
	s_nop 1
	v_add_f32_dpp v10, v10, v10 row_bcast:15 row_mask:0xa bank_mask:0xf
	s_nop 1
	v_add_f32_dpp v10, v10, v10 row_bcast:31 row_mask:0xc bank_mask:0xf
	s_nop 0
	v_readlane_b32 s50, v10, 63
	v_add_u32_e32 v10, s52, v128
	ds_write2st64_b32 v10, v7, v9 offset1:32
	v_mul_f32_e32 v7, v8, v9
	ds_write2st64_b32 v10, v7, v2 offset0:64 offset1:96
	ds_write_b32 v10, v4 offset:32768
	v_add_u32_e32 v2, vcc_lo, v128
	ds_write_b32 v2, v0
	v_lshlrev_b32_e32 v0, 16, v190
	v_add_u32_e32 v2, vcc_hi, v128
	ds_write_b32 v2, v0
	s_and_saveexec_b64 s[72:73], s[4:5]
	s_lshl_b32 s0, s38, 2
	s_add_i32 s0, s43, s0
	v_mov_b32_e32 v0, s0
	v_mov_b32_e32 v2, s50
	ds_write_b32 v0, v2 offset:4
	s_or_b64 exec, exec, s[72:73]
	v_and_b32_e32 v2, 0xffff0000, v226
	v_sub_f32_e32 v3, v3, v2
	v_fma_f32 v3, v245, v3, v2
	v_mul_f32_e32 v9, v247, v3
	v_mul_f32_e32 v10, v9, v9
	v_lshlrev_b32_e32 v8, 16, v199
	s_nop 0
	v_mov_b32_dpp v10, v10 quad_perm:[1,0,3,2] row_mask:0xf bank_mask:0xf bound_ctrl:1
	v_fmac_f32_e32 v10, v9, v9
	v_add_f32_e32 v8, v251, v8
	v_mul_f32_e32 v8, 0xbfb8aa3b, v8
	v_add_f32_dpp v10, v10, v10 quad_perm:[2,3,0,1] row_mask:0xf bank_mask:0xf bound_ctrl:1
	v_exp_f32_e32 v8, v8
	v_lshlrev_b32_e32 v7, 16, v207
	v_add_f32_dpp v10, v10, v10 row_half_mirror row_mask:0xf bank_mask:0xf bound_ctrl:1
	v_add_f32_e32 v7, v250, v7
	v_add_f32_e32 v8, 1.0, v8
	v_add_f32_dpp v10, v10, v10 row_mirror row_mask:0xf bank_mask:0xf bound_ctrl:1
	v_rcp_f32_e32 v8, v8
	v_mul_f32_e32 v7, 0xbfb8aa3b, v7
	v_add_f32_dpp v10, v10, v10 row_bcast:15 row_mask:0xa bank_mask:0xf
	v_and_b32_e32 v4, 0xffff0000, v223
	v_exp_f32_e32 v7, v7
	v_add_f32_dpp v10, v10, v10 row_bcast:31 row_mask:0xc bank_mask:0xf
	v_sub_f32_e32 v6, v6, v4
	v_readlane_b32 s0, v10, 63
	v_fma_f32 v6, v244, v6, v4
	v_add_f32_e32 v7, 1.0, v7
	v_max_f32_e64 v10, s0, s0
	v_max_f32_e32 v10, 0x179abe15, v10
	v_rsq_f32_e32 v10, v10
	v_rcp_f32_e32 v7, v7
	v_and_b32_e32 v0, 0xffff0000, v216
	v_sub_f32_e32 v1, v1, v0
	v_mul_f32_e32 v9, v9, v10
	v_add_f32_e32 v10, -1.0, v8
	v_fma_f32 v10, v248, v10, 1.0
	v_mul_f32_e32 v3, v10, v3
	v_mul_f32_e32 v10, v6, v3
	v_mul_f32_e32 v11, v249, v10
	v_mul_f32_e32 v7, 0xbf1b4598, v7
	v_mul_f32_e32 v7, 0x3fb8aa3b, v7
	v_mov_b32_dpp v11, v11 quad_perm:[1,0,3,2] row_mask:0xf bank_mask:0xf bound_ctrl:1
	v_fmac_f32_e32 v11, v249, v10
	v_exp_f32_e32 v7, v7
	v_fma_f32 v1, v246, v1, v0
	v_add_f32_dpp v10, v11, v11 quad_perm:[2,3,0,1] row_mask:0xf bank_mask:0xf bound_ctrl:1
	s_nop 0
	s_nop 0
	v_add_f32_dpp v10, v10, v10 row_half_mirror row_mask:0xf bank_mask:0xf bound_ctrl:1
	s_nop 1
	v_add_f32_dpp v10, v10, v10 row_mirror row_mask:0xf bank_mask:0xf bound_ctrl:1
	s_nop 1
	v_add_f32_dpp v10, v10, v10 row_bcast:15 row_mask:0xa bank_mask:0xf
	s_nop 1
	v_add_f32_dpp v10, v10, v10 row_bcast:31 row_mask:0xc bank_mask:0xf
	s_nop 0
	v_readlane_b32 s50, v10, 63
	v_add_u32_e32 v10, s52, v132
	ds_write2st64_b32 v10, v7, v9 offset1:32
	v_mul_f32_e32 v7, v8, v9
	ds_write2st64_b32 v10, v7, v3 offset0:64 offset1:96
	ds_write_b32 v10, v6 offset:32768
	v_add_u32_e32 v3, vcc_lo, v132
	ds_write_b32 v3, v1
	v_lshlrev_b32_e32 v1, 16, v191
	v_add_u32_e32 v3, vcc_hi, v132
	ds_write_b32 v3, v1
	s_and_saveexec_b64 s[72:73], s[4:5]
	s_lshl_b32 s0, s38, 2
	s_add_i32 s0, s43, s0
	v_mov_b32_e32 v1, s0
	v_mov_b32_e32 v3, s50
	ds_write_b32 v1, v3 offset:8
	s_or_b64 exec, exec, s[72:73]
	v_lshlrev_b32_e32 v3, 16, v227
	v_sub_f32_e32 v2, v2, v3
	v_fma_f32 v2, v245, v2, v3
	v_mul_f32_e32 v9, v247, v2
	v_mul_f32_e32 v10, v9, v9
	v_lshlrev_b32_e32 v8, 16, v200
	s_nop 0
	v_mov_b32_dpp v10, v10 quad_perm:[1,0,3,2] row_mask:0xf bank_mask:0xf bound_ctrl:1
	v_fmac_f32_e32 v10, v9, v9
	v_add_f32_e32 v8, v251, v8
	v_mul_f32_e32 v8, 0xbfb8aa3b, v8
	v_add_f32_dpp v10, v10, v10 quad_perm:[2,3,0,1] row_mask:0xf bank_mask:0xf bound_ctrl:1
	v_exp_f32_e32 v8, v8
	v_lshlrev_b32_e32 v7, 16, v208
	v_add_f32_dpp v10, v10, v10 row_half_mirror row_mask:0xf bank_mask:0xf bound_ctrl:1
	v_add_f32_e32 v7, v250, v7
	v_add_f32_e32 v8, 1.0, v8
	v_add_f32_dpp v10, v10, v10 row_mirror row_mask:0xf bank_mask:0xf bound_ctrl:1
	v_rcp_f32_e32 v8, v8
	v_mul_f32_e32 v7, 0xbfb8aa3b, v7
	v_add_f32_dpp v10, v10, v10 row_bcast:15 row_mask:0xa bank_mask:0xf
	v_lshlrev_b32_e32 v6, 16, v224
	v_exp_f32_e32 v7, v7
	v_add_f32_dpp v10, v10, v10 row_bcast:31 row_mask:0xc bank_mask:0xf
	v_sub_f32_e32 v4, v4, v6
	v_readlane_b32 s0, v10, 63
	v_fma_f32 v4, v244, v4, v6
	v_add_f32_e32 v7, 1.0, v7
	v_max_f32_e64 v10, s0, s0
	v_max_f32_e32 v10, 0x179abe15, v10
	v_rsq_f32_e32 v10, v10
	v_rcp_f32_e32 v7, v7
	v_lshlrev_b32_e32 v1, 16, v217
	v_sub_f32_e32 v0, v0, v1
	v_mul_f32_e32 v9, v9, v10
	v_add_f32_e32 v10, -1.0, v8
	v_fma_f32 v10, v248, v10, 1.0
	v_mul_f32_e32 v2, v10, v2
	v_mul_f32_e32 v10, v4, v2
	v_mul_f32_e32 v11, v249, v10
	v_mul_f32_e32 v7, 0xbf1b4598, v7
	v_mul_f32_e32 v7, 0x3fb8aa3b, v7
	v_mov_b32_dpp v11, v11 quad_perm:[1,0,3,2] row_mask:0xf bank_mask:0xf bound_ctrl:1
	v_fmac_f32_e32 v11, v249, v10
	v_exp_f32_e32 v7, v7
	v_fma_f32 v0, v246, v0, v1
	v_add_f32_dpp v10, v11, v11 quad_perm:[2,3,0,1] row_mask:0xf bank_mask:0xf bound_ctrl:1
	s_nop 0
	s_nop 0
	v_add_f32_dpp v10, v10, v10 row_half_mirror row_mask:0xf bank_mask:0xf bound_ctrl:1
	s_nop 1
	v_add_f32_dpp v10, v10, v10 row_mirror row_mask:0xf bank_mask:0xf bound_ctrl:1
	s_nop 1
	v_add_f32_dpp v10, v10, v10 row_bcast:15 row_mask:0xa bank_mask:0xf
	s_nop 1
	v_add_f32_dpp v10, v10, v10 row_bcast:31 row_mask:0xc bank_mask:0xf
	s_nop 0
	v_readlane_b32 s50, v10, 63
	v_add_u32_e32 v10, s52, v136
	ds_write2st64_b32 v10, v7, v9 offset1:32
	v_mul_f32_e32 v7, v8, v9
	ds_write2st64_b32 v10, v7, v2 offset0:64 offset1:96
	ds_write_b32 v10, v4 offset:32768
	v_add_u32_e32 v2, vcc_lo, v136
	ds_write_b32 v2, v0
	v_lshlrev_b32_e32 v0, 16, v192
	v_add_u32_e32 v2, vcc_hi, v136
	ds_write_b32 v2, v0
	s_and_saveexec_b64 s[72:73], s[4:5]
	s_lshl_b32 s0, s38, 2
	s_add_i32 s0, s43, s0
	v_mov_b32_e32 v0, s0
	v_mov_b32_e32 v2, s50
	ds_write_b32 v0, v2 offset:12
	s_or_b64 exec, exec, s[72:73]
	v_and_b32_e32 v2, 0xffff0000, v227
	v_sub_f32_e32 v3, v3, v2
	v_fma_f32 v3, v245, v3, v2
	v_mul_f32_e32 v9, v247, v3
	v_mul_f32_e32 v10, v9, v9
	v_lshlrev_b32_e32 v8, 16, v201
	s_nop 0
	v_mov_b32_dpp v10, v10 quad_perm:[1,0,3,2] row_mask:0xf bank_mask:0xf bound_ctrl:1
	v_fmac_f32_e32 v10, v9, v9
	v_add_f32_e32 v8, v251, v8
	v_mul_f32_e32 v8, 0xbfb8aa3b, v8
	v_add_f32_dpp v10, v10, v10 quad_perm:[2,3,0,1] row_mask:0xf bank_mask:0xf bound_ctrl:1
	v_exp_f32_e32 v8, v8
	v_lshlrev_b32_e32 v7, 16, v209
	v_add_f32_dpp v10, v10, v10 row_half_mirror row_mask:0xf bank_mask:0xf bound_ctrl:1
	v_add_f32_e32 v7, v250, v7
	v_add_f32_e32 v8, 1.0, v8
	v_add_f32_dpp v10, v10, v10 row_mirror row_mask:0xf bank_mask:0xf bound_ctrl:1
	v_rcp_f32_e32 v8, v8
	v_mul_f32_e32 v7, 0xbfb8aa3b, v7
	v_add_f32_dpp v10, v10, v10 row_bcast:15 row_mask:0xa bank_mask:0xf
	v_and_b32_e32 v4, 0xffff0000, v224
	v_exp_f32_e32 v7, v7
	v_add_f32_dpp v10, v10, v10 row_bcast:31 row_mask:0xc bank_mask:0xf
	v_sub_f32_e32 v6, v6, v4
	v_readlane_b32 s0, v10, 63
	v_fma_f32 v6, v244, v6, v4
	v_add_f32_e32 v7, 1.0, v7
	v_max_f32_e64 v10, s0, s0
	v_max_f32_e32 v10, 0x179abe15, v10
	v_rsq_f32_e32 v10, v10
	v_rcp_f32_e32 v7, v7
	v_and_b32_e32 v0, 0xffff0000, v217
	v_sub_f32_e32 v1, v1, v0
	v_mul_f32_e32 v9, v9, v10
	v_add_f32_e32 v10, -1.0, v8
	v_fma_f32 v10, v248, v10, 1.0
	v_mul_f32_e32 v3, v10, v3
	v_mul_f32_e32 v10, v6, v3
	v_mul_f32_e32 v11, v249, v10
	v_mul_f32_e32 v7, 0xbf1b4598, v7
	v_mul_f32_e32 v7, 0x3fb8aa3b, v7
	v_mov_b32_dpp v11, v11 quad_perm:[1,0,3,2] row_mask:0xf bank_mask:0xf bound_ctrl:1
	v_fmac_f32_e32 v11, v249, v10
	v_exp_f32_e32 v7, v7
	v_fma_f32 v1, v246, v1, v0
	v_add_f32_dpp v10, v11, v11 quad_perm:[2,3,0,1] row_mask:0xf bank_mask:0xf bound_ctrl:1
	s_nop 0
	s_nop 0
	v_add_f32_dpp v10, v10, v10 row_half_mirror row_mask:0xf bank_mask:0xf bound_ctrl:1
	s_nop 1
	v_add_f32_dpp v10, v10, v10 row_mirror row_mask:0xf bank_mask:0xf bound_ctrl:1
	s_nop 1
	v_add_f32_dpp v10, v10, v10 row_bcast:15 row_mask:0xa bank_mask:0xf
	s_nop 1
	v_add_f32_dpp v10, v10, v10 row_bcast:31 row_mask:0xc bank_mask:0xf
	s_nop 0
	v_readlane_b32 s50, v10, 63
	v_add_u32_e32 v10, s52, v140
	ds_write2st64_b32 v10, v7, v9 offset1:32
	v_mul_f32_e32 v7, v8, v9
	ds_write2st64_b32 v10, v7, v3 offset0:64 offset1:96
	ds_write_b32 v10, v6 offset:32768
	v_add_u32_e32 v3, vcc_lo, v140
	ds_write_b32 v3, v1
	v_lshlrev_b32_e32 v1, 16, v193
	v_add_u32_e32 v3, vcc_hi, v140
	ds_write_b32 v3, v1
	s_and_saveexec_b64 s[72:73], s[4:5]
	s_lshl_b32 s0, s38, 2
	s_add_i32 s0, s43, s0
	v_mov_b32_e32 v1, s0
	v_mov_b32_e32 v3, s50
	ds_write_b32 v1, v3 offset:16
	s_or_b64 exec, exec, s[72:73]
	v_lshlrev_b32_e32 v3, 16, v242
	v_sub_f32_e32 v2, v2, v3
	v_fma_f32 v2, v245, v2, v3
	v_mul_f32_e32 v9, v247, v2
	v_mul_f32_e32 v10, v9, v9
	v_lshlrev_b32_e32 v8, 16, v202
	s_nop 0
	v_mov_b32_dpp v10, v10 quad_perm:[1,0,3,2] row_mask:0xf bank_mask:0xf bound_ctrl:1
	v_fmac_f32_e32 v10, v9, v9
	v_add_f32_e32 v8, v251, v8
	v_mul_f32_e32 v8, 0xbfb8aa3b, v8
	v_add_f32_dpp v10, v10, v10 quad_perm:[2,3,0,1] row_mask:0xf bank_mask:0xf bound_ctrl:1
	v_exp_f32_e32 v8, v8
	v_lshlrev_b32_e32 v7, 16, v210
	v_add_f32_dpp v10, v10, v10 row_half_mirror row_mask:0xf bank_mask:0xf bound_ctrl:1
	v_add_f32_e32 v7, v250, v7
	v_add_f32_e32 v8, 1.0, v8
	v_add_f32_dpp v10, v10, v10 row_mirror row_mask:0xf bank_mask:0xf bound_ctrl:1
	v_rcp_f32_e32 v8, v8
	v_mul_f32_e32 v7, 0xbfb8aa3b, v7
	v_add_f32_dpp v10, v10, v10 row_bcast:15 row_mask:0xa bank_mask:0xf
	v_lshlrev_b32_e32 v6, 16, v225
	v_exp_f32_e32 v7, v7
	v_add_f32_dpp v10, v10, v10 row_bcast:31 row_mask:0xc bank_mask:0xf
	v_sub_f32_e32 v4, v4, v6
	v_readlane_b32 s0, v10, 63
	v_fma_f32 v4, v244, v4, v6
	v_add_f32_e32 v7, 1.0, v7
	v_max_f32_e64 v10, s0, s0
	v_max_f32_e32 v10, 0x179abe15, v10
	v_rsq_f32_e32 v10, v10
	v_rcp_f32_e32 v7, v7
	v_lshlrev_b32_e32 v1, 16, v218
	v_sub_f32_e32 v0, v0, v1
	v_mul_f32_e32 v9, v9, v10
	v_add_f32_e32 v10, -1.0, v8
	v_fma_f32 v10, v248, v10, 1.0
	v_mul_f32_e32 v2, v10, v2
	v_mul_f32_e32 v10, v4, v2
	v_mul_f32_e32 v11, v249, v10
	v_mul_f32_e32 v7, 0xbf1b4598, v7
	v_mul_f32_e32 v7, 0x3fb8aa3b, v7
	v_mov_b32_dpp v11, v11 quad_perm:[1,0,3,2] row_mask:0xf bank_mask:0xf bound_ctrl:1
	v_fmac_f32_e32 v11, v249, v10
	v_exp_f32_e32 v7, v7
	v_fma_f32 v0, v246, v0, v1
	v_add_f32_dpp v10, v11, v11 quad_perm:[2,3,0,1] row_mask:0xf bank_mask:0xf bound_ctrl:1
	s_nop 0
	s_nop 0
	v_add_f32_dpp v10, v10, v10 row_half_mirror row_mask:0xf bank_mask:0xf bound_ctrl:1
	s_nop 1
	v_add_f32_dpp v10, v10, v10 row_mirror row_mask:0xf bank_mask:0xf bound_ctrl:1
	s_nop 1
	v_add_f32_dpp v10, v10, v10 row_bcast:15 row_mask:0xa bank_mask:0xf
	s_nop 1
	v_add_f32_dpp v10, v10, v10 row_bcast:31 row_mask:0xc bank_mask:0xf
	s_nop 0
	v_readlane_b32 s50, v10, 63
	v_add_u32_e32 v10, s52, v144
	ds_write2st64_b32 v10, v7, v9 offset1:32
	v_mul_f32_e32 v7, v8, v9
	ds_write2st64_b32 v10, v7, v2 offset0:64 offset1:96
	ds_write_b32 v10, v4 offset:32768
	v_add_u32_e32 v2, vcc_lo, v144
	ds_write_b32 v2, v0
	v_lshlrev_b32_e32 v0, 16, v194
	v_add_u32_e32 v2, vcc_hi, v144
	ds_write_b32 v2, v0
	s_and_saveexec_b64 s[72:73], s[4:5]
; __device__ __forceinline__ void phase_rwkv(KP P, int l_, unsigned char* shm) {
;     ...
;                 if (c + 1 < NC) { RW_PREP(c + 1); if (c + 2 < NC) RW_LOAD(c + 2); }
	s_lshl_b32 s0, s38, 2
	s_add_i32 s0, s43, s0
	v_mov_b32_e32 v0, s0
	v_mov_b32_e32 v2, s50
	ds_write_b32 v0, v2 offset:20
	s_or_b64 exec, exec, s[72:73]
	v_and_b32_e32 v2, 0xffff0000, v242
	v_sub_f32_e32 v3, v3, v2
	v_fma_f32 v3, v245, v3, v2
	v_mul_f32_e32 v9, v247, v3
	v_mul_f32_e32 v10, v9, v9
	v_lshlrev_b32_e32 v8, 16, v203
	s_nop 0
	v_mov_b32_dpp v10, v10 quad_perm:[1,0,3,2] row_mask:0xf bank_mask:0xf bound_ctrl:1
	v_fmac_f32_e32 v10, v9, v9
	v_add_f32_e32 v8, v251, v8
	v_mul_f32_e32 v8, 0xbfb8aa3b, v8
	v_add_f32_dpp v10, v10, v10 quad_perm:[2,3,0,1] row_mask:0xf bank_mask:0xf bound_ctrl:1
	v_exp_f32_e32 v8, v8
	v_lshlrev_b32_e32 v7, 16, v211
	v_add_f32_dpp v10, v10, v10 row_half_mirror row_mask:0xf bank_mask:0xf bound_ctrl:1
	v_add_f32_e32 v7, v250, v7
	v_add_f32_e32 v8, 1.0, v8
	v_add_f32_dpp v10, v10, v10 row_mirror row_mask:0xf bank_mask:0xf bound_ctrl:1
	v_rcp_f32_e32 v8, v8
	v_mul_f32_e32 v7, 0xbfb8aa3b, v7
	v_add_f32_dpp v10, v10, v10 row_bcast:15 row_mask:0xa bank_mask:0xf
	v_and_b32_e32 v4, 0xffff0000, v225
	v_exp_f32_e32 v7, v7
	v_add_f32_dpp v10, v10, v10 row_bcast:31 row_mask:0xc bank_mask:0xf
	v_sub_f32_e32 v6, v6, v4
	v_readlane_b32 s0, v10, 63
	v_fma_f32 v6, v244, v6, v4
	v_add_f32_e32 v7, 1.0, v7
	v_max_f32_e64 v10, s0, s0
	v_max_f32_e32 v10, 0x179abe15, v10
	v_rsq_f32_e32 v10, v10
	v_rcp_f32_e32 v7, v7
	v_and_b32_e32 v0, 0xffff0000, v218
	v_sub_f32_e32 v1, v1, v0
	v_mul_f32_e32 v9, v9, v10
	v_add_f32_e32 v10, -1.0, v8
	v_fma_f32 v10, v248, v10, 1.0
	v_mul_f32_e32 v3, v10, v3
	v_mul_f32_e32 v10, v6, v3
	v_mul_f32_e32 v11, v249, v10
	v_mul_f32_e32 v7, 0xbf1b4598, v7
	v_mul_f32_e32 v7, 0x3fb8aa3b, v7
	v_mov_b32_dpp v11, v11 quad_perm:[1,0,3,2] row_mask:0xf bank_mask:0xf bound_ctrl:1
	v_fmac_f32_e32 v11, v249, v10
	v_exp_f32_e32 v7, v7
	v_fma_f32 v1, v246, v1, v0
	v_add_f32_dpp v10, v11, v11 quad_perm:[2,3,0,1] row_mask:0xf bank_mask:0xf bound_ctrl:1
	s_nop 0
	s_nop 0
	v_add_f32_dpp v10, v10, v10 row_half_mirror row_mask:0xf bank_mask:0xf bound_ctrl:1
	s_nop 1
	v_add_f32_dpp v10, v10, v10 row_mirror row_mask:0xf bank_mask:0xf bound_ctrl:1
	s_nop 1
	v_add_f32_dpp v10, v10, v10 row_bcast:15 row_mask:0xa bank_mask:0xf
	s_nop 1
	v_add_f32_dpp v10, v10, v10 row_bcast:31 row_mask:0xc bank_mask:0xf
	s_nop 0
	v_readlane_b32 s50, v10, 63
	v_add_u32_e32 v10, s52, v148
	ds_write2st64_b32 v10, v7, v9 offset1:32
	v_mul_f32_e32 v7, v8, v9
	ds_write2st64_b32 v10, v7, v3 offset0:64 offset1:96
	ds_write_b32 v10, v6 offset:32768
	v_add_u32_e32 v3, vcc_lo, v148
	ds_write_b32 v3, v1
	v_lshlrev_b32_e32 v1, 16, v195
	v_add_u32_e32 v3, vcc_hi, v148
	ds_write_b32 v3, v1
	s_and_saveexec_b64 s[72:73], s[4:5]
	s_lshl_b32 s0, s38, 2
	s_add_i32 s0, s43, s0
	v_mov_b32_e32 v1, s0
	v_mov_b32_e32 v3, s50
	ds_write_b32 v1, v3 offset:24
	s_or_b64 exec, exec, s[72:73]
	v_lshlrev_b32_e32 v7, 16, v212
	v_add_f32_e32 v7, v250, v7
	v_mul_f32_e32 v7, 0xbfb8aa3b, v7
	v_lshlrev_b32_e32 v1, 16, v176
	v_exp_f32_e32 v7, v7
	v_sub_f32_e32 v4, v4, v1
	v_lshlrev_b32_e32 v3, 16, v214
	v_fmac_f32_e32 v1, v244, v4
	v_lshlrev_b32_e32 v4, 16, v204
	v_sub_f32_e32 v2, v2, v3
	v_add_f32_e32 v4, v251, v4
	v_fmac_f32_e32 v3, v245, v2
	v_add_f32_e32 v2, 1.0, v7
	v_mul_f32_e32 v4, 0xbfb8aa3b, v4
	v_rcp_f32_e32 v2, v2
	v_exp_f32_e32 v4, v4
	v_lshlrev_b32_e32 v6, 16, v219
	v_sub_f32_e32 v0, v0, v6
	v_fmac_f32_e32 v6, v246, v0
	v_mul_f32_e32 v0, 0xbf1b4598, v2
	v_add_f32_e32 v2, 1.0, v4
	v_mul_f32_e32 v4, v247, v3
	v_mul_f32_e32 v7, v4, v4
	v_rcp_f32_e32 v2, v2
	s_nop 0
	v_mov_b32_dpp v7, v7 quad_perm:[1,0,3,2] row_mask:0xf bank_mask:0xf bound_ctrl:1
	v_fmac_f32_e32 v7, v4, v4
	v_mul_f32_e32 v0, 0x3fb8aa3b, v0
	v_exp_f32_e32 v0, v0
	v_add_f32_dpp v7, v7, v7 quad_perm:[2,3,0,1] row_mask:0xf bank_mask:0xf bound_ctrl:1
	s_nop 1
	v_add_f32_dpp v7, v7, v7 row_half_mirror row_mask:0xf bank_mask:0xf bound_ctrl:1
	s_nop 1
	v_add_f32_dpp v7, v7, v7 row_mirror row_mask:0xf bank_mask:0xf bound_ctrl:1
	s_nop 1
	v_add_f32_dpp v7, v7, v7 row_bcast:15 row_mask:0xa bank_mask:0xf
	s_nop 1
	v_add_f32_dpp v7, v7, v7 row_bcast:31 row_mask:0xc bank_mask:0xf
	s_nop 0
	v_readlane_b32 s0, v7, 63
	s_nop 1
	v_max_f32_e64 v7, s0, s0
	v_max_f32_e32 v7, 0x179abe15, v7
	v_rsq_f32_e32 v7, v7
	s_nop 0
	v_mul_f32_e32 v4, v4, v7
	v_add_f32_e32 v7, -1.0, v2
	v_fma_f32 v7, v248, v7, 1.0
	v_mul_f32_e32 v3, v7, v3
	v_mul_f32_e32 v7, v1, v3
	v_mul_f32_e32 v8, v249, v7
	s_nop 1
	v_mov_b32_dpp v8, v8 quad_perm:[1,0,3,2] row_mask:0xf bank_mask:0xf bound_ctrl:1
	v_fmac_f32_e32 v8, v249, v7
	s_nop 1
	v_add_f32_dpp v7, v8, v8 quad_perm:[2,3,0,1] row_mask:0xf bank_mask:0xf bound_ctrl:1
	s_nop 0
	s_nop 0
	v_add_f32_dpp v7, v7, v7 row_half_mirror row_mask:0xf bank_mask:0xf bound_ctrl:1
	s_nop 1
	v_add_f32_dpp v7, v7, v7 row_mirror row_mask:0xf bank_mask:0xf bound_ctrl:1
	s_nop 1
	v_add_f32_dpp v7, v7, v7 row_bcast:15 row_mask:0xa bank_mask:0xf
	s_nop 1
	v_add_f32_dpp v7, v7, v7 row_bcast:31 row_mask:0xc bank_mask:0xf
	s_nop 0
	v_readlane_b32 s50, v7, 63
	v_add_u32_e32 v7, s52, v152
	ds_write2st64_b32 v7, v0, v4 offset1:32
	v_mul_f32_e32 v0, v2, v4
	ds_write2st64_b32 v7, v0, v3 offset0:64 offset1:96
	ds_write_b32 v7, v1 offset:32768
	v_add_u32_e32 v0, vcc_lo, v152
	ds_write_b32 v0, v6
	v_lshlrev_b32_e32 v0, 16, v196
	v_add_u32_e32 v1, vcc_hi, v152
	ds_write_b32 v1, v0
	s_and_saveexec_b64 s[72:73], s[4:5]
	s_lshl_b32 s0, s38, 2
	s_add_i32 s0, s43, s0
	v_mov_b32_e32 v0, s0
	v_mov_b32_e32 v1, s50
	ds_write_b32 v0, v1 offset:28
	s_or_b64 exec, exec, s[72:73]
	s_cmp_gt_u32 s42, 61
	s_cbranch_scc1 .LBB0_2525
	s_lshl_b32 s0, s42, 5
	s_add_i32 s72, s0, s40
	s_add_i32 s52, s72, -1
	s_lshl_b64 s[0:1], s[52:53], 12
	s_mov_b32 s73, s53
	v_lshl_add_u64 v[0:1], v[86:87], 0, s[0:1]
	s_lshl_b64 s[0:1], s[72:73], 12
	global_load_ushort v40, v[0:1], off
	global_load_ushort v60, v[0:1], off offset:1024
	global_load_ushort v61, v[0:1], off offset:2048
	v_lshl_add_u64 v[0:1], v[86:87], 0, s[0:1]
	s_lshl_b32 s52, s72, 12
	global_load_ushort v41, v[0:1], off
	global_load_ushort v42, v[0:1], off offset:1024
	global_load_ushort v62, v[0:1], off offset:2048
	v_lshl_add_u64 v[0:1], v[86:87], 0, s[52:53]
	v_add_co_u32_e32 v2, vcc, s66, v0
	s_movk_i32 s51, 0x3000
	s_nop 0
	v_addc_co_u32_e32 v3, vcc, 0, v1, vcc
	v_add_co_u32_e32 v6, vcc, s67, v0
	s_movk_i32 s50, 0x4000
	s_nop 0
	v_addc_co_u32_e32 v7, vcc, 0, v1, vcc
	global_load_ushort v43, v[6:7], off offset:-4096
	global_load_ushort v44, v[2:3], off offset:1024
	global_load_ushort v63, v[2:3], off offset:2048
	global_load_ushort v45, v[6:7], off
	global_load_ushort v46, v[6:7], off offset:1024
	global_load_ushort v64, v[6:7], off offset:2048
	v_add_co_u32_e32 v2, vcc, s51, v0
	s_movk_i32 s52, 0x5000
	s_nop 0
	v_addc_co_u32_e32 v3, vcc, 0, v1, vcc
	v_add_co_u32_e32 v6, vcc, s50, v0
	s_movk_i32 s0, 0x6000
	s_nop 0
	v_addc_co_u32_e32 v7, vcc, 0, v1, vcc
	global_load_ushort v47, v[6:7], off offset:-4096
	global_load_ushort v48, v[2:3], off offset:1024
	global_load_ushort v49, v[2:3], off offset:2048
	global_load_ushort v50, v[6:7], off
	global_load_ushort v51, v[6:7], off offset:1024
	global_load_ushort v52, v[6:7], off offset:2048
	v_add_co_u32_e32 v2, vcc, s52, v0
	s_movk_i32 s68, 0x5000
	s_nop 0
	v_addc_co_u32_e32 v3, vcc, 0, v1, vcc
	v_add_co_u32_e32 v6, vcc, s0, v0
	s_movk_i32 s0, 0x7000
	s_nop 0
	v_addc_co_u32_e32 v7, vcc, 0, v1, vcc
	global_load_ushort v53, v[6:7], off offset:-4096
	global_load_ushort v54, v[2:3], off offset:1024
	global_load_ushort v55, v[2:3], off offset:2048
	global_load_ushort v56, v[6:7], off
	global_load_ushort v57, v[6:7], off offset:1024
	global_load_ushort v58, v[6:7], off offset:2048
	v_add_co_u32_e32 v2, vcc, s0, v0
	s_add_u32 s0, s84, s72
	s_addc_u32 s1, s85, 0
	v_addc_co_u32_e32 v3, vcc, 0, v1, vcc
	s_mul_i32 s43, s1, 0xc00
	v_mad_u64_u32 v[16:17], s[0:1], s0, v236, v[88:89]
	v_add_u32_e32 v17, s43, v17
	v_add_co_u32_e32 v10, vcc, s66, v16
	global_load_ushort v176, v[2:3], off
	global_load_ushort v214, v[2:3], off offset:1024
	s_nop 0
	global_load_ushort v219, v[2:3], off offset:2048
	v_addc_co_u32_e32 v11, vcc, 0, v17, vcc
	v_add_co_u32_e32 v18, vcc, s67, v16
	global_load_ushort v205, v[16:17], off
	global_load_ushort v197, v[16:17], off offset:1024
	global_load_ushort v177, v[16:17], off offset:2048
	global_load_ushort v206, v[16:17], off offset:3072
	v_addc_co_u32_e32 v19, vcc, 0, v17, vcc
	global_load_ushort v198, v[18:19], off offset:-4096
	global_load_ushort v190, v[10:11], off offset:1024
	global_load_ushort v207, v[10:11], off offset:2048
	global_load_ushort v199, v[10:11], off offset:3072
	s_nop 0
	global_load_ushort v191, v[18:19], off
	global_load_ushort v208, v[18:19], off offset:1024
	global_load_ushort v200, v[18:19], off offset:2048
	global_load_ushort v192, v[18:19], off offset:3072
	v_add_co_u32_e32 v18, vcc, s51, v16
	v_addc_co_u32_e32 v19, vcc, 0, v17, vcc
	v_add_co_u32_e32 v22, vcc, s50, v16
	s_nop 0
	v_addc_co_u32_e32 v23, vcc, 0, v17, vcc
	global_load_ushort v209, v[22:23], off offset:-4096
	global_load_ushort v201, v[18:19], off offset:1024
	global_load_ushort v193, v[18:19], off offset:2048
	global_load_ushort v210, v[18:19], off offset:3072
	global_load_ushort v202, v[22:23], off
	global_load_ushort v194, v[22:23], off offset:1024
	global_load_ushort v211, v[22:23], off offset:2048
	global_load_ushort v203, v[22:23], off offset:3072
	v_add_co_u32_e32 v16, vcc, s52, v16
	v_addc_co_u32_e32 v17, vcc, 0, v17, vcc
	global_load_ushort v195, v[16:17], off
	global_load_ushort v212, v[16:17], off offset:1024
	global_load_ushort v204, v[16:17], off offset:2048
	global_load_ushort v196, v[16:17], off offset:3072

; __device__ __forceinline__ void phase_rwkv(KP P, int l_, unsigned char* shm) {
;     ...
;         if (!scanw) RW_POST(NC - 1);
.LBB0_2526:
	s_andn2_b64 vcc, exec, s[20:21]
	s_cbranch_vccnz .LBB0_2462
	ds_read_b32 v0, v157
	s_lshl_b64 s[42:43], s[70:71], 21
	s_waitcnt lgkmcnt(0)
	v_add_f32_dpp v1, v0, v0 quad_perm:[1,0,3,2] row_mask:0xf bank_mask:0xf bound_ctrl:1
	s_nop 1
	v_add_f32_dpp v1, v1, v1 quad_perm:[2,3,0,1] row_mask:0xf bank_mask:0xf bound_ctrl:1
	s_nop 1
	v_add_f32_dpp v1, v1, v1 row_half_mirror row_mask:0xf bank_mask:0xf bound_ctrl:1
	s_nop 1
	v_add_f32_dpp v1, v1, v1 row_mirror row_mask:0xf bank_mask:0xf bound_ctrl:1
	s_nop 1
	v_add_f32_dpp v1, v1, v1 row_bcast:15 row_mask:0xa bank_mask:0xf
	s_nop 1
	v_add_f32_dpp v1, v1, v1 row_bcast:31 row_mask:0xc bank_mask:0xf
	s_nop 0
	v_readlane_b32 s0, v1, 63
	s_nop 1
	v_fmac_f32_e32 v0, s0, v237
	v_mul_f32_e32 v1, v0, v0
	s_nop 1
	v_mov_b32_dpp v1, v1 quad_perm:[1,0,3,2] row_mask:0xf bank_mask:0xf bound_ctrl:1
	v_fmac_f32_e32 v1, v0, v0
	s_nop 1
	v_add_f32_dpp v1, v1, v1 quad_perm:[2,3,0,1] row_mask:0xf bank_mask:0xf bound_ctrl:1
	s_nop 1
	v_add_f32_dpp v1, v1, v1 row_half_mirror row_mask:0xf bank_mask:0xf bound_ctrl:1
	s_nop 1
	v_add_f32_dpp v1, v1, v1 row_mirror row_mask:0xf bank_mask:0xf bound_ctrl:1
	s_nop 1
	v_add_f32_dpp v1, v1, v1 row_bcast:15 row_mask:0xa bank_mask:0xf
	s_nop 1
	v_add_f32_dpp v1, v1, v1 row_bcast:31 row_mask:0xc bank_mask:0xf
	s_nop 0
	v_readlane_b32 s0, v1, 63
	s_nop 1
	v_fma_f32 v1, s0, v238, v234
	v_rsq_f32_e32 v1, v1
	v_readlane_b32 s0, v255, 18
	v_readlane_b32 s1, v255, 19
	v_mul_f32_e32 v0, v0, v1
	v_mov_b32_e32 v1, s41
	ds_read_b32 v1, v1
	ds_read_b32 v2, v126
	v_fma_f32 v0, v220, v0, v213
	s_waitcnt lgkmcnt(0)
	v_fmac_f32_e32 v0, v1, v2
	ds_read_b32 v1, v158
	s_waitcnt lgkmcnt(0)
	v_mul_f32_e32 v0, v1, v0
	s_nop 0
	v_cvt_pk_bf16_f32 v4, v0, v5
	v_lshl_or_b32 v0, v243, 1, s42
	v_mov_b32_e32 v1, s43
	v_lshl_add_u64 v[2:3], s[0:1], 0, v[0:1]
	s_mov_b32 s1, 0x1f8000
	v_add_co_u32_e32 v2, vcc, s1, v2
	v_readlane_b32 s42, v255, 20
	s_nop 0
	v_addc_co_u32_e32 v3, vcc, 0, v3, vcc
	global_store_short v[2:3], v4, off
	ds_read_b32 v2, v159
	v_readlane_b32 s43, v255, 21
	s_waitcnt lgkmcnt(0)
	v_add_f32_dpp v3, v2, v2 quad_perm:[1,0,3,2] row_mask:0xf bank_mask:0xf bound_ctrl:1
	s_nop 1
	v_add_f32_dpp v3, v3, v3 quad_perm:[2,3,0,1] row_mask:0xf bank_mask:0xf bound_ctrl:1
	s_nop 1
	v_add_f32_dpp v3, v3, v3 row_half_mirror row_mask:0xf bank_mask:0xf bound_ctrl:1
	s_nop 1
	v_add_f32_dpp v3, v3, v3 row_mirror row_mask:0xf bank_mask:0xf bound_ctrl:1
	s_nop 1
	v_add_f32_dpp v3, v3, v3 row_bcast:15 row_mask:0xa bank_mask:0xf
	s_nop 1
	v_add_f32_dpp v3, v3, v3 row_bcast:31 row_mask:0xc bank_mask:0xf
	s_nop 0
	v_readlane_b32 s0, v3, 63
	s_nop 1
	v_fmac_f32_e32 v2, s0, v237
	v_mul_f32_e32 v3, v2, v2
	s_nop 1
	v_mov_b32_dpp v3, v3 quad_perm:[1,0,3,2] row_mask:0xf bank_mask:0xf bound_ctrl:1
	v_fmac_f32_e32 v3, v2, v2
	s_nop 1
	v_add_f32_dpp v3, v3, v3 quad_perm:[2,3,0,1] row_mask:0xf bank_mask:0xf bound_ctrl:1
	s_nop 1
	v_add_f32_dpp v3, v3, v3 row_half_mirror row_mask:0xf bank_mask:0xf bound_ctrl:1
	s_nop 1
	v_add_f32_dpp v3, v3, v3 row_mirror row_mask:0xf bank_mask:0xf bound_ctrl:1
	s_nop 1
	v_add_f32_dpp v3, v3, v3 row_bcast:15 row_mask:0xa bank_mask:0xf
	s_nop 1
	v_add_f32_dpp v3, v3, v3 row_bcast:31 row_mask:0xc bank_mask:0xf
	s_nop 0
	v_readlane_b32 s0, v3, 63
	s_nop 1
	v_fma_f32 v3, s0, v238, v234
	v_rsq_f32_e32 v3, v3
	s_nop 0
	v_mul_f32_e32 v2, v2, v3
	v_mov_b32_e32 v3, s62
	ds_read_b32 v3, v3
	ds_read_b32 v4, v130
	v_fma_f32 v2, v220, v2, v213
	s_waitcnt lgkmcnt(0)
	v_fmac_f32_e32 v2, v3, v4
	ds_read_b32 v3, v160
	s_waitcnt lgkmcnt(0)
	v_mul_f32_e32 v2, v3, v2
	s_nop 0
	v_cvt_pk_bf16_f32 v4, v2, v5
	v_lshl_add_u64 v[2:3], s[42:43], 0, v[0:1]
	v_add_co_u32_e32 v2, vcc, s1, v2
	v_readlane_b32 s42, v255, 22
	s_nop 0
	v_addc_co_u32_e32 v3, vcc, 0, v3, vcc
	global_store_short v[2:3], v4, off
	ds_read_b32 v2, v161
	v_readlane_b32 s43, v255, 23
	s_waitcnt lgkmcnt(0)
	v_add_f32_dpp v3, v2, v2 quad_perm:[1,0,3,2] row_mask:0xf bank_mask:0xf bound_ctrl:1
	s_nop 1
	v_add_f32_dpp v3, v3, v3 quad_perm:[2,3,0,1] row_mask:0xf bank_mask:0xf bound_ctrl:1
	s_nop 1
	v_add_f32_dpp v3, v3, v3 row_half_mirror row_mask:0xf bank_mask:0xf bound_ctrl:1
	s_nop 1
	v_add_f32_dpp v3, v3, v3 row_mirror row_mask:0xf bank_mask:0xf bound_ctrl:1
	s_nop 1
	v_add_f32_dpp v3, v3, v3 row_bcast:15 row_mask:0xa bank_mask:0xf
	s_nop 1
	v_add_f32_dpp v3, v3, v3 row_bcast:31 row_mask:0xc bank_mask:0xf
	s_nop 0
	v_readlane_b32 s0, v3, 63
	s_nop 1
	v_fmac_f32_e32 v2, s0, v237
	v_mul_f32_e32 v3, v2, v2
	s_nop 1
	v_mov_b32_dpp v3, v3 quad_perm:[1,0,3,2] row_mask:0xf bank_mask:0xf bound_ctrl:1
	v_fmac_f32_e32 v3, v2, v2
	s_nop 1
	v_add_f32_dpp v3, v3, v3 quad_perm:[2,3,0,1] row_mask:0xf bank_mask:0xf bound_ctrl:1
	s_nop 1
	v_add_f32_dpp v3, v3, v3 row_half_mirror row_mask:0xf bank_mask:0xf bound_ctrl:1
	s_nop 1
	v_add_f32_dpp v3, v3, v3 row_mirror row_mask:0xf bank_mask:0xf bound_ctrl:1
	s_nop 1
	v_add_f32_dpp v3, v3, v3 row_bcast:15 row_mask:0xa bank_mask:0xf
	s_nop 1
	v_add_f32_dpp v3, v3, v3 row_bcast:31 row_mask:0xc bank_mask:0xf
	s_nop 0
	v_readlane_b32 s0, v3, 63
	s_nop 1
	v_fma_f32 v3, s0, v238, v234
	v_rsq_f32_e32 v3, v3
	s_nop 0
	v_mul_f32_e32 v2, v2, v3
	v_mov_b32_e32 v3, s63
	ds_read_b32 v3, v3
	ds_read_b32 v4, v134
	v_fma_f32 v2, v220, v2, v213
	s_waitcnt lgkmcnt(0)
	v_fmac_f32_e32 v2, v3, v4
	ds_read_b32 v3, v162
	s_waitcnt lgkmcnt(0)
	v_mul_f32_e32 v2, v3, v2
	s_nop 0
	v_cvt_pk_bf16_f32 v4, v2, v5
	v_lshl_add_u64 v[2:3], s[42:43], 0, v[0:1]
	v_add_co_u32_e32 v2, vcc, s1, v2
	v_readlane_b32 s42, v255, 24
	s_nop 0
	v_addc_co_u32_e32 v3, vcc, 0, v3, vcc
	global_store_short v[2:3], v4, off
	ds_read_b32 v2, v163
	v_readlane_b32 s43, v255, 25
	s_waitcnt lgkmcnt(0)
; __device__ __forceinline__ void phase_rwkv(KP P, int l_, unsigned char* shm) {
;     ...
;         if (!scanw) RW_POST(NC - 1);
	v_add_f32_dpp v3, v2, v2 quad_perm:[1,0,3,2] row_mask:0xf bank_mask:0xf bound_ctrl:1
	s_nop 1
	v_add_f32_dpp v3, v3, v3 quad_perm:[2,3,0,1] row_mask:0xf bank_mask:0xf bound_ctrl:1
	s_nop 1
	v_add_f32_dpp v3, v3, v3 row_half_mirror row_mask:0xf bank_mask:0xf bound_ctrl:1
	s_nop 1
	v_add_f32_dpp v3, v3, v3 row_mirror row_mask:0xf bank_mask:0xf bound_ctrl:1
	s_nop 1
	v_add_f32_dpp v3, v3, v3 row_bcast:15 row_mask:0xa bank_mask:0xf
	s_nop 1
	v_add_f32_dpp v3, v3, v3 row_bcast:31 row_mask:0xc bank_mask:0xf
	s_nop 0
	v_readlane_b32 s0, v3, 63
	s_nop 1
	v_fmac_f32_e32 v2, s0, v237
	v_mul_f32_e32 v3, v2, v2
	s_nop 1
	v_mov_b32_dpp v3, v3 quad_perm:[1,0,3,2] row_mask:0xf bank_mask:0xf bound_ctrl:1
	v_fmac_f32_e32 v3, v2, v2
	s_nop 1
	v_add_f32_dpp v3, v3, v3 quad_perm:[2,3,0,1] row_mask:0xf bank_mask:0xf bound_ctrl:1
	s_nop 1
	v_add_f32_dpp v3, v3, v3 row_half_mirror row_mask:0xf bank_mask:0xf bound_ctrl:1
	s_nop 1
	v_add_f32_dpp v3, v3, v3 row_mirror row_mask:0xf bank_mask:0xf bound_ctrl:1
	s_nop 1
	v_add_f32_dpp v3, v3, v3 row_bcast:15 row_mask:0xa bank_mask:0xf
	s_nop 1
	v_add_f32_dpp v3, v3, v3 row_bcast:31 row_mask:0xc bank_mask:0xf
	s_nop 0
	v_readlane_b32 s0, v3, 63
	s_nop 1
	v_fma_f32 v3, s0, v238, v234
	v_rsq_f32_e32 v3, v3
	s_nop 0
	v_mul_f32_e32 v2, v2, v3
	v_mov_b32_e32 v3, s64
	ds_read_b32 v3, v3
	ds_read_b32 v4, v138
	v_fma_f32 v2, v220, v2, v213
	s_waitcnt lgkmcnt(0)
	v_fmac_f32_e32 v2, v3, v4
	ds_read_b32 v3, v164
	s_waitcnt lgkmcnt(0)
	v_mul_f32_e32 v2, v3, v2
	s_nop 0
	v_cvt_pk_bf16_f32 v4, v2, v5
	v_lshl_add_u64 v[2:3], s[42:43], 0, v[0:1]
	v_add_co_u32_e32 v2, vcc, s1, v2
	v_readlane_b32 s42, v255, 26
	s_nop 0
	v_addc_co_u32_e32 v3, vcc, 0, v3, vcc
	global_store_short v[2:3], v4, off
	ds_read_b32 v2, v165
	v_readlane_b32 s43, v255, 27
	s_waitcnt lgkmcnt(0)
	v_add_f32_dpp v3, v2, v2 quad_perm:[1,0,3,2] row_mask:0xf bank_mask:0xf bound_ctrl:1
	s_nop 1
	v_add_f32_dpp v3, v3, v3 quad_perm:[2,3,0,1] row_mask:0xf bank_mask:0xf bound_ctrl:1
	s_nop 1
	v_add_f32_dpp v3, v3, v3 row_half_mirror row_mask:0xf bank_mask:0xf bound_ctrl:1
	s_nop 1
	v_add_f32_dpp v3, v3, v3 row_mirror row_mask:0xf bank_mask:0xf bound_ctrl:1
	s_nop 1
	v_add_f32_dpp v3, v3, v3 row_bcast:15 row_mask:0xa bank_mask:0xf
	s_nop 1
	v_add_f32_dpp v3, v3, v3 row_bcast:31 row_mask:0xc bank_mask:0xf
	s_nop 0
	v_readlane_b32 s0, v3, 63
	s_nop 1
	v_fmac_f32_e32 v2, s0, v237
	v_mul_f32_e32 v3, v2, v2
	s_nop 1
	v_mov_b32_dpp v3, v3 quad_perm:[1,0,3,2] row_mask:0xf bank_mask:0xf bound_ctrl:1
	v_fmac_f32_e32 v3, v2, v2
	s_nop 1
	v_add_f32_dpp v3, v3, v3 quad_perm:[2,3,0,1] row_mask:0xf bank_mask:0xf bound_ctrl:1
	s_nop 1
	v_add_f32_dpp v3, v3, v3 row_half_mirror row_mask:0xf bank_mask:0xf bound_ctrl:1
	s_nop 1
	v_add_f32_dpp v3, v3, v3 row_mirror row_mask:0xf bank_mask:0xf bound_ctrl:1
	s_nop 1
	v_add_f32_dpp v3, v3, v3 row_bcast:15 row_mask:0xa bank_mask:0xf
	s_nop 1
	v_add_f32_dpp v3, v3, v3 row_bcast:31 row_mask:0xc bank_mask:0xf
	s_nop 0
	v_readlane_b32 s0, v3, 63
	s_nop 1
	v_fma_f32 v3, s0, v238, v234
	v_rsq_f32_e32 v3, v3
	s_nop 0
	v_mul_f32_e32 v2, v2, v3
	v_mov_b32_e32 v3, s65
	ds_read_b32 v3, v3
	ds_read_b32 v4, v142
	v_fma_f32 v2, v220, v2, v213
	s_waitcnt lgkmcnt(0)
	v_fmac_f32_e32 v2, v3, v4
	ds_read_b32 v3, v166
	s_waitcnt lgkmcnt(0)
	v_mul_f32_e32 v2, v3, v2
	s_nop 0
	v_cvt_pk_bf16_f32 v4, v2, v5
	v_lshl_add_u64 v[2:3], s[42:43], 0, v[0:1]
	v_add_co_u32_e32 v2, vcc, s1, v2
	v_readlane_b32 s42, v255, 28
	s_nop 0
	v_addc_co_u32_e32 v3, vcc, 0, v3, vcc
	global_store_short v[2:3], v4, off
	ds_read_b32 v2, v167
	v_readlane_b32 s43, v255, 29
	s_waitcnt lgkmcnt(0)
	v_add_f32_dpp v3, v2, v2 quad_perm:[1,0,3,2] row_mask:0xf bank_mask:0xf bound_ctrl:1
	s_nop 1
	v_add_f32_dpp v3, v3, v3 quad_perm:[2,3,0,1] row_mask:0xf bank_mask:0xf bound_ctrl:1
	s_nop 1
	v_add_f32_dpp v3, v3, v3 row_half_mirror row_mask:0xf bank_mask:0xf bound_ctrl:1
	s_nop 1
	v_add_f32_dpp v3, v3, v3 row_mirror row_mask:0xf bank_mask:0xf bound_ctrl:1
	s_nop 1
	v_add_f32_dpp v3, v3, v3 row_bcast:15 row_mask:0xa bank_mask:0xf
	s_nop 1
	v_add_f32_dpp v3, v3, v3 row_bcast:31 row_mask:0xc bank_mask:0xf
	s_nop 0
	v_readlane_b32 s0, v3, 63
	s_nop 1
	v_fmac_f32_e32 v2, s0, v237
	v_mul_f32_e32 v3, v2, v2
	s_nop 1
	v_mov_b32_dpp v3, v3 quad_perm:[1,0,3,2] row_mask:0xf bank_mask:0xf bound_ctrl:1
	v_fmac_f32_e32 v3, v2, v2
	s_nop 1
	v_add_f32_dpp v3, v3, v3 quad_perm:[2,3,0,1] row_mask:0xf bank_mask:0xf bound_ctrl:1
	s_nop 1
	v_add_f32_dpp v3, v3, v3 row_half_mirror row_mask:0xf bank_mask:0xf bound_ctrl:1
	s_nop 1
	v_add_f32_dpp v3, v3, v3 row_mirror row_mask:0xf bank_mask:0xf bound_ctrl:1
	s_nop 1
	v_add_f32_dpp v3, v3, v3 row_bcast:15 row_mask:0xa bank_mask:0xf
	s_nop 1
	v_add_f32_dpp v3, v3, v3 row_bcast:31 row_mask:0xc bank_mask:0xf
	s_nop 0
	v_readlane_b32 s0, v3, 63
	s_nop 1
	v_fma_f32 v3, s0, v238, v234
	v_rsq_f32_e32 v3, v3
	s_nop 0
	v_mul_f32_e32 v2, v2, v3
	v_mov_b32_e32 v3, s58
	ds_read_b32 v3, v3
	ds_read_b32 v4, v146
	v_fma_f32 v2, v220, v2, v213
	s_waitcnt lgkmcnt(0)
; __device__ __forceinline__ void phase_rwkv(KP P, int l_, unsigned char* shm) {
;     ...
;         if (!scanw) RW_POST(NC - 1);
	v_fmac_f32_e32 v2, v3, v4
	ds_read_b32 v3, v168
	s_waitcnt lgkmcnt(0)
	v_mul_f32_e32 v2, v3, v2
	s_nop 0
	v_cvt_pk_bf16_f32 v4, v2, v5
	v_lshl_add_u64 v[2:3], s[42:43], 0, v[0:1]
	v_add_co_u32_e32 v2, vcc, s1, v2
	v_readlane_b32 s42, v255, 30
	s_nop 0
	v_addc_co_u32_e32 v3, vcc, 0, v3, vcc
	global_store_short v[2:3], v4, off
	ds_read_b32 v2, v169
	v_readlane_b32 s43, v255, 31
	s_waitcnt lgkmcnt(0)
	v_add_f32_dpp v3, v2, v2 quad_perm:[1,0,3,2] row_mask:0xf bank_mask:0xf bound_ctrl:1
	s_nop 1
	v_add_f32_dpp v3, v3, v3 quad_perm:[2,3,0,1] row_mask:0xf bank_mask:0xf bound_ctrl:1
	s_nop 1
	v_add_f32_dpp v3, v3, v3 row_half_mirror row_mask:0xf bank_mask:0xf bound_ctrl:1
	s_nop 1
	v_add_f32_dpp v3, v3, v3 row_mirror row_mask:0xf bank_mask:0xf bound_ctrl:1
	s_nop 1
	v_add_f32_dpp v3, v3, v3 row_bcast:15 row_mask:0xa bank_mask:0xf
	s_nop 1
	v_add_f32_dpp v3, v3, v3 row_bcast:31 row_mask:0xc bank_mask:0xf
	s_nop 0
	v_readlane_b32 s0, v3, 63
	s_nop 1
	v_fmac_f32_e32 v2, s0, v237
	v_mul_f32_e32 v3, v2, v2
	s_nop 1
	v_mov_b32_dpp v3, v3 quad_perm:[1,0,3,2] row_mask:0xf bank_mask:0xf bound_ctrl:1
	v_fmac_f32_e32 v3, v2, v2
	s_nop 1
	v_add_f32_dpp v3, v3, v3 quad_perm:[2,3,0,1] row_mask:0xf bank_mask:0xf bound_ctrl:1
	s_nop 1
	v_add_f32_dpp v3, v3, v3 row_half_mirror row_mask:0xf bank_mask:0xf bound_ctrl:1
	s_nop 1
	v_add_f32_dpp v3, v3, v3 row_mirror row_mask:0xf bank_mask:0xf bound_ctrl:1
	s_nop 1
	v_add_f32_dpp v3, v3, v3 row_bcast:15 row_mask:0xa bank_mask:0xf
	s_nop 1
	v_add_f32_dpp v3, v3, v3 row_bcast:31 row_mask:0xc bank_mask:0xf
	s_nop 0
	v_readlane_b32 s0, v3, 63
	s_nop 1
	v_fma_f32 v3, s0, v238, v234
	v_rsq_f32_e32 v3, v3
	s_nop 0
	v_mul_f32_e32 v2, v2, v3
	v_mov_b32_e32 v3, s59
	ds_read_b32 v3, v3
	ds_read_b32 v4, v150
	v_fma_f32 v2, v220, v2, v213
	s_waitcnt lgkmcnt(0)
	v_fmac_f32_e32 v2, v3, v4
	ds_read_b32 v3, v170
	s_waitcnt lgkmcnt(0)
	v_mul_f32_e32 v2, v3, v2
	s_nop 0
	v_cvt_pk_bf16_f32 v4, v2, v5
	v_lshl_add_u64 v[2:3], s[42:43], 0, v[0:1]
	v_add_co_u32_e32 v2, vcc, s1, v2
	s_nop 1
	v_addc_co_u32_e32 v3, vcc, 0, v3, vcc
	global_store_short v[2:3], v4, off
	ds_read_b32 v2, v171
	s_waitcnt lgkmcnt(0)
	v_add_f32_dpp v3, v2, v2 quad_perm:[1,0,3,2] row_mask:0xf bank_mask:0xf bound_ctrl:1
	s_nop 1
	v_add_f32_dpp v3, v3, v3 quad_perm:[2,3,0,1] row_mask:0xf bank_mask:0xf bound_ctrl:1
	s_nop 1
	v_add_f32_dpp v3, v3, v3 row_half_mirror row_mask:0xf bank_mask:0xf bound_ctrl:1
	s_nop 1
	v_add_f32_dpp v3, v3, v3 row_mirror row_mask:0xf bank_mask:0xf bound_ctrl:1
	s_nop 1
	v_add_f32_dpp v3, v3, v3 row_bcast:15 row_mask:0xa bank_mask:0xf
	s_nop 1
	v_add_f32_dpp v3, v3, v3 row_bcast:31 row_mask:0xc bank_mask:0xf
	s_nop 0
	v_readlane_b32 s0, v3, 63
	s_nop 1
	v_fmac_f32_e32 v2, s0, v237
	v_mul_f32_e32 v3, v2, v2
	s_nop 1
	v_mov_b32_dpp v3, v3 quad_perm:[1,0,3,2] row_mask:0xf bank_mask:0xf bound_ctrl:1
	v_fmac_f32_e32 v3, v2, v2
	s_nop 1
	v_add_f32_dpp v3, v3, v3 quad_perm:[2,3,0,1] row_mask:0xf bank_mask:0xf bound_ctrl:1
	s_nop 1
	v_add_f32_dpp v3, v3, v3 row_half_mirror row_mask:0xf bank_mask:0xf bound_ctrl:1
	s_nop 1
	v_add_f32_dpp v3, v3, v3 row_mirror row_mask:0xf bank_mask:0xf bound_ctrl:1
	s_nop 1
	v_add_f32_dpp v3, v3, v3 row_bcast:15 row_mask:0xa bank_mask:0xf
	s_nop 1
	v_add_f32_dpp v3, v3, v3 row_bcast:31 row_mask:0xc bank_mask:0xf
	s_nop 0
	v_readlane_b32 s0, v3, 63
	s_nop 1
	v_fma_f32 v3, s0, v238, v234
	v_rsq_f32_e32 v3, v3
	v_readlane_b32 s0, v255, 32
	v_readlane_b32 s1, v255, 33
	v_mul_f32_e32 v2, v2, v3
	v_fmac_f32_e32 v213, v220, v2
	v_mov_b32_e32 v2, s56
	ds_read_b32 v2, v2
	ds_read_b32 v3, v154
	v_lshl_add_u64 v[0:1], s[0:1], 0, v[0:1]
	v_add_co_u32_e32 v0, vcc, 0x1f8000, v0
	s_waitcnt lgkmcnt(0)
	v_fmac_f32_e32 v213, v2, v3
	ds_read_b32 v2, v172
	v_addc_co_u32_e32 v1, vcc, 0, v1, vcc
	s_waitcnt lgkmcnt(0)
	v_mul_f32_e32 v2, v2, v213
	s_nop 0
	v_cvt_pk_bf16_f32 v2, v2, v5
	global_store_short v[0:1], v2, off
	s_branch .LBB0_2462

; __device__ __forceinline__ void phase_attn(KP P, int l_, unsigned char* shm) {
;     ...
;     const float lam_init = 0.8f - 0.6f * __expf(-0.3f * (float)l);
;     float lam;
;     { const float* lq = P->in[11] + (size_t)l * 256; const float s1 = wave_sum(lq[lane] * lq[64 + lane]), s2 = wave_sum(lq[128 + lane] * lq[192 + lane]); lam = __expf(s1) - __expf(s2) + lam_init; }
.LBB0_2646:
	s_or_b64 exec, exec, s[4:5]
	v_readlane_b32 s0, v255, 1
	s_mov_b64 s[42:43], s[72:73]
	s_mov_b32 s8, s0
	s_waitcnt lgkmcnt(0)
	v_mov_b32_e32 v0, v228
	s_barrier
	s_load_dwordx2 s[4:5], s[42:43], 0x58
	s_ashr_i32 s9, s8, 31
	s_lshl_b64 s[6:7], s[8:9], 10
	v_and_b32_e32 v2, 63, v0
	v_lshlrev_b32_e32 v1, 2, v2
	s_waitcnt lgkmcnt(0)
	s_add_u32 s6, s4, s6
	s_addc_u32 s7, s5, s7
	global_load_dword v3, v1, s[6:7]
	global_load_dword v4, v1, s[6:7] offset:256
	v_readlane_b32 s0, v254, 6
	v_readlane_b32 s1, v254, 7
	s_and_b64 vcc, exec, s[0:1]
	s_waitcnt vmcnt(0)
	v_mul_f32_e32 v6, v3, v4
	s_nop 1
	v_mov_b32_dpp v6, v6 quad_perm:[1,0,3,2] row_mask:0xf bank_mask:0xf bound_ctrl:1
	v_fmac_f32_e32 v6, v3, v4
	s_nop 0
	s_nop 0
	v_add_f32_dpp v3, v6, v6 quad_perm:[2,3,0,1] row_mask:0xf bank_mask:0xf bound_ctrl:1
	s_nop 1
	v_add_f32_dpp v3, v3, v3 row_half_mirror row_mask:0xf bank_mask:0xf bound_ctrl:1
	s_nop 1
	v_add_f32_dpp v3, v3, v3 row_mirror row_mask:0xf bank_mask:0xf bound_ctrl:1
	s_nop 1
	v_add_f32_dpp v3, v3, v3 row_bcast:15 row_mask:0xa bank_mask:0xf
	s_nop 1
	v_add_f32_dpp v3, v3, v3 row_bcast:31 row_mask:0xc bank_mask:0xf
	s_nop 0
	v_readlane_b32 s4, v3, 63
	global_load_dword v3, v1, s[6:7] offset:512
	global_load_dword v4, v1, s[6:7] offset:768
	s_waitcnt vmcnt(0)
	v_mul_f32_e32 v6, v3, v4
	s_nop 1
	v_mov_b32_dpp v6, v6 quad_perm:[1,0,3,2] row_mask:0xf bank_mask:0xf bound_ctrl:1
	v_fmac_f32_e32 v6, v3, v4
	s_nop 0
	s_nop 0
	v_add_f32_dpp v3, v6, v6 quad_perm:[2,3,0,1] row_mask:0xf bank_mask:0xf bound_ctrl:1
	s_nop 1
	v_add_f32_dpp v3, v3, v3 row_half_mirror row_mask:0xf bank_mask:0xf bound_ctrl:1
	s_nop 1
	v_add_f32_dpp v3, v3, v3 row_mirror row_mask:0xf bank_mask:0xf bound_ctrl:1
	s_nop 1
	v_add_f32_dpp v3, v3, v3 row_bcast:15 row_mask:0xa bank_mask:0xf
	s_nop 1
	v_add_f32_dpp v3, v3, v3 row_bcast:31 row_mask:0xc bank_mask:0xf
	s_nop 0
	v_readlane_b32 s5, v3, 63
	s_cbranch_vccz .LBB0_2668
; __device__ __forceinline__ int ltid() { int t = threadIdx.x; asm volatile("" : "+v"(t)); return t; }
; __device__ __forceinline__ void phase_attn(KP P, int l_, unsigned char* shm) {
;     ...
;     const int tid = ltid(), wave = tid >> 6, lane = tid & 63, mp = wave >> 2, rq = wave & 3, l15 = lane & 15, g = lane >> 4;
;     const u16* pA = (const u16*)(P->ws + WS_P);
;     u16* OA = (u16*)(P->ws + WS_O);
;     constexpr int KROW = 72, VROW = 136, KT_B = 128 * KROW * 2, VT_B = 128 * VROW * 2, STG = 2 * KT_B + VT_B;
;     const u16* vTg = (const u16*)(P->ws + WS_LO);
;     const float lam_init = 0.8f - 0.6f * __expf(-0.3f * (float)l);
;     float lam;
;     { const float* lq = P->in[11] + (size_t)l * 256; const float s1 = wave_sum(lq[lane] * lq[64 + lane]), s2 = wave_sum(lq[128 + lane] * lq[192 + lane]); lam = __expf(s1) - __expf(s2) + lam_init; }
;     for (int it = blockIdx.x; it < 4096; it += gridDim.x) {
;         const int j = it & 255, pi = 15 - (it >> 8), bh = j >> 1, half = j & 1, b = bh >> 2, h = bh & 3;
;         const int qb = (pi >> 1) * 4 + ((pi & 1) ? (half ? 2 : 3) : (half ? 1 : 0));
;         const int q0 = qb * 64, nt = (qb >> 1) + 1;
;         const size_t tok0 = (size_t)b * SEQ;
;         bf16x8 qf[2];
;         { const u16* qp = pA + (tok0 + q0 + rq * 16 + l15) * 1536 + h * 128 + mp * 64 + g * 8;
;           qf[0] = *(const bf16x8*)qp; qf[1] = *(const bf16x8*)(qp + 32); }
;         f32x4 ot[8];
; #pragma unroll
;         for (int e = 0; e < 8; ++e) ot[e] = (f32x4){0.f, 0.f, 0.f, 0.f};
;         float mrun = -INFINITY, lrun = 0.f;
;         uint4 kreg0, kreg1, kreg2, kreg3, vreg0, vreg1, vreg2, vreg3;
;         const int kc_key = (tid >> 3) & 63, kc_ch = tid & 7, vc_e = tid >> 4, vc_ch = tid & 15;
;         const u16* kgb = pA + (tok0 + kc_key) * 1536 + 512 + h * 128 + kc_ch * 8;
;         const u16* vTb = vTg + ((size_t)bh * 128 + vc_e) * SEQ + vc_ch * 8;
;     ...
;                         const int qr = rq * 16 + l15;
; #pragma unroll
;                         for (int kt = 0; kt < 4; ++kt)
; #pragma unroll
;                             for (int jj = 0; jj < 4; ++jj) if (kt * 16 + g * 4 + jj > qr) st[kt][jj] = -INFINITY;
	v_cvt_f32_i32_e32 v3, s8
	v_mov_b32_e32 v6, 0x3fb8aa3b
	v_mul_f32_e32 v4, s4, v6
	v_mul_f32_e32 v6, s5, v6
	v_mul_f32_e32 v3, 0xbe99999a, v3
	v_mul_f32_e32 v3, 0x3fb8aa3b, v3
	v_exp_f32_e32 v3, v3
	v_exp_f32_e32 v4, v4
	v_exp_f32_e32 v6, v6
	v_mov_b32_e32 v7, 0x3f4ccccd
	v_fmamk_f32 v3, v3, 0xbf19999a, v7
	v_lshrrev_b32_e32 v8, 4, v2
	v_sub_f32_e32 v4, v4, v6
	v_add_f32_e32 v165, v3, v4
	v_and_b32_e32 v4, 15, v0
	v_bfe_u32 v10, v0, 6, 2
	v_lshlrev_b32_e32 v164, 2, v8
	v_lshl_or_b32 v194, v10, 4, v4
	v_sub_f32_e32 v197, 1.0, v3
	v_or_b32_e32 v3, 2, v164
	v_cmp_gt_u32_e64 s[12:13], v3, v194
	v_or_b32_e32 v3, 3, v164
	v_cmp_gt_u32_e64 s[14:15], v3, v194
	v_or_b32_e32 v3, 16, v164
	v_cmp_gt_u32_e64 s[16:17], v3, v194
	v_or_b32_e32 v3, 17, v164
	v_cmp_gt_u32_e64 s[18:19], v3, v194
	v_or_b32_e32 v3, 18, v164
	s_load_dwordx2 s[48:49], s[42:43], 0xf8
	v_cmp_gt_u32_e64 s[20:21], v3, v194
	v_or_b32_e32 v3, 19, v164
	v_cmp_gt_u32_e64 s[22:23], v3, v194
	v_or_b32_e32 v3, 32, v164
	v_lshlrev_b32_e32 v6, 3, v0
	v_cmp_gt_u32_e64 s[24:25], v3, v194
	v_or_b32_e32 v3, 33, v164
	v_and_b32_e32 v2, 56, v6
	v_and_b32_e32 v6, 0x78, v6
	v_cmp_gt_u32_e64 s[26:27], v3, v194
	v_or_b32_e32 v3, 34, v164
	v_lshlrev_b32_e32 v160, 1, v6
	v_mov_b32_e32 v161, v5
	v_cmp_gt_u32_e64 s[28:29], v3, v194
	v_or_b32_e32 v3, 35, v164
	v_bfe_u32 v169, v0, 3, 6
	s_waitcnt lgkmcnt(0)
	v_lshl_add_u64 v[6:7], s[48:49], 0, v[160:161]
	s_mov_b64 s[0:1], 0x2bb00000
	v_cmp_gt_u32_e64 s[30:31], v3, v194
	v_or_b32_e32 v3, 48, v164
	v_lshl_add_u64 v[162:163], v[6:7], 0, s[0:1]
	v_mul_u32_u24_e32 v6, 0x48, v169
	v_cmp_gt_u32_e64 s[34:35], v3, v194
	v_or_b32_e32 v3, 49, v164
	s_add_u32 s50, s48, 0x17b00000
	v_ashrrev_i32_e32 v158, 4, v0
	v_lshlrev_b32_e32 v161, 1, v6
	v_lshlrev_b32_e32 v6, 1, v2
	s_movk_i32 s0, 0x88
	v_cmp_gt_u32_e64 s[36:37], v3, v194
	v_or_b32_e32 v3, 50, v164
	s_addc_u32 s51, s49, 0
	v_lshrrev_b32_e32 v9, 6, v0
	v_ashrrev_i32_e32 v11, 8, v0
	v_ashrrev_i32_e32 v159, 31, v158
	v_add3_u32 v190, 0, v161, v6
	v_mul_lo_u32 v6, v158, s0
	v_xor_b32_e32 v195, 64, v1
	v_xor_b32_e32 v196, 0x80, v1
	v_lshl_add_u32 v1, v4, 2, 0
	s_movk_i32 s0, 0x100
	v_cmp_gt_u32_e64 s[38:39], v3, v194
	v_or_b32_e32 v3, 51, v164
	s_add_u32 s60, s48, 0x27b00000
	v_lshlrev_b32_e32 v154, 6, v11
	v_lshlrev_b32_e32 v156, 3, v8
	v_lshlrev_b32_e32 v191, 1, v6
	v_cmp_gt_u32_e64 s[6:7], s0, v0
	v_cmp_gt_u32_e64 s[40:41], v3, v194
	v_lshlrev_b32_e32 v3, 8, v8
	v_lshl_add_u32 v6, v10, 13, v1
	v_lshl_add_u32 v1, v9, 13, v1
	v_lshlrev_b64 v[166:167], 12, v[158:159]
	v_and_b32_e32 v0, 7, v0
	s_addc_u32 s61, s49, 0
	v_ashrrev_i32_e32 v155, 31, v154
	v_add3_u32 v192, 0, v191, v160
	v_mul_i32_i24_e32 v193, 0x4800, v11
	v_cmp_eq_u32_e64 s[4:5], 1, v11
	s_lshl_b64 s[54:55], s[8:9], 9
	v_mul_u32_u24_e32 v198, 0x90, v4
	v_mul_u32_u24_e32 v199, 0x110, v4
	v_cmp_gt_u32_e64 s[8:9], v164, v194
	v_cmp_lt_u32_e64 s[10:11], v164, v194
	v_lshl_or_b32 v166, v4, 4, v166
	v_lshlrev_b32_e32 v168, 4, v0
	v_mov_b32_e32 v157, v5
	v_lshlrev_b32_e32 v170, 1, v156
	v_lshlrev_b32_e32 v172, 1, v2
	v_add_u32_e32 v200, v6, v3
	v_add_u32_e32 v201, v1, v3
	v_bfe_u32 v0, v228, 3, 6
	v_bfe_u32 v1, v0, 1, 3
	v_and_b32_e32 v2, 7, v228
	v_xor_b32_e32 v1, v1, v2
	v_lshlrev_b32_e32 v1, 4, v1
	v_lshl_add_u32 v190, v0, 7, v1
	v_lshrrev_b32_e32 v0, 4, v228
	v_and_b32_e32 v1, 15, v0
	v_add_u32_e32 v2, 4, v1
	v_bfe_u32 v2, v2, 3, 1
	v_xor_b32_e32 v1, v1, v2
	v_and_b32_e32 v2, 15, v228
	v_xor_b32_e32 v1, v1, v2
	v_lshlrev_b32_e32 v1, 4, v1
	v_lshl_add_u32 v192, v0, 8, v1
	v_add_u32_e32 v192, 0x8000, v192
	v_and_b32_e32 v0, 15, v228
	v_bfe_u32 v1, v228, 4, 2
	v_lshrrev_b32_e32 v2, 1, v0
	v_xor_b32_e32 v2, v2, v1
	v_lshlrev_b32_e32 v3, 7, v0
	v_lshl_add_u32 v198, v2, 4, v3
	v_xor_b32_e32 v2, 4, v2
	v_lshl_add_u32 v199, v2, 4, v3
	v_lshrrev_b32_e32 v2, 8, v228
	v_lshlrev_b32_e32 v2, 14, v2
	v_add_u32_e32 v198, v198, v2
	v_add_u32_e32 v199, v199, v2
	v_add_u32_e32 v2, 4, v0
	v_bfe_u32 v2, v2, 3, 1
	v_xor_b32_e32 v2, v2, v0
	v_lshlrev_b32_e32 v3, 8, v0
	v_add_u32_e32 v3, 0x8000, v3
	v_xor_b32_e32 v1, v1, v2
	v_lshl_add_u32 v161, v1, 4, v3
	v_xor_b32_e32 v2, 4, v1
	v_lshl_add_u32 v191, v2, 4, v3
	v_xor_b32_e32 v2, 8, v1
	v_lshl_add_u32 v160, v2, 4, v3
	v_xor_b32_e32 v2, 12, v1
	v_lshl_add_u32 v210, v2, 4, v3
	v_lshrrev_b32_e32 v0, 6, v228
	v_and_b32_e32 v1, 63, v228
	s_nop 0
	v_readfirstlane_b32 s32, v0
	s_lshl_b32 s32, s32, 12
	v_and_b32_e32 v2, 3, v0
	v_lshrrev_b32_e32 v3, 3, v1
	v_lshl_add_u32 v2, v2, 5, v3
	v_mul_u32_u24_e32 v2, 0xc00, v2
	v_lshrrev_b32_e32 v6, 2, v0
	v_lshl_add_u32 v2, v6, 7, v2
	v_and_b32_e32 v6, 7, v1
	v_lshrrev_b32_e32 v7, 1, v3
	v_xor_b32_e32 v6, v6, v7
	v_xor_b32_e32 v7, 4, v6
	v_lshl_add_u32 v202, v6, 4, v2
	v_lshl_add_u32 v203, v7, 4, v2
	v_add_u32_e32 v203, 0x6000, v203
	v_lshl_add_u32 v211, v6, 4, v2
	v_add_u32_e32 v211, 0xc000, v211
	v_lshl_add_u32 v235, v7, 4, v2
	v_add_u32_e32 v235, 0x12000, v235
	v_lshrrev_b32_e32 v3, 4, v1
	v_and_b32_e32 v6, 15, v1
	v_lshl_add_u32 v2, v0, 4, v3
	v_lshlrev_b32_e32 v2, 12, v2
	v_mov_b32_e32 v7, v3
	v_add_u32_e32 v8, 4, v7
	v_bfe_u32 v8, v8, 3, 1
	v_xor_b32_e32 v7, v7, v8
	v_xor_b32_e32 v7, v7, v6
	v_lshl_add_u32 v239, v7, 4, v2
	v_add_u32_e32 v7, 4, v3
	v_add_u32_e32 v8, 4, v7
	v_bfe_u32 v8, v8, 3, 1
	v_xor_b32_e32 v7, v7, v8
	v_xor_b32_e32 v7, v7, v6
	v_lshl_add_u32 v240, v7, 4, v2
	v_add_u32_e32 v240, 0x4000, v240
	v_add_u32_e32 v7, 8, v3
	v_add_u32_e32 v8, 4, v7
	v_bfe_u32 v8, v8, 3, 1
	v_xor_b32_e32 v7, v7, v8
	v_xor_b32_e32 v7, v7, v6
	v_lshl_add_u32 v247, v7, 4, v2
	v_add_u32_e32 v247, 0x8000, v247
	v_add_u32_e32 v7, 12, v3
	v_add_u32_e32 v8, 4, v7
	v_bfe_u32 v8, v8, 3, 1
	v_xor_b32_e32 v7, v7, v8
	v_xor_b32_e32 v7, v7, v6
	v_lshl_add_u32 v193, v7, 4, v2
	v_add_u32_e32 v193, 0xc000, v193
	s_mov_b32 s62, s2
	s_mov_b32 s65, 0
	s_branch .LBB0_2649
